# K-loops: SP2 loads in saddr form (6 fewer 64-bit VALU adds per iteration), loop-carried SALU moved into MFMA blocks, merged vmcnt+lgkmcnt waits; on top of peeled first iteration
# speedup vs baseline: 1.0101x; 1.0063x over previous
; #define PG8_STAGE(bufoff, gbase, voff) do { _Pragma("unroll") for (int _i = 0; _i < 2; ++_i) \
;         __builtin_amdgcn_global_load_lds((const unsigned*)((const char*)(gbase) + (voff)[_i]), (PG8_LAS unsigned*)(lds + (bufoff) + ldsw + _i * 8192), 16, 0, 0); } while (0)
; #define PG8_LDA(dst, b, h) do { _Pragma("unroll") for (int m = 0; m < 4; ++m) _Pragma("unroll") for (int k = 0; k < 2; ++k) dst[m][k] = *(const PG8_LAS bf16x8*)(lds + PG8_SA(b, h) + aoff + m * 2048 + k * 1024); } while (0)
; #define PG8_LDB(dst, b, h) do { _Pragma("unroll") for (int n = 0; n < 2; ++n) _Pragma("unroll") for (int k = 0; k < 2; ++k) dst[n][k] = *(const PG8_LAS bf16x8*)(lds + PG8_SB(b, h) + boff + n * 2048 + k * 1024); } while (0)
; #define PG8_MMA(ai, bj, At, Bt) do { __builtin_amdgcn_s_setprio(1); _Pragma("unroll") for (int m = 0; m < 4; ++m) _Pragma("unroll") for (int n = 0; n < 2; ++n) _Pragma("unroll") for (int k = 0; k < 2; ++k) \
;         acc[ai][bj][m][n] = __builtin_amdgcn_mfma_f32_16x16x32_bf16(Bt[n][k], At[m][k], acc[ai][bj][m][n], 0, 0, 0); __builtin_amdgcn_s_setprio(0); } while (0)
; #define PG8_WAIT_V(n) asm volatile("s_waitcnt vmcnt(" #n ")" ::: "memory")
; #define PG8_BAR __builtin_amdgcn_s_barrier()
; template <class Epi, class Sched, bool ALIGN_EPI = false, bool SP2 = false>
; __device__ __forceinline__ void gemm_phase(PG8_LAS unsigned char* lds, const Gemm g, const Sched& S, const Epi& E) {
;     ...
;         for (int t = 0; t < nt; t += 2) {
;             const bool last = (t == nt - 2);
;             const char* a1 = cA + (size_t)(t + 1) * kstep;
;             const char* a2 = last ? nA : cA + (size_t)(t + 2) * kstep; const char* b2 = last ? nB : cB + (size_t)(t + 2) * kstep;
;             const char* a3 = a2 + kstep; const char* b3 = b2 + kstep;
;             if (last && has_next) S.a_ready(nxt);
;             if constexpr (SP2) {
;             PG8_LDB(B0, 0, 0); PG8_LDB(B1, 0, 1); PG8_SCHED; PG8_LDA(At, 0, 0); PG8_STAGE(PG8_SA(1, 1), a1 + hstep, voffA);
;             PG8_WAIT_V(8); PG8_WAIT_L(0); PG8_BAR; PG8_MMA(0, 0, At, B0); PG8_MMA(0, 1, At, B1); PG8_BAR; PG8_SCHED;
;             PG8_LDA(At, 0, 1); PG8_STAGE(PG8_SB(0, 0), b2, voffB); PG8_STAGE(PG8_SB(0, 1), b2 + hstep, voffB); PG8_STAGE(PG8_SA(0, 0), a2, voffA);
;             PG8_WAIT_V(8); PG8_WAIT_L(0); PG8_BAR; PG8_MMA(1, 0, At, B0); PG8_MMA(1, 1, At, B1); PG8_BAR; PG8_SCHED;
.Lz_enter_339:
	s_add_u32 s16, s16, 0x80
	s_addc_u32 s17, s17, 0
	s_add_u32 s33, s20, 0x100
	s_addc_u32 s39, s21, 0
	s_mov_b32 s20, 0
	ds_read_b128 v[82:85], v167
	ds_read_b128 v[86:89], v167 offset:1024
	ds_read_b128 v[138:141], v167 offset:2048
	ds_read_b128 v[142:145], v167 offset:3072
	ds_read_b128 v[158:161], v167 offset:16384
	ds_read_b128 v[162:165], v167 offset:17408
	ds_read_b128 v[170:173], v167 offset:18432
	ds_read_b128 v[174:177], v167 offset:19456
	s_add_i32 m0, s63, 0xc000
	ds_read_b128 v[178:181], v169
	ds_read_b128 v[182:185], v169 offset:1024
	ds_read_b128 v[186:189], v169 offset:2048
	ds_read_b128 v[190:193], v169 offset:3072
	ds_read_b128 v[194:197], v169 offset:4096
	ds_read_b128 v[198:201], v169 offset:5120
	ds_read_b128 v[202:205], v169 offset:6144
	global_load_lds_dwordx4 v154, s[16:17]
	s_add_i32 m0, s63, 0xe000
	ds_read_b128 v[206:209], v169 offset:7168
	global_load_lds_dwordx4 v156, s[16:17]
	s_waitcnt vmcnt(8) lgkmcnt(0)
	s_barrier
	s_setprio 1
	v_mfma_f32_16x16x32_bf16 v[134:137], v[82:85], v[178:181], 0
	v_mfma_f32_16x16x32_bf16 v[130:133], v[138:141], v[178:181], 0
	v_mfma_f32_16x16x32_bf16 v[126:129], v[82:85], v[186:189], 0
	v_mfma_f32_16x16x32_bf16 v[122:125], v[138:141], v[186:189], 0
	s_add_i32 s44, s20, 2
	v_mfma_f32_16x16x32_bf16 v[118:121], v[82:85], v[194:197], 0
	s_add_u32 s45, s16, 0x80
	v_mfma_f32_16x16x32_bf16 v[114:117], v[138:141], v[194:197], 0
	s_addc_u32 s21, s17, 0
	v_mfma_f32_16x16x32_bf16 v[110:113], v[82:85], v[202:205], 0
	s_cmp_eq_u32 s70, s20
	v_mfma_f32_16x16x32_bf16 v[106:109], v[138:141], v[202:205], 0
	s_cselect_b32 s21, s7, s21
	v_mfma_f32_16x16x32_bf16 v[134:137], v[86:89], v[182:185], v[134:137]
	s_cselect_b32 s20, s6, s45
	v_mfma_f32_16x16x32_bf16 v[130:133], v[142:145], v[182:185], v[130:133]
	s_cselect_b32 s47, s57, s39
	v_mfma_f32_16x16x32_bf16 v[126:129], v[86:89], v[190:193], v[126:129]
	s_cselect_b32 s46, s56, s33
	v_mfma_f32_16x16x32_bf16 v[122:125], v[142:145], v[190:193], v[122:125]
	v_mfma_f32_16x16x32_bf16 v[118:121], v[86:89], v[198:201], v[118:121]
	v_mfma_f32_16x16x32_bf16 v[114:117], v[142:145], v[198:201], v[114:117]
	v_mfma_f32_16x16x32_bf16 v[110:113], v[86:89], v[206:209], v[110:113]
	v_mfma_f32_16x16x32_bf16 v[106:109], v[142:145], v[206:209], v[106:109]
	v_mfma_f32_16x16x32_bf16 v[62:65], v[158:161], v[178:181], 0
	v_mfma_f32_16x16x32_bf16 v[58:61], v[170:173], v[178:181], 0
	v_mfma_f32_16x16x32_bf16 v[54:57], v[158:161], v[186:189], 0
	v_mfma_f32_16x16x32_bf16 v[50:53], v[170:173], v[186:189], 0
	v_mfma_f32_16x16x32_bf16 v[46:49], v[158:161], v[194:197], 0
	v_mfma_f32_16x16x32_bf16 v[42:45], v[170:173], v[194:197], 0
	v_mfma_f32_16x16x32_bf16 v[38:41], v[158:161], v[202:205], 0
	v_mfma_f32_16x16x32_bf16 v[34:37], v[170:173], v[202:205], 0
	v_mfma_f32_16x16x32_bf16 v[62:65], v[162:165], v[182:185], v[62:65]
	v_mfma_f32_16x16x32_bf16 v[58:61], v[174:177], v[182:185], v[58:61]
	v_mfma_f32_16x16x32_bf16 v[54:57], v[162:165], v[190:193], v[54:57]
	v_mfma_f32_16x16x32_bf16 v[50:53], v[174:177], v[190:193], v[50:53]
	v_mfma_f32_16x16x32_bf16 v[46:49], v[162:165], v[198:201], v[46:49]
	v_mfma_f32_16x16x32_bf16 v[42:45], v[174:177], v[198:201], v[42:45]
	v_mfma_f32_16x16x32_bf16 v[38:41], v[162:165], v[206:209], v[38:41]
	v_mfma_f32_16x16x32_bf16 v[34:37], v[174:177], v[206:209], v[34:37]
	s_setprio 0
	s_barrier
	s_add_i32 m0, s62, 0x10000
	s_add_u32 s100, s46, s10
	s_addc_u32 s101, s47, s11
	ds_read_b128 v[178:181], v169 offset:16384
	ds_read_b128 v[182:185], v169 offset:17408
	ds_read_b128 v[186:189], v169 offset:18432
	global_load_lds_dwordx4 v148, s[46:47]
	s_add_i32 m0, s62, 0x12000
	ds_read_b128 v[190:193], v169 offset:19456
	global_load_lds_dwordx4 v152, s[46:47]
	s_add_i32 m0, s62, 0x14000
	ds_read_b128 v[194:197], v169 offset:20480
	global_load_lds_dwordx4 v148, s[100:101]
	s_add_i32 m0, s62, 0x16000
	ds_read_b128 v[198:201], v169 offset:21504
	global_load_lds_dwordx4 v152, s[100:101]
	s_mov_b32 m0, s63
	ds_read_b128 v[202:205], v169 offset:22528
	global_load_lds_dwordx4 v146, s[20:21]
	s_mov_b32 m0, s64
	ds_read_b128 v[206:209], v169 offset:23552
	global_load_lds_dwordx4 v150, s[20:21]
	s_waitcnt vmcnt(8) lgkmcnt(0)
	s_barrier
	s_setprio 1
	v_mfma_f32_16x16x32_bf16 v[102:105], v[82:85], v[178:181], 0
	v_mfma_f32_16x16x32_bf16 v[98:101], v[138:141], v[178:181], 0
	v_mfma_f32_16x16x32_bf16 v[94:97], v[82:85], v[186:189], 0
	v_mfma_f32_16x16x32_bf16 v[90:93], v[138:141], v[186:189], 0
	v_mfma_f32_16x16x32_bf16 v[78:81], v[82:85], v[194:197], 0
	v_mfma_f32_16x16x32_bf16 v[74:77], v[138:141], v[194:197], 0
	v_mfma_f32_16x16x32_bf16 v[70:73], v[82:85], v[202:205], 0
	v_mfma_f32_16x16x32_bf16 v[66:69], v[138:141], v[202:205], 0
	v_mfma_f32_16x16x32_bf16 v[102:105], v[86:89], v[182:185], v[102:105]
	v_mfma_f32_16x16x32_bf16 v[98:101], v[142:145], v[182:185], v[98:101]
	v_mfma_f32_16x16x32_bf16 v[94:97], v[86:89], v[190:193], v[94:97]
	v_mfma_f32_16x16x32_bf16 v[90:93], v[142:145], v[190:193], v[90:93]
	v_mfma_f32_16x16x32_bf16 v[78:81], v[86:89], v[198:201], v[78:81]
	v_mfma_f32_16x16x32_bf16 v[74:77], v[142:145], v[198:201], v[74:77]
	v_mfma_f32_16x16x32_bf16 v[70:73], v[86:89], v[206:209], v[70:73]
	v_mfma_f32_16x16x32_bf16 v[66:69], v[142:145], v[206:209], v[66:69]
	v_mfma_f32_16x16x32_bf16 v[30:33], v[158:161], v[178:181], 0
	v_mfma_f32_16x16x32_bf16 v[26:29], v[170:173], v[178:181], 0
	v_mfma_f32_16x16x32_bf16 v[22:25], v[158:161], v[186:189], 0
	v_mfma_f32_16x16x32_bf16 v[18:21], v[170:173], v[186:189], 0
	v_mfma_f32_16x16x32_bf16 v[14:17], v[158:161], v[194:197], 0
	v_mfma_f32_16x16x32_bf16 v[10:13], v[170:173], v[194:197], 0
	v_mfma_f32_16x16x32_bf16 v[6:9], v[158:161], v[202:205], 0
	v_mfma_f32_16x16x32_bf16 v[2:5], v[170:173], v[202:205], 0
	v_mfma_f32_16x16x32_bf16 v[30:33], v[162:165], v[182:185], v[30:33]
	v_mfma_f32_16x16x32_bf16 v[26:29], v[174:177], v[182:185], v[26:29]
	v_mfma_f32_16x16x32_bf16 v[22:25], v[162:165], v[190:193], v[22:25]
	v_mfma_f32_16x16x32_bf16 v[18:21], v[174:177], v[190:193], v[18:21]
	v_mfma_f32_16x16x32_bf16 v[14:17], v[162:165], v[198:201], v[14:17]
	v_mfma_f32_16x16x32_bf16 v[10:13], v[174:177], v[198:201], v[10:13]
	v_mfma_f32_16x16x32_bf16 v[6:9], v[162:165], v[206:209], v[6:9]
	v_mfma_f32_16x16x32_bf16 v[2:5], v[174:177], v[206:209], v[2:5]
	s_setprio 0
	s_barrier
; #define PG8_STAGE(bufoff, gbase, voff) do { _Pragma("unroll") for (int _i = 0; _i < 2; ++_i) \
;         __builtin_amdgcn_global_load_lds((const unsigned*)((const char*)(gbase) + (voff)[_i]), (PG8_LAS unsigned*)(lds + (bufoff) + ldsw + _i * 8192), 16, 0, 0); } while (0)
; #define PG8_LDA(dst, b, h) do { _Pragma("unroll") for (int m = 0; m < 4; ++m) _Pragma("unroll") for (int k = 0; k < 2; ++k) dst[m][k] = *(const PG8_LAS bf16x8*)(lds + PG8_SA(b, h) + aoff + m * 2048 + k * 1024); } while (0)
; #define PG8_LDB(dst, b, h) do { _Pragma("unroll") for (int n = 0; n < 2; ++n) _Pragma("unroll") for (int k = 0; k < 2; ++k) dst[n][k] = *(const PG8_LAS bf16x8*)(lds + PG8_SB(b, h) + boff + n * 2048 + k * 1024); } while (0)
; #define PG8_MMA(ai, bj, At, Bt) do { __builtin_amdgcn_s_setprio(1); _Pragma("unroll") for (int m = 0; m < 4; ++m) _Pragma("unroll") for (int n = 0; n < 2; ++n) _Pragma("unroll") for (int k = 0; k < 2; ++k) \
;         acc[ai][bj][m][n] = __builtin_amdgcn_mfma_f32_16x16x32_bf16(Bt[n][k], At[m][k], acc[ai][bj][m][n], 0, 0, 0); __builtin_amdgcn_s_setprio(0); } while (0)
; #define PG8_WAIT_V(n) asm volatile("s_waitcnt vmcnt(" #n ")" ::: "memory")
; #define PG8_WAIT_L(n) asm volatile("s_waitcnt lgkmcnt(" #n ")" ::: "memory")
; #define PG8_BAR __builtin_amdgcn_s_barrier()
; #define PG8_SCHED __builtin_amdgcn_sched_barrier(0)
; template <class Epi, class Sched, bool ALIGN_EPI = false, bool SP2 = false>
; __device__ __forceinline__ void gemm_phase(PG8_LAS unsigned char* lds, const Gemm g, const Sched& S, const Epi& E) {
;     ...
;             PG8_LDB(B0, 1, 0); PG8_LDB(B1, 1, 1); PG8_SCHED; PG8_LDA(At, 1, 0); PG8_STAGE(PG8_SA(0, 1), a2 + hstep, voffA);
;             PG8_WAIT_V(8); PG8_WAIT_L(0); PG8_BAR; PG8_MMA(0, 0, At, B0); PG8_MMA(0, 1, At, B1); PG8_BAR; PG8_SCHED;
;             PG8_LDA(At, 1, 1); PG8_STAGE(PG8_SB(1, 0), b3, voffB); PG8_STAGE(PG8_SB(1, 1), b3 + hstep, voffB); PG8_STAGE(PG8_SA(1, 0), a3, voffA);
;             PG8_WAIT_V(8); PG8_WAIT_L(0); PG8_BAR; PG8_MMA(1, 0, At, B0); PG8_MMA(1, 1, At, B1); PG8_BAR; PG8_SCHED;
	ds_read_b128 v[82:85], v167 offset:32768
	ds_read_b128 v[86:89], v167 offset:33792
	ds_read_b128 v[138:141], v167 offset:34816
	ds_read_b128 v[142:145], v167 offset:35840
	ds_read_b128 v[158:161], v167 offset:49152
	ds_read_b128 v[162:165], v167 offset:50176
	ds_read_b128 v[170:173], v167 offset:51200
	ds_read_b128 v[174:177], v167 offset:52224
	s_mov_b32 m0, s65
	ds_read_b128 v[178:181], v169 offset:32768
	ds_read_b128 v[182:185], v169 offset:33792
	ds_read_b128 v[186:189], v169 offset:34816
	ds_read_b128 v[190:193], v169 offset:35840
	ds_read_b128 v[194:197], v169 offset:36864
	ds_read_b128 v[198:201], v169 offset:37888
	ds_read_b128 v[202:205], v169 offset:38912
	global_load_lds_dwordx4 v154, s[20:21]
	s_mov_b32 m0, s66
	ds_read_b128 v[206:209], v169 offset:39936
	global_load_lds_dwordx4 v156, s[20:21]
	s_waitcnt vmcnt(8) lgkmcnt(0)
	s_barrier
	s_setprio 1
	v_mfma_f32_16x16x32_bf16 v[134:137], v[82:85], v[178:181], v[134:137]
	v_mfma_f32_16x16x32_bf16 v[130:133], v[138:141], v[178:181], v[130:133]
	v_mfma_f32_16x16x32_bf16 v[126:129], v[82:85], v[186:189], v[126:129]
	v_mfma_f32_16x16x32_bf16 v[122:125], v[138:141], v[186:189], v[122:125]
	v_mfma_f32_16x16x32_bf16 v[118:121], v[82:85], v[194:197], v[118:121]
	v_mfma_f32_16x16x32_bf16 v[114:117], v[138:141], v[194:197], v[114:117]
	v_mfma_f32_16x16x32_bf16 v[110:113], v[82:85], v[202:205], v[110:113]
	v_mfma_f32_16x16x32_bf16 v[106:109], v[138:141], v[202:205], v[106:109]
	v_mfma_f32_16x16x32_bf16 v[134:137], v[86:89], v[182:185], v[134:137]
	v_mfma_f32_16x16x32_bf16 v[130:133], v[142:145], v[182:185], v[130:133]
	v_mfma_f32_16x16x32_bf16 v[126:129], v[86:89], v[190:193], v[126:129]
	v_mfma_f32_16x16x32_bf16 v[122:125], v[142:145], v[190:193], v[122:125]
	v_mfma_f32_16x16x32_bf16 v[118:121], v[86:89], v[198:201], v[118:121]
	v_mfma_f32_16x16x32_bf16 v[114:117], v[142:145], v[198:201], v[114:117]
	v_mfma_f32_16x16x32_bf16 v[110:113], v[86:89], v[206:209], v[110:113]
	v_mfma_f32_16x16x32_bf16 v[106:109], v[142:145], v[206:209], v[106:109]
	v_mfma_f32_16x16x32_bf16 v[62:65], v[158:161], v[178:181], v[62:65]
	v_mfma_f32_16x16x32_bf16 v[58:61], v[170:173], v[178:181], v[58:61]
	v_mfma_f32_16x16x32_bf16 v[54:57], v[158:161], v[186:189], v[54:57]
	v_mfma_f32_16x16x32_bf16 v[50:53], v[170:173], v[186:189], v[50:53]
	v_mfma_f32_16x16x32_bf16 v[46:49], v[158:161], v[194:197], v[46:49]
	v_mfma_f32_16x16x32_bf16 v[42:45], v[170:173], v[194:197], v[42:45]
	v_mfma_f32_16x16x32_bf16 v[38:41], v[158:161], v[202:205], v[38:41]
	v_mfma_f32_16x16x32_bf16 v[34:37], v[170:173], v[202:205], v[34:37]
	v_mfma_f32_16x16x32_bf16 v[62:65], v[162:165], v[182:185], v[62:65]
	v_mfma_f32_16x16x32_bf16 v[58:61], v[174:177], v[182:185], v[58:61]
	v_mfma_f32_16x16x32_bf16 v[54:57], v[162:165], v[190:193], v[54:57]
	v_mfma_f32_16x16x32_bf16 v[50:53], v[174:177], v[190:193], v[50:53]
	v_mfma_f32_16x16x32_bf16 v[46:49], v[162:165], v[198:201], v[46:49]
	v_mfma_f32_16x16x32_bf16 v[42:45], v[174:177], v[198:201], v[42:45]
	v_mfma_f32_16x16x32_bf16 v[38:41], v[162:165], v[206:209], v[38:41]
	v_mfma_f32_16x16x32_bf16 v[34:37], v[174:177], v[206:209], v[34:37]
	s_setprio 0
	s_barrier
	s_add_i32 m0, s62, 0x17f80
	ds_read_b128 v[178:181], v169 offset:49152
	ds_read_b128 v[182:185], v169 offset:50176
	ds_read_b128 v[186:189], v169 offset:51200
	global_load_lds_dwordx4 v148, s[46:47] offset:128
	s_add_i32 m0, s62, 0x19f80
	ds_read_b128 v[190:193], v169 offset:52224
	global_load_lds_dwordx4 v152, s[46:47] offset:128
	s_add_i32 m0, s62, 0x1bf80
	ds_read_b128 v[194:197], v169 offset:53248
	global_load_lds_dwordx4 v148, s[100:101] offset:128
	s_add_i32 m0, s62, 0x1df80
	ds_read_b128 v[198:201], v169 offset:54272
	global_load_lds_dwordx4 v152, s[100:101] offset:128
	s_sub_i32 m0, s68, 0x80
	ds_read_b128 v[202:205], v169 offset:55296
	global_load_lds_dwordx4 v146, s[20:21] offset:128
	s_sub_i32 m0, s69, 0x80
	ds_read_b128 v[206:209], v169 offset:56320
	global_load_lds_dwordx4 v150, s[20:21] offset:128
	s_waitcnt vmcnt(8) lgkmcnt(0)
	s_barrier
	s_setprio 1
	v_mfma_f32_16x16x32_bf16 v[102:105], v[82:85], v[178:181], v[102:105]
	v_mfma_f32_16x16x32_bf16 v[98:101], v[138:141], v[178:181], v[98:101]
	v_mfma_f32_16x16x32_bf16 v[94:97], v[82:85], v[186:189], v[94:97]
	v_mfma_f32_16x16x32_bf16 v[90:93], v[138:141], v[186:189], v[90:93]
	s_add_u32 s16, s16, 0x100
	v_mfma_f32_16x16x32_bf16 v[78:81], v[82:85], v[194:197], v[78:81]
	s_addc_u32 s17, s17, 0
	v_mfma_f32_16x16x32_bf16 v[74:77], v[138:141], v[194:197], v[74:77]
	s_add_u32 s33, s33, 0x100
	v_mfma_f32_16x16x32_bf16 v[70:73], v[82:85], v[202:205], v[70:73]
	s_addc_u32 s39, s39, 0
	v_mfma_f32_16x16x32_bf16 v[66:69], v[138:141], v[202:205], v[66:69]
	s_mov_b32 s20, s44
	v_mfma_f32_16x16x32_bf16 v[102:105], v[86:89], v[182:185], v[102:105]
	v_mfma_f32_16x16x32_bf16 v[98:101], v[142:145], v[182:185], v[98:101]
	v_mfma_f32_16x16x32_bf16 v[94:97], v[86:89], v[190:193], v[94:97]
	v_mfma_f32_16x16x32_bf16 v[90:93], v[142:145], v[190:193], v[90:93]
	v_mfma_f32_16x16x32_bf16 v[78:81], v[86:89], v[198:201], v[78:81]
	v_mfma_f32_16x16x32_bf16 v[74:77], v[142:145], v[198:201], v[74:77]
	v_mfma_f32_16x16x32_bf16 v[70:73], v[86:89], v[206:209], v[70:73]
	v_mfma_f32_16x16x32_bf16 v[66:69], v[142:145], v[206:209], v[66:69]
	v_mfma_f32_16x16x32_bf16 v[30:33], v[158:161], v[178:181], v[30:33]
	v_mfma_f32_16x16x32_bf16 v[26:29], v[170:173], v[178:181], v[26:29]
	v_mfma_f32_16x16x32_bf16 v[22:25], v[158:161], v[186:189], v[22:25]
	v_mfma_f32_16x16x32_bf16 v[18:21], v[170:173], v[186:189], v[18:21]
	v_mfma_f32_16x16x32_bf16 v[14:17], v[158:161], v[194:197], v[14:17]
	v_mfma_f32_16x16x32_bf16 v[10:13], v[170:173], v[194:197], v[10:13]
	v_mfma_f32_16x16x32_bf16 v[6:9], v[158:161], v[202:205], v[6:9]
	v_mfma_f32_16x16x32_bf16 v[2:5], v[170:173], v[202:205], v[2:5]
	v_mfma_f32_16x16x32_bf16 v[30:33], v[162:165], v[182:185], v[30:33]
	v_mfma_f32_16x16x32_bf16 v[26:29], v[174:177], v[182:185], v[26:29]
	v_mfma_f32_16x16x32_bf16 v[22:25], v[162:165], v[190:193], v[22:25]
	v_mfma_f32_16x16x32_bf16 v[18:21], v[174:177], v[190:193], v[18:21]
	v_mfma_f32_16x16x32_bf16 v[14:17], v[162:165], v[198:201], v[14:17]
	v_mfma_f32_16x16x32_bf16 v[10:13], v[174:177], v[198:201], v[10:13]
	v_mfma_f32_16x16x32_bf16 v[6:9], v[162:165], v[206:209], v[6:9]
	v_mfma_f32_16x16x32_bf16 v[2:5], v[174:177], v[206:209], v[2:5]
	s_setprio 0
	s_barrier
	s_cmp_ge_i32 s44, s67
	s_cbranch_scc1 .Lpz_exit_341
; #define PG8_STAGE(bufoff, gbase, voff) do { _Pragma("unroll") for (int _i = 0; _i < 2; ++_i) \
;         __builtin_amdgcn_global_load_lds((const unsigned*)((const char*)(gbase) + (voff)[_i]), (PG8_LAS unsigned*)(lds + (bufoff) + ldsw + _i * 8192), 16, 0, 0); } while (0)
; #define PG8_LDA(dst, b, h) do { _Pragma("unroll") for (int m = 0; m < 4; ++m) _Pragma("unroll") for (int k = 0; k < 2; ++k) dst[m][k] = *(const PG8_LAS bf16x8*)(lds + PG8_SA(b, h) + aoff + m * 2048 + k * 1024); } while (0)
; #define PG8_LDB(dst, b, h) do { _Pragma("unroll") for (int n = 0; n < 2; ++n) _Pragma("unroll") for (int k = 0; k < 2; ++k) dst[n][k] = *(const PG8_LAS bf16x8*)(lds + PG8_SB(b, h) + boff + n * 2048 + k * 1024); } while (0)
; #define PG8_MMA(ai, bj, At, Bt) do { __builtin_amdgcn_s_setprio(1); _Pragma("unroll") for (int m = 0; m < 4; ++m) _Pragma("unroll") for (int n = 0; n < 2; ++n) _Pragma("unroll") for (int k = 0; k < 2; ++k) \
;         acc[ai][bj][m][n] = __builtin_amdgcn_mfma_f32_16x16x32_bf16(Bt[n][k], At[m][k], acc[ai][bj][m][n], 0, 0, 0); __builtin_amdgcn_s_setprio(0); } while (0)
; #define PG8_WAIT_V(n) asm volatile("s_waitcnt vmcnt(" #n ")" ::: "memory")
; #define PG8_BAR __builtin_amdgcn_s_barrier()
; template <class Epi, class Sched, bool ALIGN_EPI = false, bool SP2 = false>
; __device__ __forceinline__ void gemm_phase(PG8_LAS unsigned char* lds, const Gemm g, const Sched& S, const Epi& E) {
;     ...
;         for (int t = 0; t < nt; t += 2) {
;             const bool last = (t == nt - 2);
;             const char* a1 = cA + (size_t)(t + 1) * kstep;
;             const char* a2 = last ? nA : cA + (size_t)(t + 2) * kstep; const char* b2 = last ? nB : cB + (size_t)(t + 2) * kstep;
;             const char* a3 = a2 + kstep; const char* b3 = b2 + kstep;
;             if (last && has_next) S.a_ready(nxt);
;             if constexpr (SP2) {
;             PG8_LDB(B0, 0, 0); PG8_LDB(B1, 0, 1); PG8_SCHED; PG8_LDA(At, 0, 0); PG8_STAGE(PG8_SA(1, 1), a1 + hstep, voffA);
;             PG8_WAIT_V(8); PG8_WAIT_L(0); PG8_BAR; PG8_MMA(0, 0, At, B0); PG8_MMA(0, 1, At, B1); PG8_BAR; PG8_SCHED;
;             PG8_LDA(At, 0, 1); PG8_STAGE(PG8_SB(0, 0), b2, voffB); PG8_STAGE(PG8_SB(0, 1), b2 + hstep, voffB); PG8_STAGE(PG8_SA(0, 0), a2, voffA);
;             PG8_WAIT_V(8); PG8_WAIT_L(0); PG8_BAR; PG8_MMA(1, 0, At, B0); PG8_MMA(1, 1, At, B1); PG8_BAR; PG8_SCHED;
.LBB0_341:
	ds_read_b128 v[82:85], v167
	ds_read_b128 v[86:89], v167 offset:1024
	ds_read_b128 v[138:141], v167 offset:2048
	ds_read_b128 v[142:145], v167 offset:3072
	ds_read_b128 v[158:161], v167 offset:16384
	ds_read_b128 v[162:165], v167 offset:17408
	ds_read_b128 v[170:173], v167 offset:18432
	ds_read_b128 v[174:177], v167 offset:19456
	s_add_i32 m0, s63, 0xc000
	ds_read_b128 v[178:181], v169
	ds_read_b128 v[182:185], v169 offset:1024
	ds_read_b128 v[186:189], v169 offset:2048
	ds_read_b128 v[190:193], v169 offset:3072
	ds_read_b128 v[194:197], v169 offset:4096
	ds_read_b128 v[198:201], v169 offset:5120
	ds_read_b128 v[202:205], v169 offset:6144
	global_load_lds_dwordx4 v154, s[16:17]
	s_add_i32 m0, s63, 0xe000
	ds_read_b128 v[206:209], v169 offset:7168
	global_load_lds_dwordx4 v156, s[16:17]
	s_waitcnt vmcnt(8) lgkmcnt(0)
	s_barrier
	s_setprio 1
	v_mfma_f32_16x16x32_bf16 v[134:137], v[82:85], v[178:181], v[134:137]
	v_mfma_f32_16x16x32_bf16 v[130:133], v[138:141], v[178:181], v[130:133]
	v_mfma_f32_16x16x32_bf16 v[126:129], v[82:85], v[186:189], v[126:129]
	v_mfma_f32_16x16x32_bf16 v[122:125], v[138:141], v[186:189], v[122:125]
	s_add_i32 s44, s20, 2
	v_mfma_f32_16x16x32_bf16 v[118:121], v[82:85], v[194:197], v[118:121]
	s_add_u32 s45, s16, 0x80
	v_mfma_f32_16x16x32_bf16 v[114:117], v[138:141], v[194:197], v[114:117]
	s_addc_u32 s21, s17, 0
	v_mfma_f32_16x16x32_bf16 v[110:113], v[82:85], v[202:205], v[110:113]
	s_cmp_eq_u32 s70, s20
	v_mfma_f32_16x16x32_bf16 v[106:109], v[138:141], v[202:205], v[106:109]
	s_cselect_b32 s21, s7, s21
	v_mfma_f32_16x16x32_bf16 v[134:137], v[86:89], v[182:185], v[134:137]
	s_cselect_b32 s20, s6, s45
	v_mfma_f32_16x16x32_bf16 v[130:133], v[142:145], v[182:185], v[130:133]
	s_cselect_b32 s47, s57, s39
	v_mfma_f32_16x16x32_bf16 v[126:129], v[86:89], v[190:193], v[126:129]
	s_cselect_b32 s46, s56, s33
	v_mfma_f32_16x16x32_bf16 v[122:125], v[142:145], v[190:193], v[122:125]
	v_mfma_f32_16x16x32_bf16 v[118:121], v[86:89], v[198:201], v[118:121]
	v_mfma_f32_16x16x32_bf16 v[114:117], v[142:145], v[198:201], v[114:117]
	v_mfma_f32_16x16x32_bf16 v[110:113], v[86:89], v[206:209], v[110:113]
	v_mfma_f32_16x16x32_bf16 v[106:109], v[142:145], v[206:209], v[106:109]
	v_mfma_f32_16x16x32_bf16 v[62:65], v[158:161], v[178:181], v[62:65]
	v_mfma_f32_16x16x32_bf16 v[58:61], v[170:173], v[178:181], v[58:61]
	v_mfma_f32_16x16x32_bf16 v[54:57], v[158:161], v[186:189], v[54:57]
	v_mfma_f32_16x16x32_bf16 v[50:53], v[170:173], v[186:189], v[50:53]
	v_mfma_f32_16x16x32_bf16 v[46:49], v[158:161], v[194:197], v[46:49]
	v_mfma_f32_16x16x32_bf16 v[42:45], v[170:173], v[194:197], v[42:45]
	v_mfma_f32_16x16x32_bf16 v[38:41], v[158:161], v[202:205], v[38:41]
	v_mfma_f32_16x16x32_bf16 v[34:37], v[170:173], v[202:205], v[34:37]
	v_mfma_f32_16x16x32_bf16 v[62:65], v[162:165], v[182:185], v[62:65]
	v_mfma_f32_16x16x32_bf16 v[58:61], v[174:177], v[182:185], v[58:61]
	v_mfma_f32_16x16x32_bf16 v[54:57], v[162:165], v[190:193], v[54:57]
	v_mfma_f32_16x16x32_bf16 v[50:53], v[174:177], v[190:193], v[50:53]
	v_mfma_f32_16x16x32_bf16 v[46:49], v[162:165], v[198:201], v[46:49]
	v_mfma_f32_16x16x32_bf16 v[42:45], v[174:177], v[198:201], v[42:45]
	v_mfma_f32_16x16x32_bf16 v[38:41], v[162:165], v[206:209], v[38:41]
	v_mfma_f32_16x16x32_bf16 v[34:37], v[174:177], v[206:209], v[34:37]
	s_setprio 0
	s_barrier
	s_add_i32 m0, s62, 0x10000
	s_add_u32 s100, s46, s10
	s_addc_u32 s101, s47, s11
	ds_read_b128 v[178:181], v169 offset:16384
	ds_read_b128 v[182:185], v169 offset:17408
	ds_read_b128 v[186:189], v169 offset:18432
	global_load_lds_dwordx4 v148, s[46:47]
	s_add_i32 m0, s62, 0x12000
	ds_read_b128 v[190:193], v169 offset:19456
	global_load_lds_dwordx4 v152, s[46:47]
	s_add_i32 m0, s62, 0x14000
	ds_read_b128 v[194:197], v169 offset:20480
	global_load_lds_dwordx4 v148, s[100:101]
	s_add_i32 m0, s62, 0x16000
	ds_read_b128 v[198:201], v169 offset:21504
	global_load_lds_dwordx4 v152, s[100:101]
	s_mov_b32 m0, s63
	ds_read_b128 v[202:205], v169 offset:22528
	global_load_lds_dwordx4 v146, s[20:21]
	s_mov_b32 m0, s64
	ds_read_b128 v[206:209], v169 offset:23552
	global_load_lds_dwordx4 v150, s[20:21]
	s_waitcnt vmcnt(8) lgkmcnt(0)
	s_barrier
	s_setprio 1
	v_mfma_f32_16x16x32_bf16 v[102:105], v[82:85], v[178:181], v[102:105]
	v_mfma_f32_16x16x32_bf16 v[98:101], v[138:141], v[178:181], v[98:101]
	v_mfma_f32_16x16x32_bf16 v[94:97], v[82:85], v[186:189], v[94:97]
	v_mfma_f32_16x16x32_bf16 v[90:93], v[138:141], v[186:189], v[90:93]
	v_mfma_f32_16x16x32_bf16 v[78:81], v[82:85], v[194:197], v[78:81]
	v_mfma_f32_16x16x32_bf16 v[74:77], v[138:141], v[194:197], v[74:77]
	v_mfma_f32_16x16x32_bf16 v[70:73], v[82:85], v[202:205], v[70:73]
	v_mfma_f32_16x16x32_bf16 v[66:69], v[138:141], v[202:205], v[66:69]
	v_mfma_f32_16x16x32_bf16 v[102:105], v[86:89], v[182:185], v[102:105]
	v_mfma_f32_16x16x32_bf16 v[98:101], v[142:145], v[182:185], v[98:101]
	v_mfma_f32_16x16x32_bf16 v[94:97], v[86:89], v[190:193], v[94:97]
	v_mfma_f32_16x16x32_bf16 v[90:93], v[142:145], v[190:193], v[90:93]
	v_mfma_f32_16x16x32_bf16 v[78:81], v[86:89], v[198:201], v[78:81]
	v_mfma_f32_16x16x32_bf16 v[74:77], v[142:145], v[198:201], v[74:77]
	v_mfma_f32_16x16x32_bf16 v[70:73], v[86:89], v[206:209], v[70:73]
	v_mfma_f32_16x16x32_bf16 v[66:69], v[142:145], v[206:209], v[66:69]
	v_mfma_f32_16x16x32_bf16 v[30:33], v[158:161], v[178:181], v[30:33]
	v_mfma_f32_16x16x32_bf16 v[26:29], v[170:173], v[178:181], v[26:29]
	v_mfma_f32_16x16x32_bf16 v[22:25], v[158:161], v[186:189], v[22:25]
	v_mfma_f32_16x16x32_bf16 v[18:21], v[170:173], v[186:189], v[18:21]
	v_mfma_f32_16x16x32_bf16 v[14:17], v[158:161], v[194:197], v[14:17]
	v_mfma_f32_16x16x32_bf16 v[10:13], v[170:173], v[194:197], v[10:13]
	v_mfma_f32_16x16x32_bf16 v[6:9], v[158:161], v[202:205], v[6:9]
	v_mfma_f32_16x16x32_bf16 v[2:5], v[170:173], v[202:205], v[2:5]
	v_mfma_f32_16x16x32_bf16 v[30:33], v[162:165], v[182:185], v[30:33]
	v_mfma_f32_16x16x32_bf16 v[26:29], v[174:177], v[182:185], v[26:29]
	v_mfma_f32_16x16x32_bf16 v[22:25], v[162:165], v[190:193], v[22:25]
	v_mfma_f32_16x16x32_bf16 v[18:21], v[174:177], v[190:193], v[18:21]
	v_mfma_f32_16x16x32_bf16 v[14:17], v[162:165], v[198:201], v[14:17]
	v_mfma_f32_16x16x32_bf16 v[10:13], v[174:177], v[198:201], v[10:13]
	v_mfma_f32_16x16x32_bf16 v[6:9], v[162:165], v[206:209], v[6:9]
	v_mfma_f32_16x16x32_bf16 v[2:5], v[174:177], v[206:209], v[2:5]
	s_setprio 0
	s_barrier
; #define PG8_STAGE(bufoff, gbase, voff) do { _Pragma("unroll") for (int _i = 0; _i < 2; ++_i) \
;         __builtin_amdgcn_global_load_lds((const unsigned*)((const char*)(gbase) + (voff)[_i]), (PG8_LAS unsigned*)(lds + (bufoff) + ldsw + _i * 8192), 16, 0, 0); } while (0)
; #define PG8_LDA(dst, b, h) do { _Pragma("unroll") for (int m = 0; m < 4; ++m) _Pragma("unroll") for (int k = 0; k < 2; ++k) dst[m][k] = *(const PG8_LAS bf16x8*)(lds + PG8_SA(b, h) + aoff + m * 2048 + k * 1024); } while (0)
; #define PG8_LDB(dst, b, h) do { _Pragma("unroll") for (int n = 0; n < 2; ++n) _Pragma("unroll") for (int k = 0; k < 2; ++k) dst[n][k] = *(const PG8_LAS bf16x8*)(lds + PG8_SB(b, h) + boff + n * 2048 + k * 1024); } while (0)
; #define PG8_MMA(ai, bj, At, Bt) do { __builtin_amdgcn_s_setprio(1); _Pragma("unroll") for (int m = 0; m < 4; ++m) _Pragma("unroll") for (int n = 0; n < 2; ++n) _Pragma("unroll") for (int k = 0; k < 2; ++k) \
;         acc[ai][bj][m][n] = __builtin_amdgcn_mfma_f32_16x16x32_bf16(Bt[n][k], At[m][k], acc[ai][bj][m][n], 0, 0, 0); __builtin_amdgcn_s_setprio(0); } while (0)
; #define PG8_WAIT_V(n) asm volatile("s_waitcnt vmcnt(" #n ")" ::: "memory")
; #define PG8_WAIT_L(n) asm volatile("s_waitcnt lgkmcnt(" #n ")" ::: "memory")
; #define PG8_BAR __builtin_amdgcn_s_barrier()
; #define PG8_SCHED __builtin_amdgcn_sched_barrier(0)
; template <class Epi, class Sched, bool ALIGN_EPI = false, bool SP2 = false>
; __device__ __forceinline__ void gemm_phase(PG8_LAS unsigned char* lds, const Gemm g, const Sched& S, const Epi& E) {
;     ...
;             PG8_LDB(B0, 1, 0); PG8_LDB(B1, 1, 1); PG8_SCHED; PG8_LDA(At, 1, 0); PG8_STAGE(PG8_SA(0, 1), a2 + hstep, voffA);
;             PG8_WAIT_V(8); PG8_WAIT_L(0); PG8_BAR; PG8_MMA(0, 0, At, B0); PG8_MMA(0, 1, At, B1); PG8_BAR; PG8_SCHED;
;             PG8_LDA(At, 1, 1); PG8_STAGE(PG8_SB(1, 0), b3, voffB); PG8_STAGE(PG8_SB(1, 1), b3 + hstep, voffB); PG8_STAGE(PG8_SA(1, 0), a3, voffA);
;             PG8_WAIT_V(8); PG8_WAIT_L(0); PG8_BAR; PG8_MMA(1, 0, At, B0); PG8_MMA(1, 1, At, B1); PG8_BAR; PG8_SCHED;
	ds_read_b128 v[82:85], v167 offset:32768
	ds_read_b128 v[86:89], v167 offset:33792
	ds_read_b128 v[138:141], v167 offset:34816
	ds_read_b128 v[142:145], v167 offset:35840
	ds_read_b128 v[158:161], v167 offset:49152
	ds_read_b128 v[162:165], v167 offset:50176
	ds_read_b128 v[170:173], v167 offset:51200
	ds_read_b128 v[174:177], v167 offset:52224
	s_mov_b32 m0, s65
	ds_read_b128 v[178:181], v169 offset:32768
	ds_read_b128 v[182:185], v169 offset:33792
	ds_read_b128 v[186:189], v169 offset:34816
	ds_read_b128 v[190:193], v169 offset:35840
	ds_read_b128 v[194:197], v169 offset:36864
	ds_read_b128 v[198:201], v169 offset:37888
	ds_read_b128 v[202:205], v169 offset:38912
	global_load_lds_dwordx4 v154, s[20:21]
	s_mov_b32 m0, s66
	ds_read_b128 v[206:209], v169 offset:39936
	global_load_lds_dwordx4 v156, s[20:21]
	s_waitcnt vmcnt(8) lgkmcnt(0)
	s_barrier
	s_setprio 1
	v_mfma_f32_16x16x32_bf16 v[134:137], v[82:85], v[178:181], v[134:137]
	v_mfma_f32_16x16x32_bf16 v[130:133], v[138:141], v[178:181], v[130:133]
	v_mfma_f32_16x16x32_bf16 v[126:129], v[82:85], v[186:189], v[126:129]
	v_mfma_f32_16x16x32_bf16 v[122:125], v[138:141], v[186:189], v[122:125]
	v_mfma_f32_16x16x32_bf16 v[118:121], v[82:85], v[194:197], v[118:121]
	v_mfma_f32_16x16x32_bf16 v[114:117], v[138:141], v[194:197], v[114:117]
	v_mfma_f32_16x16x32_bf16 v[110:113], v[82:85], v[202:205], v[110:113]
	v_mfma_f32_16x16x32_bf16 v[106:109], v[138:141], v[202:205], v[106:109]
	v_mfma_f32_16x16x32_bf16 v[134:137], v[86:89], v[182:185], v[134:137]
	v_mfma_f32_16x16x32_bf16 v[130:133], v[142:145], v[182:185], v[130:133]
	v_mfma_f32_16x16x32_bf16 v[126:129], v[86:89], v[190:193], v[126:129]
	v_mfma_f32_16x16x32_bf16 v[122:125], v[142:145], v[190:193], v[122:125]
	v_mfma_f32_16x16x32_bf16 v[118:121], v[86:89], v[198:201], v[118:121]
	v_mfma_f32_16x16x32_bf16 v[114:117], v[142:145], v[198:201], v[114:117]
	v_mfma_f32_16x16x32_bf16 v[110:113], v[86:89], v[206:209], v[110:113]
	v_mfma_f32_16x16x32_bf16 v[106:109], v[142:145], v[206:209], v[106:109]
	v_mfma_f32_16x16x32_bf16 v[62:65], v[158:161], v[178:181], v[62:65]
	v_mfma_f32_16x16x32_bf16 v[58:61], v[170:173], v[178:181], v[58:61]
	v_mfma_f32_16x16x32_bf16 v[54:57], v[158:161], v[186:189], v[54:57]
	v_mfma_f32_16x16x32_bf16 v[50:53], v[170:173], v[186:189], v[50:53]
	v_mfma_f32_16x16x32_bf16 v[46:49], v[158:161], v[194:197], v[46:49]
	v_mfma_f32_16x16x32_bf16 v[42:45], v[170:173], v[194:197], v[42:45]
	v_mfma_f32_16x16x32_bf16 v[38:41], v[158:161], v[202:205], v[38:41]
	v_mfma_f32_16x16x32_bf16 v[34:37], v[170:173], v[202:205], v[34:37]
	v_mfma_f32_16x16x32_bf16 v[62:65], v[162:165], v[182:185], v[62:65]
	v_mfma_f32_16x16x32_bf16 v[58:61], v[174:177], v[182:185], v[58:61]
	v_mfma_f32_16x16x32_bf16 v[54:57], v[162:165], v[190:193], v[54:57]
	v_mfma_f32_16x16x32_bf16 v[50:53], v[174:177], v[190:193], v[50:53]
	v_mfma_f32_16x16x32_bf16 v[46:49], v[162:165], v[198:201], v[46:49]
	v_mfma_f32_16x16x32_bf16 v[42:45], v[174:177], v[198:201], v[42:45]
	v_mfma_f32_16x16x32_bf16 v[38:41], v[162:165], v[206:209], v[38:41]
	v_mfma_f32_16x16x32_bf16 v[34:37], v[174:177], v[206:209], v[34:37]
	s_setprio 0
	s_barrier
	s_add_i32 m0, s62, 0x17f80
	ds_read_b128 v[178:181], v169 offset:49152
	ds_read_b128 v[182:185], v169 offset:50176
	ds_read_b128 v[186:189], v169 offset:51200
	global_load_lds_dwordx4 v148, s[46:47] offset:128
	s_add_i32 m0, s62, 0x19f80
	ds_read_b128 v[190:193], v169 offset:52224
	global_load_lds_dwordx4 v152, s[46:47] offset:128
	s_add_i32 m0, s62, 0x1bf80
	ds_read_b128 v[194:197], v169 offset:53248
	global_load_lds_dwordx4 v148, s[100:101] offset:128
	s_add_i32 m0, s62, 0x1df80
	ds_read_b128 v[198:201], v169 offset:54272
	global_load_lds_dwordx4 v152, s[100:101] offset:128
	s_sub_i32 m0, s68, 0x80
	ds_read_b128 v[202:205], v169 offset:55296
	global_load_lds_dwordx4 v146, s[20:21] offset:128
	s_sub_i32 m0, s69, 0x80
	ds_read_b128 v[206:209], v169 offset:56320
	global_load_lds_dwordx4 v150, s[20:21] offset:128
	s_waitcnt vmcnt(8) lgkmcnt(0)
	s_barrier
	s_setprio 1
	v_mfma_f32_16x16x32_bf16 v[102:105], v[82:85], v[178:181], v[102:105]
	v_mfma_f32_16x16x32_bf16 v[98:101], v[138:141], v[178:181], v[98:101]
	v_mfma_f32_16x16x32_bf16 v[94:97], v[82:85], v[186:189], v[94:97]
	v_mfma_f32_16x16x32_bf16 v[90:93], v[138:141], v[186:189], v[90:93]
	s_add_u32 s16, s16, 0x100
	v_mfma_f32_16x16x32_bf16 v[78:81], v[82:85], v[194:197], v[78:81]
	s_addc_u32 s17, s17, 0
	v_mfma_f32_16x16x32_bf16 v[74:77], v[138:141], v[194:197], v[74:77]
	s_add_u32 s33, s33, 0x100
	v_mfma_f32_16x16x32_bf16 v[70:73], v[82:85], v[202:205], v[70:73]
	s_addc_u32 s39, s39, 0
	v_mfma_f32_16x16x32_bf16 v[66:69], v[138:141], v[202:205], v[66:69]
	s_mov_b32 s20, s44
	v_mfma_f32_16x16x32_bf16 v[102:105], v[86:89], v[182:185], v[102:105]
	v_mfma_f32_16x16x32_bf16 v[98:101], v[142:145], v[182:185], v[98:101]
	v_mfma_f32_16x16x32_bf16 v[94:97], v[86:89], v[190:193], v[94:97]
	v_mfma_f32_16x16x32_bf16 v[90:93], v[142:145], v[190:193], v[90:93]
	v_mfma_f32_16x16x32_bf16 v[78:81], v[86:89], v[198:201], v[78:81]
	v_mfma_f32_16x16x32_bf16 v[74:77], v[142:145], v[198:201], v[74:77]
	v_mfma_f32_16x16x32_bf16 v[70:73], v[86:89], v[206:209], v[70:73]
	v_mfma_f32_16x16x32_bf16 v[66:69], v[142:145], v[206:209], v[66:69]
	v_mfma_f32_16x16x32_bf16 v[30:33], v[158:161], v[178:181], v[30:33]
	v_mfma_f32_16x16x32_bf16 v[26:29], v[170:173], v[178:181], v[26:29]
	v_mfma_f32_16x16x32_bf16 v[22:25], v[158:161], v[186:189], v[22:25]
	v_mfma_f32_16x16x32_bf16 v[18:21], v[170:173], v[186:189], v[18:21]
	v_mfma_f32_16x16x32_bf16 v[14:17], v[158:161], v[194:197], v[14:17]
	v_mfma_f32_16x16x32_bf16 v[10:13], v[170:173], v[194:197], v[10:13]
	v_mfma_f32_16x16x32_bf16 v[6:9], v[158:161], v[202:205], v[6:9]
	v_mfma_f32_16x16x32_bf16 v[2:5], v[170:173], v[202:205], v[2:5]
	v_mfma_f32_16x16x32_bf16 v[30:33], v[162:165], v[182:185], v[30:33]
	v_mfma_f32_16x16x32_bf16 v[26:29], v[174:177], v[182:185], v[26:29]
	v_mfma_f32_16x16x32_bf16 v[22:25], v[162:165], v[190:193], v[22:25]
	v_mfma_f32_16x16x32_bf16 v[18:21], v[174:177], v[190:193], v[18:21]
	v_mfma_f32_16x16x32_bf16 v[14:17], v[162:165], v[198:201], v[14:17]
	v_mfma_f32_16x16x32_bf16 v[10:13], v[174:177], v[198:201], v[10:13]
	v_mfma_f32_16x16x32_bf16 v[6:9], v[162:165], v[206:209], v[6:9]
	v_mfma_f32_16x16x32_bf16 v[2:5], v[174:177], v[206:209], v[2:5]
	s_setprio 0
	s_barrier
	s_cmp_ge_i32 s44, s67
	s_cbranch_scc0 .LBB0_341

; #define PG8_STAGE(bufoff, gbase, voff) do { _Pragma("unroll") for (int _i = 0; _i < 2; ++_i) \
;         __builtin_amdgcn_global_load_lds((const unsigned*)((const char*)(gbase) + (voff)[_i]), (PG8_LAS unsigned*)(lds + (bufoff) + ldsw + _i * 8192), 16, 0, 0); } while (0)
; #define PG8_LDA(dst, b, h) do { _Pragma("unroll") for (int m = 0; m < 4; ++m) _Pragma("unroll") for (int k = 0; k < 2; ++k) dst[m][k] = *(const PG8_LAS bf16x8*)(lds + PG8_SA(b, h) + aoff + m * 2048 + k * 1024); } while (0)
; #define PG8_LDB(dst, b, h) do { _Pragma("unroll") for (int n = 0; n < 2; ++n) _Pragma("unroll") for (int k = 0; k < 2; ++k) dst[n][k] = *(const PG8_LAS bf16x8*)(lds + PG8_SB(b, h) + boff + n * 2048 + k * 1024); } while (0)
; #define PG8_MMA(ai, bj, At, Bt) do { __builtin_amdgcn_s_setprio(1); _Pragma("unroll") for (int m = 0; m < 4; ++m) _Pragma("unroll") for (int n = 0; n < 2; ++n) _Pragma("unroll") for (int k = 0; k < 2; ++k) \
;         acc[ai][bj][m][n] = __builtin_amdgcn_mfma_f32_16x16x32_bf16(Bt[n][k], At[m][k], acc[ai][bj][m][n], 0, 0, 0); __builtin_amdgcn_s_setprio(0); } while (0)
; #define PG8_WAIT_V(n) asm volatile("s_waitcnt vmcnt(" #n ")" ::: "memory")
; #define PG8_BAR __builtin_amdgcn_s_barrier()
; template <class Epi, class Sched, bool ALIGN_EPI = false, bool SP2 = false>
; __device__ __forceinline__ void gemm_phase(PG8_LAS unsigned char* lds, const Gemm g, const Sched& S, const Epi& E) {
;     ...
;         for (int t = 0; t < nt; t += 2) {
;             const bool last = (t == nt - 2);
;             const char* a1 = cA + (size_t)(t + 1) * kstep;
;             const char* a2 = last ? nA : cA + (size_t)(t + 2) * kstep; const char* b2 = last ? nB : cB + (size_t)(t + 2) * kstep;
;             const char* a3 = a2 + kstep; const char* b3 = b2 + kstep;
;             if (last && has_next) S.a_ready(nxt);
;             if constexpr (SP2) {
;             PG8_LDB(B0, 0, 0); PG8_LDB(B1, 0, 1); PG8_SCHED; PG8_LDA(At, 0, 0); PG8_STAGE(PG8_SA(1, 1), a1 + hstep, voffA);
;             PG8_WAIT_V(8); PG8_WAIT_L(0); PG8_BAR; PG8_MMA(0, 0, At, B0); PG8_MMA(0, 1, At, B1); PG8_BAR; PG8_SCHED;
;             PG8_LDA(At, 0, 1); PG8_STAGE(PG8_SB(0, 0), b2, voffB); PG8_STAGE(PG8_SB(0, 1), b2 + hstep, voffB); PG8_STAGE(PG8_SA(0, 0), a2, voffA);
;             PG8_WAIT_V(8); PG8_WAIT_L(0); PG8_BAR; PG8_MMA(1, 0, At, B0); PG8_MMA(1, 1, At, B1); PG8_BAR; PG8_SCHED;
.Lz_enter_518:
	s_add_u32 s8, s52, 0x80
	s_addc_u32 s9, s53, 0
	s_add_u32 s52, s20, 0x100
	s_addc_u32 s53, s21, 0
	s_mov_b32 s20, 0
	ds_read_b128 v[130:133], v185
	ds_read_b128 v[134:137], v185 offset:1024
	ds_read_b128 v[138:141], v185 offset:2048
	ds_read_b128 v[142:145], v185 offset:3072
	ds_read_b128 v[146:149], v185 offset:16384
	ds_read_b128 v[150:153], v185 offset:17408
	ds_read_b128 v[166:169], v185 offset:18432
	ds_read_b128 v[170:173], v185 offset:19456
	s_add_i32 m0, s56, 0xc000
	ds_read_b128 v[174:177], v189
	ds_read_b128 v[178:181], v189 offset:1024
	ds_read_b128 v[190:193], v189 offset:2048
	ds_read_b128 v[194:197], v189 offset:3072
	ds_read_b128 v[198:201], v189 offset:4096
	ds_read_b128 v[202:205], v189 offset:5120
	ds_read_b128 v[206:209], v189 offset:6144
	global_load_lds_dwordx4 v162, s[8:9]
	s_add_i32 m0, s56, 0xe000
	ds_read_b128 v[210:213], v189 offset:7168
	global_load_lds_dwordx4 v164, s[8:9]
	s_waitcnt vmcnt(8) lgkmcnt(0)
	s_barrier
	s_setprio 1
	v_mfma_f32_16x16x32_bf16 v[126:129], v[130:133], v[174:177], 0
	v_mfma_f32_16x16x32_bf16 v[122:125], v[138:141], v[174:177], 0
	v_mfma_f32_16x16x32_bf16 v[110:113], v[130:133], v[190:193], 0
	v_mfma_f32_16x16x32_bf16 v[106:109], v[138:141], v[190:193], 0
	s_add_i32 s69, s20, 2
	v_mfma_f32_16x16x32_bf16 v[94:97], v[130:133], v[198:201], 0
	s_add_u32 s70, s8, 0x80
	v_mfma_f32_16x16x32_bf16 v[90:93], v[138:141], v[198:201], 0
	s_addc_u32 s21, s9, 0
	v_mfma_f32_16x16x32_bf16 v[78:81], v[130:133], v[206:209], 0
	s_cmp_eq_u32 s63, s20
	v_mfma_f32_16x16x32_bf16 v[74:77], v[138:141], v[206:209], 0
	s_cselect_b32 s21, s49, s21
	v_mfma_f32_16x16x32_bf16 v[126:129], v[134:137], v[178:181], v[126:129]
	s_cselect_b32 s20, s48, s70
	v_mfma_f32_16x16x32_bf16 v[122:125], v[142:145], v[178:181], v[122:125]
	s_cselect_b32 s71, s51, s53
	v_mfma_f32_16x16x32_bf16 v[110:113], v[134:137], v[194:197], v[110:113]
	s_cselect_b32 s70, s50, s52
	v_mfma_f32_16x16x32_bf16 v[106:109], v[142:145], v[194:197], v[106:109]
	v_mfma_f32_16x16x32_bf16 v[94:97], v[134:137], v[202:205], v[94:97]
	v_mfma_f32_16x16x32_bf16 v[90:93], v[142:145], v[202:205], v[90:93]
	v_mfma_f32_16x16x32_bf16 v[78:81], v[134:137], v[210:213], v[78:81]
	v_mfma_f32_16x16x32_bf16 v[74:77], v[142:145], v[210:213], v[74:77]
	v_mfma_f32_16x16x32_bf16 v[118:121], v[146:149], v[174:177], 0
	v_mfma_f32_16x16x32_bf16 v[114:117], v[166:169], v[174:177], 0
	v_mfma_f32_16x16x32_bf16 v[102:105], v[146:149], v[190:193], 0
	v_mfma_f32_16x16x32_bf16 v[98:101], v[166:169], v[190:193], 0
	v_mfma_f32_16x16x32_bf16 v[86:89], v[146:149], v[198:201], 0
	v_mfma_f32_16x16x32_bf16 v[82:85], v[166:169], v[198:201], 0
	v_mfma_f32_16x16x32_bf16 v[70:73], v[146:149], v[206:209], 0
	v_mfma_f32_16x16x32_bf16 v[66:69], v[166:169], v[206:209], 0
	v_mfma_f32_16x16x32_bf16 v[118:121], v[150:153], v[178:181], v[118:121]
	v_mfma_f32_16x16x32_bf16 v[114:117], v[170:173], v[178:181], v[114:117]
	v_mfma_f32_16x16x32_bf16 v[102:105], v[150:153], v[194:197], v[102:105]
	v_mfma_f32_16x16x32_bf16 v[98:101], v[170:173], v[194:197], v[98:101]
	v_mfma_f32_16x16x32_bf16 v[86:89], v[150:153], v[202:205], v[86:89]
	v_mfma_f32_16x16x32_bf16 v[82:85], v[170:173], v[202:205], v[82:85]
	v_mfma_f32_16x16x32_bf16 v[70:73], v[150:153], v[210:213], v[70:73]
	v_mfma_f32_16x16x32_bf16 v[66:69], v[170:173], v[210:213], v[66:69]
	s_setprio 0
	s_barrier
	s_add_i32 m0, s30, 0x10000
	s_add_u32 s100, s70, s12
	s_addc_u32 s101, s71, s13
	ds_read_b128 v[174:177], v189 offset:16384
	ds_read_b128 v[178:181], v189 offset:17408
	ds_read_b128 v[190:193], v189 offset:18432
	global_load_lds_dwordx4 v0, s[70:71]
	s_add_i32 m0, s30, 0x12000
	ds_read_b128 v[194:197], v189 offset:19456
	global_load_lds_dwordx4 v154, s[70:71]
	s_add_i32 m0, s30, 0x14000
	ds_read_b128 v[198:201], v189 offset:20480
	global_load_lds_dwordx4 v0, s[100:101]
	s_add_i32 m0, s30, 0x16000
	ds_read_b128 v[202:205], v189 offset:21504
	global_load_lds_dwordx4 v154, s[100:101]
	s_mov_b32 m0, s56
	ds_read_b128 v[206:209], v189 offset:22528
	global_load_lds_dwordx4 v158, s[20:21]
	s_mov_b32 m0, s57
	ds_read_b128 v[210:213], v189 offset:23552
	global_load_lds_dwordx4 v156, s[20:21]
	s_waitcnt vmcnt(8) lgkmcnt(0)
	s_barrier
	s_setprio 1
	v_mfma_f32_16x16x32_bf16 v[62:65], v[130:133], v[174:177], 0
	v_mfma_f32_16x16x32_bf16 v[58:61], v[138:141], v[174:177], 0
	v_mfma_f32_16x16x32_bf16 v[46:49], v[130:133], v[190:193], 0
	v_mfma_f32_16x16x32_bf16 v[42:45], v[138:141], v[190:193], 0
	v_mfma_f32_16x16x32_bf16 v[30:33], v[130:133], v[198:201], 0
	v_mfma_f32_16x16x32_bf16 v[26:29], v[138:141], v[198:201], 0
	v_mfma_f32_16x16x32_bf16 v[14:17], v[130:133], v[206:209], 0
	v_mfma_f32_16x16x32_bf16 v[10:13], v[138:141], v[206:209], 0
	v_mfma_f32_16x16x32_bf16 v[62:65], v[134:137], v[178:181], v[62:65]
	v_mfma_f32_16x16x32_bf16 v[58:61], v[142:145], v[178:181], v[58:61]
	v_mfma_f32_16x16x32_bf16 v[46:49], v[134:137], v[194:197], v[46:49]
	v_mfma_f32_16x16x32_bf16 v[42:45], v[142:145], v[194:197], v[42:45]
	v_mfma_f32_16x16x32_bf16 v[30:33], v[134:137], v[202:205], v[30:33]
	v_mfma_f32_16x16x32_bf16 v[26:29], v[142:145], v[202:205], v[26:29]
	v_mfma_f32_16x16x32_bf16 v[14:17], v[134:137], v[210:213], v[14:17]
	v_mfma_f32_16x16x32_bf16 v[10:13], v[142:145], v[210:213], v[10:13]
	v_mfma_f32_16x16x32_bf16 v[54:57], v[146:149], v[174:177], 0
	v_mfma_f32_16x16x32_bf16 v[50:53], v[166:169], v[174:177], 0
	v_mfma_f32_16x16x32_bf16 v[38:41], v[146:149], v[190:193], 0
	v_mfma_f32_16x16x32_bf16 v[34:37], v[166:169], v[190:193], 0
	v_mfma_f32_16x16x32_bf16 v[22:25], v[146:149], v[198:201], 0
	v_mfma_f32_16x16x32_bf16 v[18:21], v[166:169], v[198:201], 0
	v_mfma_f32_16x16x32_bf16 v[6:9], v[146:149], v[206:209], 0
	v_mfma_f32_16x16x32_bf16 v[2:5], v[166:169], v[206:209], 0
	v_mfma_f32_16x16x32_bf16 v[54:57], v[150:153], v[178:181], v[54:57]
	v_mfma_f32_16x16x32_bf16 v[50:53], v[170:173], v[178:181], v[50:53]
	v_mfma_f32_16x16x32_bf16 v[38:41], v[150:153], v[194:197], v[38:41]
	v_mfma_f32_16x16x32_bf16 v[34:37], v[170:173], v[194:197], v[34:37]
	v_mfma_f32_16x16x32_bf16 v[22:25], v[150:153], v[202:205], v[22:25]
	v_mfma_f32_16x16x32_bf16 v[18:21], v[170:173], v[202:205], v[18:21]
	v_mfma_f32_16x16x32_bf16 v[6:9], v[150:153], v[210:213], v[6:9]
	v_mfma_f32_16x16x32_bf16 v[2:5], v[170:173], v[210:213], v[2:5]
	s_setprio 0
	s_barrier
; #define PG8_STAGE(bufoff, gbase, voff) do { _Pragma("unroll") for (int _i = 0; _i < 2; ++_i) \
;         __builtin_amdgcn_global_load_lds((const unsigned*)((const char*)(gbase) + (voff)[_i]), (PG8_LAS unsigned*)(lds + (bufoff) + ldsw + _i * 8192), 16, 0, 0); } while (0)
; #define PG8_LDA(dst, b, h) do { _Pragma("unroll") for (int m = 0; m < 4; ++m) _Pragma("unroll") for (int k = 0; k < 2; ++k) dst[m][k] = *(const PG8_LAS bf16x8*)(lds + PG8_SA(b, h) + aoff + m * 2048 + k * 1024); } while (0)
; #define PG8_LDB(dst, b, h) do { _Pragma("unroll") for (int n = 0; n < 2; ++n) _Pragma("unroll") for (int k = 0; k < 2; ++k) dst[n][k] = *(const PG8_LAS bf16x8*)(lds + PG8_SB(b, h) + boff + n * 2048 + k * 1024); } while (0)
; #define PG8_MMA(ai, bj, At, Bt) do { __builtin_amdgcn_s_setprio(1); _Pragma("unroll") for (int m = 0; m < 4; ++m) _Pragma("unroll") for (int n = 0; n < 2; ++n) _Pragma("unroll") for (int k = 0; k < 2; ++k) \
;         acc[ai][bj][m][n] = __builtin_amdgcn_mfma_f32_16x16x32_bf16(Bt[n][k], At[m][k], acc[ai][bj][m][n], 0, 0, 0); __builtin_amdgcn_s_setprio(0); } while (0)
; #define PG8_WAIT_V(n) asm volatile("s_waitcnt vmcnt(" #n ")" ::: "memory")
; #define PG8_WAIT_L(n) asm volatile("s_waitcnt lgkmcnt(" #n ")" ::: "memory")
; #define PG8_BAR __builtin_amdgcn_s_barrier()
; #define PG8_SCHED __builtin_amdgcn_sched_barrier(0)
; template <class Epi, class Sched, bool ALIGN_EPI = false, bool SP2 = false>
; __device__ __forceinline__ void gemm_phase(PG8_LAS unsigned char* lds, const Gemm g, const Sched& S, const Epi& E) {
;     ...
;             PG8_LDB(B0, 1, 0); PG8_LDB(B1, 1, 1); PG8_SCHED; PG8_LDA(At, 1, 0); PG8_STAGE(PG8_SA(0, 1), a2 + hstep, voffA);
;             PG8_WAIT_V(8); PG8_WAIT_L(0); PG8_BAR; PG8_MMA(0, 0, At, B0); PG8_MMA(0, 1, At, B1); PG8_BAR; PG8_SCHED;
;             PG8_LDA(At, 1, 1); PG8_STAGE(PG8_SB(1, 0), b3, voffB); PG8_STAGE(PG8_SB(1, 1), b3 + hstep, voffB); PG8_STAGE(PG8_SA(1, 0), a3, voffA);
;             PG8_WAIT_V(8); PG8_WAIT_L(0); PG8_BAR; PG8_MMA(1, 0, At, B0); PG8_MMA(1, 1, At, B1); PG8_BAR; PG8_SCHED;
	ds_read_b128 v[130:133], v185 offset:32768
	ds_read_b128 v[134:137], v185 offset:33792
	ds_read_b128 v[138:141], v185 offset:34816
	ds_read_b128 v[142:145], v185 offset:35840
	ds_read_b128 v[146:149], v185 offset:49152
	ds_read_b128 v[150:153], v185 offset:50176
	ds_read_b128 v[166:169], v185 offset:51200
	ds_read_b128 v[170:173], v185 offset:52224
	s_mov_b32 m0, s58
	ds_read_b128 v[174:177], v189 offset:32768
	ds_read_b128 v[178:181], v189 offset:33792
	ds_read_b128 v[190:193], v189 offset:34816
	ds_read_b128 v[194:197], v189 offset:35840
	ds_read_b128 v[198:201], v189 offset:36864
	ds_read_b128 v[202:205], v189 offset:37888
	ds_read_b128 v[206:209], v189 offset:38912
	global_load_lds_dwordx4 v162, s[20:21]
	s_mov_b32 m0, s59
	ds_read_b128 v[210:213], v189 offset:39936
	global_load_lds_dwordx4 v164, s[20:21]
	s_waitcnt vmcnt(8) lgkmcnt(0)
	s_barrier
	s_setprio 1
	v_mfma_f32_16x16x32_bf16 v[126:129], v[130:133], v[174:177], v[126:129]
	v_mfma_f32_16x16x32_bf16 v[122:125], v[138:141], v[174:177], v[122:125]
	v_mfma_f32_16x16x32_bf16 v[110:113], v[130:133], v[190:193], v[110:113]
	v_mfma_f32_16x16x32_bf16 v[106:109], v[138:141], v[190:193], v[106:109]
	v_mfma_f32_16x16x32_bf16 v[94:97], v[130:133], v[198:201], v[94:97]
	v_mfma_f32_16x16x32_bf16 v[90:93], v[138:141], v[198:201], v[90:93]
	v_mfma_f32_16x16x32_bf16 v[78:81], v[130:133], v[206:209], v[78:81]
	v_mfma_f32_16x16x32_bf16 v[74:77], v[138:141], v[206:209], v[74:77]
	v_mfma_f32_16x16x32_bf16 v[126:129], v[134:137], v[178:181], v[126:129]
	v_mfma_f32_16x16x32_bf16 v[122:125], v[142:145], v[178:181], v[122:125]
	v_mfma_f32_16x16x32_bf16 v[110:113], v[134:137], v[194:197], v[110:113]
	v_mfma_f32_16x16x32_bf16 v[106:109], v[142:145], v[194:197], v[106:109]
	v_mfma_f32_16x16x32_bf16 v[94:97], v[134:137], v[202:205], v[94:97]
	v_mfma_f32_16x16x32_bf16 v[90:93], v[142:145], v[202:205], v[90:93]
	v_mfma_f32_16x16x32_bf16 v[78:81], v[134:137], v[210:213], v[78:81]
	v_mfma_f32_16x16x32_bf16 v[74:77], v[142:145], v[210:213], v[74:77]
	v_mfma_f32_16x16x32_bf16 v[118:121], v[146:149], v[174:177], v[118:121]
	v_mfma_f32_16x16x32_bf16 v[114:117], v[166:169], v[174:177], v[114:117]
	v_mfma_f32_16x16x32_bf16 v[102:105], v[146:149], v[190:193], v[102:105]
	v_mfma_f32_16x16x32_bf16 v[98:101], v[166:169], v[190:193], v[98:101]
	v_mfma_f32_16x16x32_bf16 v[86:89], v[146:149], v[198:201], v[86:89]
	v_mfma_f32_16x16x32_bf16 v[82:85], v[166:169], v[198:201], v[82:85]
	v_mfma_f32_16x16x32_bf16 v[70:73], v[146:149], v[206:209], v[70:73]
	v_mfma_f32_16x16x32_bf16 v[66:69], v[166:169], v[206:209], v[66:69]
	v_mfma_f32_16x16x32_bf16 v[118:121], v[150:153], v[178:181], v[118:121]
	v_mfma_f32_16x16x32_bf16 v[114:117], v[170:173], v[178:181], v[114:117]
	v_mfma_f32_16x16x32_bf16 v[102:105], v[150:153], v[194:197], v[102:105]
	v_mfma_f32_16x16x32_bf16 v[98:101], v[170:173], v[194:197], v[98:101]
	v_mfma_f32_16x16x32_bf16 v[86:89], v[150:153], v[202:205], v[86:89]
	v_mfma_f32_16x16x32_bf16 v[82:85], v[170:173], v[202:205], v[82:85]
	v_mfma_f32_16x16x32_bf16 v[70:73], v[150:153], v[210:213], v[70:73]
	v_mfma_f32_16x16x32_bf16 v[66:69], v[170:173], v[210:213], v[66:69]
	s_setprio 0
	s_barrier
	s_add_i32 m0, s30, 0x17f80
	ds_read_b128 v[174:177], v189 offset:49152
	ds_read_b128 v[178:181], v189 offset:50176
	ds_read_b128 v[190:193], v189 offset:51200
	global_load_lds_dwordx4 v0, s[70:71] offset:128
	s_add_i32 m0, s30, 0x19f80
	ds_read_b128 v[194:197], v189 offset:52224
	global_load_lds_dwordx4 v154, s[70:71] offset:128
	s_add_i32 m0, s30, 0x1bf80
	ds_read_b128 v[198:201], v189 offset:53248
	global_load_lds_dwordx4 v0, s[100:101] offset:128
	s_add_i32 m0, s30, 0x1df80
	ds_read_b128 v[202:205], v189 offset:54272
	global_load_lds_dwordx4 v154, s[100:101] offset:128
	s_sub_i32 m0, s60, 0x80
	ds_read_b128 v[206:209], v189 offset:55296
	global_load_lds_dwordx4 v158, s[20:21] offset:128
	s_sub_i32 m0, s61, 0x80
	ds_read_b128 v[210:213], v189 offset:56320
	global_load_lds_dwordx4 v156, s[20:21] offset:128
	s_waitcnt vmcnt(8) lgkmcnt(0)
	s_barrier
	s_setprio 1
	v_mfma_f32_16x16x32_bf16 v[62:65], v[130:133], v[174:177], v[62:65]
	v_mfma_f32_16x16x32_bf16 v[58:61], v[138:141], v[174:177], v[58:61]
	v_mfma_f32_16x16x32_bf16 v[46:49], v[130:133], v[190:193], v[46:49]
	v_mfma_f32_16x16x32_bf16 v[42:45], v[138:141], v[190:193], v[42:45]
	s_add_u32 s8, s8, 0x100
	v_mfma_f32_16x16x32_bf16 v[30:33], v[130:133], v[198:201], v[30:33]
	s_addc_u32 s9, s9, 0
	v_mfma_f32_16x16x32_bf16 v[26:29], v[138:141], v[198:201], v[26:29]
	s_add_u32 s52, s52, 0x100
	v_mfma_f32_16x16x32_bf16 v[14:17], v[130:133], v[206:209], v[14:17]
	s_addc_u32 s53, s53, 0
	v_mfma_f32_16x16x32_bf16 v[10:13], v[138:141], v[206:209], v[10:13]
	s_mov_b32 s20, s69
	v_mfma_f32_16x16x32_bf16 v[62:65], v[134:137], v[178:181], v[62:65]
	v_mfma_f32_16x16x32_bf16 v[58:61], v[142:145], v[178:181], v[58:61]
	v_mfma_f32_16x16x32_bf16 v[46:49], v[134:137], v[194:197], v[46:49]
	v_mfma_f32_16x16x32_bf16 v[42:45], v[142:145], v[194:197], v[42:45]
	v_mfma_f32_16x16x32_bf16 v[30:33], v[134:137], v[202:205], v[30:33]
	v_mfma_f32_16x16x32_bf16 v[26:29], v[142:145], v[202:205], v[26:29]
	v_mfma_f32_16x16x32_bf16 v[14:17], v[134:137], v[210:213], v[14:17]
	v_mfma_f32_16x16x32_bf16 v[10:13], v[142:145], v[210:213], v[10:13]
	v_mfma_f32_16x16x32_bf16 v[54:57], v[146:149], v[174:177], v[54:57]
	v_mfma_f32_16x16x32_bf16 v[50:53], v[166:169], v[174:177], v[50:53]
	v_mfma_f32_16x16x32_bf16 v[38:41], v[146:149], v[190:193], v[38:41]
	v_mfma_f32_16x16x32_bf16 v[34:37], v[166:169], v[190:193], v[34:37]
	v_mfma_f32_16x16x32_bf16 v[22:25], v[146:149], v[198:201], v[22:25]
	v_mfma_f32_16x16x32_bf16 v[18:21], v[166:169], v[198:201], v[18:21]
	v_mfma_f32_16x16x32_bf16 v[6:9], v[146:149], v[206:209], v[6:9]
	v_mfma_f32_16x16x32_bf16 v[2:5], v[166:169], v[206:209], v[2:5]
	v_mfma_f32_16x16x32_bf16 v[54:57], v[150:153], v[178:181], v[54:57]
	v_mfma_f32_16x16x32_bf16 v[50:53], v[170:173], v[178:181], v[50:53]
	v_mfma_f32_16x16x32_bf16 v[38:41], v[150:153], v[194:197], v[38:41]
	v_mfma_f32_16x16x32_bf16 v[34:37], v[170:173], v[194:197], v[34:37]
	v_mfma_f32_16x16x32_bf16 v[22:25], v[150:153], v[202:205], v[22:25]
	v_mfma_f32_16x16x32_bf16 v[18:21], v[170:173], v[202:205], v[18:21]
	v_mfma_f32_16x16x32_bf16 v[6:9], v[150:153], v[210:213], v[6:9]
	v_mfma_f32_16x16x32_bf16 v[2:5], v[170:173], v[210:213], v[2:5]
	s_setprio 0
	s_barrier
	s_cmp_ge_i32 s69, s62
	s_cbranch_scc1 .Lpz_exit_520
; #define PG8_STAGE(bufoff, gbase, voff) do { _Pragma("unroll") for (int _i = 0; _i < 2; ++_i) \
;         __builtin_amdgcn_global_load_lds((const unsigned*)((const char*)(gbase) + (voff)[_i]), (PG8_LAS unsigned*)(lds + (bufoff) + ldsw + _i * 8192), 16, 0, 0); } while (0)
; #define PG8_LDA(dst, b, h) do { _Pragma("unroll") for (int m = 0; m < 4; ++m) _Pragma("unroll") for (int k = 0; k < 2; ++k) dst[m][k] = *(const PG8_LAS bf16x8*)(lds + PG8_SA(b, h) + aoff + m * 2048 + k * 1024); } while (0)
; #define PG8_LDB(dst, b, h) do { _Pragma("unroll") for (int n = 0; n < 2; ++n) _Pragma("unroll") for (int k = 0; k < 2; ++k) dst[n][k] = *(const PG8_LAS bf16x8*)(lds + PG8_SB(b, h) + boff + n * 2048 + k * 1024); } while (0)
; #define PG8_MMA(ai, bj, At, Bt) do { __builtin_amdgcn_s_setprio(1); _Pragma("unroll") for (int m = 0; m < 4; ++m) _Pragma("unroll") for (int n = 0; n < 2; ++n) _Pragma("unroll") for (int k = 0; k < 2; ++k) \
;         acc[ai][bj][m][n] = __builtin_amdgcn_mfma_f32_16x16x32_bf16(Bt[n][k], At[m][k], acc[ai][bj][m][n], 0, 0, 0); __builtin_amdgcn_s_setprio(0); } while (0)
; #define PG8_WAIT_V(n) asm volatile("s_waitcnt vmcnt(" #n ")" ::: "memory")
; #define PG8_BAR __builtin_amdgcn_s_barrier()
; template <class Epi, class Sched, bool ALIGN_EPI = false, bool SP2 = false>
; __device__ __forceinline__ void gemm_phase(PG8_LAS unsigned char* lds, const Gemm g, const Sched& S, const Epi& E) {
;     ...
;         for (int t = 0; t < nt; t += 2) {
;             const bool last = (t == nt - 2);
;             const char* a1 = cA + (size_t)(t + 1) * kstep;
;             const char* a2 = last ? nA : cA + (size_t)(t + 2) * kstep; const char* b2 = last ? nB : cB + (size_t)(t + 2) * kstep;
;             const char* a3 = a2 + kstep; const char* b3 = b2 + kstep;
;             if (last && has_next) S.a_ready(nxt);
;             if constexpr (SP2) {
;             PG8_LDB(B0, 0, 0); PG8_LDB(B1, 0, 1); PG8_SCHED; PG8_LDA(At, 0, 0); PG8_STAGE(PG8_SA(1, 1), a1 + hstep, voffA);
;             PG8_WAIT_V(8); PG8_WAIT_L(0); PG8_BAR; PG8_MMA(0, 0, At, B0); PG8_MMA(0, 1, At, B1); PG8_BAR; PG8_SCHED;
;             PG8_LDA(At, 0, 1); PG8_STAGE(PG8_SB(0, 0), b2, voffB); PG8_STAGE(PG8_SB(0, 1), b2 + hstep, voffB); PG8_STAGE(PG8_SA(0, 0), a2, voffA);
;             PG8_WAIT_V(8); PG8_WAIT_L(0); PG8_BAR; PG8_MMA(1, 0, At, B0); PG8_MMA(1, 1, At, B1); PG8_BAR; PG8_SCHED;
.LBB0_520:
	ds_read_b128 v[130:133], v185
	ds_read_b128 v[134:137], v185 offset:1024
	ds_read_b128 v[138:141], v185 offset:2048
	ds_read_b128 v[142:145], v185 offset:3072
	ds_read_b128 v[146:149], v185 offset:16384
	ds_read_b128 v[150:153], v185 offset:17408
	ds_read_b128 v[166:169], v185 offset:18432
	ds_read_b128 v[170:173], v185 offset:19456
	s_add_i32 m0, s56, 0xc000
	ds_read_b128 v[174:177], v189
	ds_read_b128 v[178:181], v189 offset:1024
	ds_read_b128 v[190:193], v189 offset:2048
	ds_read_b128 v[194:197], v189 offset:3072
	ds_read_b128 v[198:201], v189 offset:4096
	ds_read_b128 v[202:205], v189 offset:5120
	ds_read_b128 v[206:209], v189 offset:6144
	global_load_lds_dwordx4 v162, s[8:9]
	s_add_i32 m0, s56, 0xe000
	ds_read_b128 v[210:213], v189 offset:7168
	global_load_lds_dwordx4 v164, s[8:9]
	s_waitcnt vmcnt(8) lgkmcnt(0)
	s_barrier
	s_setprio 1
	v_mfma_f32_16x16x32_bf16 v[126:129], v[130:133], v[174:177], v[126:129]
	v_mfma_f32_16x16x32_bf16 v[122:125], v[138:141], v[174:177], v[122:125]
	v_mfma_f32_16x16x32_bf16 v[110:113], v[130:133], v[190:193], v[110:113]
	v_mfma_f32_16x16x32_bf16 v[106:109], v[138:141], v[190:193], v[106:109]
	s_add_i32 s69, s20, 2
	v_mfma_f32_16x16x32_bf16 v[94:97], v[130:133], v[198:201], v[94:97]
	s_add_u32 s70, s8, 0x80
	v_mfma_f32_16x16x32_bf16 v[90:93], v[138:141], v[198:201], v[90:93]
	s_addc_u32 s21, s9, 0
	v_mfma_f32_16x16x32_bf16 v[78:81], v[130:133], v[206:209], v[78:81]
	s_cmp_eq_u32 s63, s20
	v_mfma_f32_16x16x32_bf16 v[74:77], v[138:141], v[206:209], v[74:77]
	s_cselect_b32 s21, s49, s21
	v_mfma_f32_16x16x32_bf16 v[126:129], v[134:137], v[178:181], v[126:129]
	s_cselect_b32 s20, s48, s70
	v_mfma_f32_16x16x32_bf16 v[122:125], v[142:145], v[178:181], v[122:125]
	s_cselect_b32 s71, s51, s53
	v_mfma_f32_16x16x32_bf16 v[110:113], v[134:137], v[194:197], v[110:113]
	s_cselect_b32 s70, s50, s52
	v_mfma_f32_16x16x32_bf16 v[106:109], v[142:145], v[194:197], v[106:109]
	v_mfma_f32_16x16x32_bf16 v[94:97], v[134:137], v[202:205], v[94:97]
	v_mfma_f32_16x16x32_bf16 v[90:93], v[142:145], v[202:205], v[90:93]
	v_mfma_f32_16x16x32_bf16 v[78:81], v[134:137], v[210:213], v[78:81]
	v_mfma_f32_16x16x32_bf16 v[74:77], v[142:145], v[210:213], v[74:77]
	v_mfma_f32_16x16x32_bf16 v[118:121], v[146:149], v[174:177], v[118:121]
	v_mfma_f32_16x16x32_bf16 v[114:117], v[166:169], v[174:177], v[114:117]
	v_mfma_f32_16x16x32_bf16 v[102:105], v[146:149], v[190:193], v[102:105]
	v_mfma_f32_16x16x32_bf16 v[98:101], v[166:169], v[190:193], v[98:101]
	v_mfma_f32_16x16x32_bf16 v[86:89], v[146:149], v[198:201], v[86:89]
	v_mfma_f32_16x16x32_bf16 v[82:85], v[166:169], v[198:201], v[82:85]
	v_mfma_f32_16x16x32_bf16 v[70:73], v[146:149], v[206:209], v[70:73]
	v_mfma_f32_16x16x32_bf16 v[66:69], v[166:169], v[206:209], v[66:69]
	v_mfma_f32_16x16x32_bf16 v[118:121], v[150:153], v[178:181], v[118:121]
	v_mfma_f32_16x16x32_bf16 v[114:117], v[170:173], v[178:181], v[114:117]
	v_mfma_f32_16x16x32_bf16 v[102:105], v[150:153], v[194:197], v[102:105]
	v_mfma_f32_16x16x32_bf16 v[98:101], v[170:173], v[194:197], v[98:101]
	v_mfma_f32_16x16x32_bf16 v[86:89], v[150:153], v[202:205], v[86:89]
	v_mfma_f32_16x16x32_bf16 v[82:85], v[170:173], v[202:205], v[82:85]
	v_mfma_f32_16x16x32_bf16 v[70:73], v[150:153], v[210:213], v[70:73]
	v_mfma_f32_16x16x32_bf16 v[66:69], v[170:173], v[210:213], v[66:69]
	s_setprio 0
	s_barrier
	s_add_i32 m0, s30, 0x10000
	s_add_u32 s100, s70, s12
	s_addc_u32 s101, s71, s13
	ds_read_b128 v[174:177], v189 offset:16384
	ds_read_b128 v[178:181], v189 offset:17408
	ds_read_b128 v[190:193], v189 offset:18432
	global_load_lds_dwordx4 v0, s[70:71]
	s_add_i32 m0, s30, 0x12000
	ds_read_b128 v[194:197], v189 offset:19456
	global_load_lds_dwordx4 v154, s[70:71]
	s_add_i32 m0, s30, 0x14000
	ds_read_b128 v[198:201], v189 offset:20480
	global_load_lds_dwordx4 v0, s[100:101]
	s_add_i32 m0, s30, 0x16000
	ds_read_b128 v[202:205], v189 offset:21504
	global_load_lds_dwordx4 v154, s[100:101]
	s_mov_b32 m0, s56
	ds_read_b128 v[206:209], v189 offset:22528
	global_load_lds_dwordx4 v158, s[20:21]
	s_mov_b32 m0, s57
	ds_read_b128 v[210:213], v189 offset:23552
	global_load_lds_dwordx4 v156, s[20:21]
	s_waitcnt vmcnt(8) lgkmcnt(0)
	s_barrier
	s_setprio 1
	v_mfma_f32_16x16x32_bf16 v[62:65], v[130:133], v[174:177], v[62:65]
	v_mfma_f32_16x16x32_bf16 v[58:61], v[138:141], v[174:177], v[58:61]
	v_mfma_f32_16x16x32_bf16 v[46:49], v[130:133], v[190:193], v[46:49]
	v_mfma_f32_16x16x32_bf16 v[42:45], v[138:141], v[190:193], v[42:45]
	v_mfma_f32_16x16x32_bf16 v[30:33], v[130:133], v[198:201], v[30:33]
	v_mfma_f32_16x16x32_bf16 v[26:29], v[138:141], v[198:201], v[26:29]
	v_mfma_f32_16x16x32_bf16 v[14:17], v[130:133], v[206:209], v[14:17]
	v_mfma_f32_16x16x32_bf16 v[10:13], v[138:141], v[206:209], v[10:13]
	v_mfma_f32_16x16x32_bf16 v[62:65], v[134:137], v[178:181], v[62:65]
	v_mfma_f32_16x16x32_bf16 v[58:61], v[142:145], v[178:181], v[58:61]
	v_mfma_f32_16x16x32_bf16 v[46:49], v[134:137], v[194:197], v[46:49]
	v_mfma_f32_16x16x32_bf16 v[42:45], v[142:145], v[194:197], v[42:45]
	v_mfma_f32_16x16x32_bf16 v[30:33], v[134:137], v[202:205], v[30:33]
	v_mfma_f32_16x16x32_bf16 v[26:29], v[142:145], v[202:205], v[26:29]
	v_mfma_f32_16x16x32_bf16 v[14:17], v[134:137], v[210:213], v[14:17]
	v_mfma_f32_16x16x32_bf16 v[10:13], v[142:145], v[210:213], v[10:13]
	v_mfma_f32_16x16x32_bf16 v[54:57], v[146:149], v[174:177], v[54:57]
	v_mfma_f32_16x16x32_bf16 v[50:53], v[166:169], v[174:177], v[50:53]
	v_mfma_f32_16x16x32_bf16 v[38:41], v[146:149], v[190:193], v[38:41]
	v_mfma_f32_16x16x32_bf16 v[34:37], v[166:169], v[190:193], v[34:37]
	v_mfma_f32_16x16x32_bf16 v[22:25], v[146:149], v[198:201], v[22:25]
	v_mfma_f32_16x16x32_bf16 v[18:21], v[166:169], v[198:201], v[18:21]
	v_mfma_f32_16x16x32_bf16 v[6:9], v[146:149], v[206:209], v[6:9]
	v_mfma_f32_16x16x32_bf16 v[2:5], v[166:169], v[206:209], v[2:5]
	v_mfma_f32_16x16x32_bf16 v[54:57], v[150:153], v[178:181], v[54:57]
	v_mfma_f32_16x16x32_bf16 v[50:53], v[170:173], v[178:181], v[50:53]
	v_mfma_f32_16x16x32_bf16 v[38:41], v[150:153], v[194:197], v[38:41]
	v_mfma_f32_16x16x32_bf16 v[34:37], v[170:173], v[194:197], v[34:37]
	v_mfma_f32_16x16x32_bf16 v[22:25], v[150:153], v[202:205], v[22:25]
	v_mfma_f32_16x16x32_bf16 v[18:21], v[170:173], v[202:205], v[18:21]
	v_mfma_f32_16x16x32_bf16 v[6:9], v[150:153], v[210:213], v[6:9]
	v_mfma_f32_16x16x32_bf16 v[2:5], v[170:173], v[210:213], v[2:5]
	s_setprio 0
	s_barrier
; #define PG8_STAGE(bufoff, gbase, voff) do { _Pragma("unroll") for (int _i = 0; _i < 2; ++_i) \
;         __builtin_amdgcn_global_load_lds((const unsigned*)((const char*)(gbase) + (voff)[_i]), (PG8_LAS unsigned*)(lds + (bufoff) + ldsw + _i * 8192), 16, 0, 0); } while (0)
; #define PG8_LDA(dst, b, h) do { _Pragma("unroll") for (int m = 0; m < 4; ++m) _Pragma("unroll") for (int k = 0; k < 2; ++k) dst[m][k] = *(const PG8_LAS bf16x8*)(lds + PG8_SA(b, h) + aoff + m * 2048 + k * 1024); } while (0)
; #define PG8_LDB(dst, b, h) do { _Pragma("unroll") for (int n = 0; n < 2; ++n) _Pragma("unroll") for (int k = 0; k < 2; ++k) dst[n][k] = *(const PG8_LAS bf16x8*)(lds + PG8_SB(b, h) + boff + n * 2048 + k * 1024); } while (0)
; #define PG8_MMA(ai, bj, At, Bt) do { __builtin_amdgcn_s_setprio(1); _Pragma("unroll") for (int m = 0; m < 4; ++m) _Pragma("unroll") for (int n = 0; n < 2; ++n) _Pragma("unroll") for (int k = 0; k < 2; ++k) \
;         acc[ai][bj][m][n] = __builtin_amdgcn_mfma_f32_16x16x32_bf16(Bt[n][k], At[m][k], acc[ai][bj][m][n], 0, 0, 0); __builtin_amdgcn_s_setprio(0); } while (0)
; #define PG8_WAIT_V(n) asm volatile("s_waitcnt vmcnt(" #n ")" ::: "memory")
; #define PG8_WAIT_L(n) asm volatile("s_waitcnt lgkmcnt(" #n ")" ::: "memory")
; #define PG8_BAR __builtin_amdgcn_s_barrier()
; #define PG8_SCHED __builtin_amdgcn_sched_barrier(0)
; template <class Epi, class Sched, bool ALIGN_EPI = false, bool SP2 = false>
; __device__ __forceinline__ void gemm_phase(PG8_LAS unsigned char* lds, const Gemm g, const Sched& S, const Epi& E) {
;     ...
;             PG8_LDB(B0, 1, 0); PG8_LDB(B1, 1, 1); PG8_SCHED; PG8_LDA(At, 1, 0); PG8_STAGE(PG8_SA(0, 1), a2 + hstep, voffA);
;             PG8_WAIT_V(8); PG8_WAIT_L(0); PG8_BAR; PG8_MMA(0, 0, At, B0); PG8_MMA(0, 1, At, B1); PG8_BAR; PG8_SCHED;
;             PG8_LDA(At, 1, 1); PG8_STAGE(PG8_SB(1, 0), b3, voffB); PG8_STAGE(PG8_SB(1, 1), b3 + hstep, voffB); PG8_STAGE(PG8_SA(1, 0), a3, voffA);
;             PG8_WAIT_V(8); PG8_WAIT_L(0); PG8_BAR; PG8_MMA(1, 0, At, B0); PG8_MMA(1, 1, At, B1); PG8_BAR; PG8_SCHED;
	ds_read_b128 v[130:133], v185 offset:32768
	ds_read_b128 v[134:137], v185 offset:33792
	ds_read_b128 v[138:141], v185 offset:34816
	ds_read_b128 v[142:145], v185 offset:35840
	ds_read_b128 v[146:149], v185 offset:49152
	ds_read_b128 v[150:153], v185 offset:50176
	ds_read_b128 v[166:169], v185 offset:51200
	ds_read_b128 v[170:173], v185 offset:52224
	s_mov_b32 m0, s58
	ds_read_b128 v[174:177], v189 offset:32768
	ds_read_b128 v[178:181], v189 offset:33792
	ds_read_b128 v[190:193], v189 offset:34816
	ds_read_b128 v[194:197], v189 offset:35840
	ds_read_b128 v[198:201], v189 offset:36864
	ds_read_b128 v[202:205], v189 offset:37888
	ds_read_b128 v[206:209], v189 offset:38912
	global_load_lds_dwordx4 v162, s[20:21]
	s_mov_b32 m0, s59
	ds_read_b128 v[210:213], v189 offset:39936
	global_load_lds_dwordx4 v164, s[20:21]
	s_waitcnt vmcnt(8) lgkmcnt(0)
	s_barrier
	s_setprio 1
	v_mfma_f32_16x16x32_bf16 v[126:129], v[130:133], v[174:177], v[126:129]
	v_mfma_f32_16x16x32_bf16 v[122:125], v[138:141], v[174:177], v[122:125]
	v_mfma_f32_16x16x32_bf16 v[110:113], v[130:133], v[190:193], v[110:113]
	v_mfma_f32_16x16x32_bf16 v[106:109], v[138:141], v[190:193], v[106:109]
	v_mfma_f32_16x16x32_bf16 v[94:97], v[130:133], v[198:201], v[94:97]
	v_mfma_f32_16x16x32_bf16 v[90:93], v[138:141], v[198:201], v[90:93]
	v_mfma_f32_16x16x32_bf16 v[78:81], v[130:133], v[206:209], v[78:81]
	v_mfma_f32_16x16x32_bf16 v[74:77], v[138:141], v[206:209], v[74:77]
	v_mfma_f32_16x16x32_bf16 v[126:129], v[134:137], v[178:181], v[126:129]
	v_mfma_f32_16x16x32_bf16 v[122:125], v[142:145], v[178:181], v[122:125]
	v_mfma_f32_16x16x32_bf16 v[110:113], v[134:137], v[194:197], v[110:113]
	v_mfma_f32_16x16x32_bf16 v[106:109], v[142:145], v[194:197], v[106:109]
	v_mfma_f32_16x16x32_bf16 v[94:97], v[134:137], v[202:205], v[94:97]
	v_mfma_f32_16x16x32_bf16 v[90:93], v[142:145], v[202:205], v[90:93]
	v_mfma_f32_16x16x32_bf16 v[78:81], v[134:137], v[210:213], v[78:81]
	v_mfma_f32_16x16x32_bf16 v[74:77], v[142:145], v[210:213], v[74:77]
	v_mfma_f32_16x16x32_bf16 v[118:121], v[146:149], v[174:177], v[118:121]
	v_mfma_f32_16x16x32_bf16 v[114:117], v[166:169], v[174:177], v[114:117]
	v_mfma_f32_16x16x32_bf16 v[102:105], v[146:149], v[190:193], v[102:105]
	v_mfma_f32_16x16x32_bf16 v[98:101], v[166:169], v[190:193], v[98:101]
	v_mfma_f32_16x16x32_bf16 v[86:89], v[146:149], v[198:201], v[86:89]
	v_mfma_f32_16x16x32_bf16 v[82:85], v[166:169], v[198:201], v[82:85]
	v_mfma_f32_16x16x32_bf16 v[70:73], v[146:149], v[206:209], v[70:73]
	v_mfma_f32_16x16x32_bf16 v[66:69], v[166:169], v[206:209], v[66:69]
	v_mfma_f32_16x16x32_bf16 v[118:121], v[150:153], v[178:181], v[118:121]
	v_mfma_f32_16x16x32_bf16 v[114:117], v[170:173], v[178:181], v[114:117]
	v_mfma_f32_16x16x32_bf16 v[102:105], v[150:153], v[194:197], v[102:105]
	v_mfma_f32_16x16x32_bf16 v[98:101], v[170:173], v[194:197], v[98:101]
	v_mfma_f32_16x16x32_bf16 v[86:89], v[150:153], v[202:205], v[86:89]
	v_mfma_f32_16x16x32_bf16 v[82:85], v[170:173], v[202:205], v[82:85]
	v_mfma_f32_16x16x32_bf16 v[70:73], v[150:153], v[210:213], v[70:73]
	v_mfma_f32_16x16x32_bf16 v[66:69], v[170:173], v[210:213], v[66:69]
	s_setprio 0
	s_barrier
	s_add_i32 m0, s30, 0x17f80
	ds_read_b128 v[174:177], v189 offset:49152
	ds_read_b128 v[178:181], v189 offset:50176
	ds_read_b128 v[190:193], v189 offset:51200
	global_load_lds_dwordx4 v0, s[70:71] offset:128
	s_add_i32 m0, s30, 0x19f80
	ds_read_b128 v[194:197], v189 offset:52224
	global_load_lds_dwordx4 v154, s[70:71] offset:128
	s_add_i32 m0, s30, 0x1bf80
	ds_read_b128 v[198:201], v189 offset:53248
	global_load_lds_dwordx4 v0, s[100:101] offset:128
	s_add_i32 m0, s30, 0x1df80
	ds_read_b128 v[202:205], v189 offset:54272
	global_load_lds_dwordx4 v154, s[100:101] offset:128
	s_sub_i32 m0, s60, 0x80
	ds_read_b128 v[206:209], v189 offset:55296
	global_load_lds_dwordx4 v158, s[20:21] offset:128
	s_sub_i32 m0, s61, 0x80
	ds_read_b128 v[210:213], v189 offset:56320
	global_load_lds_dwordx4 v156, s[20:21] offset:128
	s_waitcnt vmcnt(8) lgkmcnt(0)
	s_barrier
	s_setprio 1
	v_mfma_f32_16x16x32_bf16 v[62:65], v[130:133], v[174:177], v[62:65]
	v_mfma_f32_16x16x32_bf16 v[58:61], v[138:141], v[174:177], v[58:61]
	v_mfma_f32_16x16x32_bf16 v[46:49], v[130:133], v[190:193], v[46:49]
	v_mfma_f32_16x16x32_bf16 v[42:45], v[138:141], v[190:193], v[42:45]
	s_add_u32 s8, s8, 0x100
	v_mfma_f32_16x16x32_bf16 v[30:33], v[130:133], v[198:201], v[30:33]
	s_addc_u32 s9, s9, 0
	v_mfma_f32_16x16x32_bf16 v[26:29], v[138:141], v[198:201], v[26:29]
	s_add_u32 s52, s52, 0x100
	v_mfma_f32_16x16x32_bf16 v[14:17], v[130:133], v[206:209], v[14:17]
	s_addc_u32 s53, s53, 0
	v_mfma_f32_16x16x32_bf16 v[10:13], v[138:141], v[206:209], v[10:13]
	s_mov_b32 s20, s69
	v_mfma_f32_16x16x32_bf16 v[62:65], v[134:137], v[178:181], v[62:65]
	v_mfma_f32_16x16x32_bf16 v[58:61], v[142:145], v[178:181], v[58:61]
	v_mfma_f32_16x16x32_bf16 v[46:49], v[134:137], v[194:197], v[46:49]
	v_mfma_f32_16x16x32_bf16 v[42:45], v[142:145], v[194:197], v[42:45]
	v_mfma_f32_16x16x32_bf16 v[30:33], v[134:137], v[202:205], v[30:33]
	v_mfma_f32_16x16x32_bf16 v[26:29], v[142:145], v[202:205], v[26:29]
	v_mfma_f32_16x16x32_bf16 v[14:17], v[134:137], v[210:213], v[14:17]
	v_mfma_f32_16x16x32_bf16 v[10:13], v[142:145], v[210:213], v[10:13]
	v_mfma_f32_16x16x32_bf16 v[54:57], v[146:149], v[174:177], v[54:57]
	v_mfma_f32_16x16x32_bf16 v[50:53], v[166:169], v[174:177], v[50:53]
	v_mfma_f32_16x16x32_bf16 v[38:41], v[146:149], v[190:193], v[38:41]
	v_mfma_f32_16x16x32_bf16 v[34:37], v[166:169], v[190:193], v[34:37]
	v_mfma_f32_16x16x32_bf16 v[22:25], v[146:149], v[198:201], v[22:25]
	v_mfma_f32_16x16x32_bf16 v[18:21], v[166:169], v[198:201], v[18:21]
	v_mfma_f32_16x16x32_bf16 v[6:9], v[146:149], v[206:209], v[6:9]
	v_mfma_f32_16x16x32_bf16 v[2:5], v[166:169], v[206:209], v[2:5]
	v_mfma_f32_16x16x32_bf16 v[54:57], v[150:153], v[178:181], v[54:57]
	v_mfma_f32_16x16x32_bf16 v[50:53], v[170:173], v[178:181], v[50:53]
	v_mfma_f32_16x16x32_bf16 v[38:41], v[150:153], v[194:197], v[38:41]
	v_mfma_f32_16x16x32_bf16 v[34:37], v[170:173], v[194:197], v[34:37]
	v_mfma_f32_16x16x32_bf16 v[22:25], v[150:153], v[202:205], v[22:25]
	v_mfma_f32_16x16x32_bf16 v[18:21], v[170:173], v[202:205], v[18:21]
	v_mfma_f32_16x16x32_bf16 v[6:9], v[150:153], v[210:213], v[6:9]
	v_mfma_f32_16x16x32_bf16 v[2:5], v[170:173], v[210:213], v[2:5]
	s_setprio 0
	s_barrier
	s_cmp_ge_i32 s69, s62
	s_cbranch_scc0 .LBB0_520

; #define PG8_STAGE(bufoff, gbase, voff) do { _Pragma("unroll") for (int _i = 0; _i < 2; ++_i) \
;         __builtin_amdgcn_global_load_lds((const unsigned*)((const char*)(gbase) + (voff)[_i]), (PG8_LAS unsigned*)(lds + (bufoff) + ldsw + _i * 8192), 16, 0, 0); } while (0)
; #define PG8_LDA(dst, b, h) do { _Pragma("unroll") for (int m = 0; m < 4; ++m) _Pragma("unroll") for (int k = 0; k < 2; ++k) dst[m][k] = *(const PG8_LAS bf16x8*)(lds + PG8_SA(b, h) + aoff + m * 2048 + k * 1024); } while (0)
; #define PG8_LDB(dst, b, h) do { _Pragma("unroll") for (int n = 0; n < 2; ++n) _Pragma("unroll") for (int k = 0; k < 2; ++k) dst[n][k] = *(const PG8_LAS bf16x8*)(lds + PG8_SB(b, h) + boff + n * 2048 + k * 1024); } while (0)
; #define PG8_MMA(ai, bj, At, Bt) do { __builtin_amdgcn_s_setprio(1); _Pragma("unroll") for (int m = 0; m < 4; ++m) _Pragma("unroll") for (int n = 0; n < 2; ++n) _Pragma("unroll") for (int k = 0; k < 2; ++k) \
;         acc[ai][bj][m][n] = __builtin_amdgcn_mfma_f32_16x16x32_bf16(Bt[n][k], At[m][k], acc[ai][bj][m][n], 0, 0, 0); __builtin_amdgcn_s_setprio(0); } while (0)
; #define PG8_WAIT_V(n) asm volatile("s_waitcnt vmcnt(" #n ")" ::: "memory")
; #define PG8_BAR __builtin_amdgcn_s_barrier()
; template <class Epi, class Sched, bool ALIGN_EPI = false, bool SP2 = false>
; __device__ __forceinline__ void gemm_phase(PG8_LAS unsigned char* lds, const Gemm g, const Sched& S, const Epi& E) {
;     ...
;         for (int t = 0; t < nt; t += 2) {
;             const bool last = (t == nt - 2);
;             const char* a1 = cA + (size_t)(t + 1) * kstep;
;             const char* a2 = last ? nA : cA + (size_t)(t + 2) * kstep; const char* b2 = last ? nB : cB + (size_t)(t + 2) * kstep;
;             const char* a3 = a2 + kstep; const char* b3 = b2 + kstep;
;             if (last && has_next) S.a_ready(nxt);
;             if constexpr (SP2) {
;             PG8_LDB(B0, 0, 0); PG8_LDB(B1, 0, 1); PG8_SCHED; PG8_LDA(At, 0, 0); PG8_STAGE(PG8_SA(1, 1), a1 + hstep, voffA);
;             PG8_WAIT_V(8); PG8_WAIT_L(0); PG8_BAR; PG8_MMA(0, 0, At, B0); PG8_MMA(0, 1, At, B1); PG8_BAR; PG8_SCHED;
;             PG8_LDA(At, 0, 1); PG8_STAGE(PG8_SB(0, 0), b2, voffB); PG8_STAGE(PG8_SB(0, 1), b2 + hstep, voffB); PG8_STAGE(PG8_SA(0, 0), a2, voffA);
;             PG8_WAIT_V(8); PG8_WAIT_L(0); PG8_BAR; PG8_MMA(1, 0, At, B0); PG8_MMA(1, 1, At, B1); PG8_BAR; PG8_SCHED;
.Lz_enter_568:
	s_add_u32 s10, s62, 0x80
	s_addc_u32 s11, s63, 0
	s_add_u32 s62, s20, 0x100
	s_addc_u32 s63, s21, 0
	s_mov_b32 s20, 0
	ds_read_b128 v[82:85], v246
	ds_read_b128 v[98:101], v246 offset:1024
	ds_read_b128 v[102:105], v246 offset:2048
	ds_read_b128 v[106:109], v246 offset:3072
	ds_read_b128 v[146:149], v246 offset:16384
	ds_read_b128 v[150:153], v246 offset:17408
	ds_read_b128 v[154:157], v246 offset:18432
	ds_read_b128 v[158:161], v246 offset:19456
	s_add_i32 m0, s64, 0xc000
	ds_read_b128 v[162:165], v249
	ds_read_b128 v[166:169], v249 offset:1024
	ds_read_b128 v[170:173], v249 offset:2048
	ds_read_b128 v[174:177], v249 offset:3072
	ds_read_b128 v[178:181], v249 offset:4096
	ds_read_b128 v[182:185], v249 offset:5120
	ds_read_b128 v[186:189], v249 offset:6144
	global_load_lds_dwordx4 v224, s[10:11]
	s_add_i32 m0, s64, 0xe000
	ds_read_b128 v[190:193], v249 offset:7168
	global_load_lds_dwordx4 v226, s[10:11]
	s_waitcnt vmcnt(8) lgkmcnt(0)
	s_barrier
	s_setprio 1
	v_mfma_f32_16x16x32_bf16 v[142:145], v[82:85], v[162:165], 0
	v_mfma_f32_16x16x32_bf16 v[138:141], v[102:105], v[162:165], 0
	v_mfma_f32_16x16x32_bf16 v[126:129], v[82:85], v[170:173], 0
	v_mfma_f32_16x16x32_bf16 v[122:125], v[102:105], v[170:173], 0
	s_add_i32 s78, s20, 2
	v_mfma_f32_16x16x32_bf16 v[110:113], v[82:85], v[178:181], 0
	s_add_u32 s79, s10, 0x80
	v_mfma_f32_16x16x32_bf16 v[94:97], v[102:105], v[178:181], 0
	s_addc_u32 s21, s11, 0
	v_mfma_f32_16x16x32_bf16 v[78:81], v[82:85], v[186:189], 0
	s_cmp_eq_u32 s68, s20
	v_mfma_f32_16x16x32_bf16 v[74:77], v[102:105], v[186:189], 0
	s_cselect_b32 s21, s59, s21
	v_mfma_f32_16x16x32_bf16 v[142:145], v[98:101], v[166:169], v[142:145]
	s_cselect_b32 s20, s58, s79
	v_mfma_f32_16x16x32_bf16 v[138:141], v[106:109], v[166:169], v[138:141]
	s_cselect_b32 s81, s61, s63
	v_mfma_f32_16x16x32_bf16 v[126:129], v[98:101], v[174:177], v[126:129]
	s_cselect_b32 s80, s60, s62
	v_mfma_f32_16x16x32_bf16 v[122:125], v[106:109], v[174:177], v[122:125]
	v_mfma_f32_16x16x32_bf16 v[110:113], v[98:101], v[182:185], v[110:113]
	v_mfma_f32_16x16x32_bf16 v[94:97], v[106:109], v[182:185], v[94:97]
	v_mfma_f32_16x16x32_bf16 v[78:81], v[98:101], v[190:193], v[78:81]
	v_mfma_f32_16x16x32_bf16 v[74:77], v[106:109], v[190:193], v[74:77]
	v_mfma_f32_16x16x32_bf16 v[134:137], v[146:149], v[162:165], 0
	v_mfma_f32_16x16x32_bf16 v[130:133], v[154:157], v[162:165], 0
	v_mfma_f32_16x16x32_bf16 v[118:121], v[146:149], v[170:173], 0
	v_mfma_f32_16x16x32_bf16 v[114:117], v[154:157], v[170:173], 0
	v_mfma_f32_16x16x32_bf16 v[90:93], v[146:149], v[178:181], 0
	v_mfma_f32_16x16x32_bf16 v[86:89], v[154:157], v[178:181], 0
	v_mfma_f32_16x16x32_bf16 v[70:73], v[146:149], v[186:189], 0
	v_mfma_f32_16x16x32_bf16 v[66:69], v[154:157], v[186:189], 0
	v_mfma_f32_16x16x32_bf16 v[134:137], v[150:153], v[166:169], v[134:137]
	v_mfma_f32_16x16x32_bf16 v[130:133], v[158:161], v[166:169], v[130:133]
	v_mfma_f32_16x16x32_bf16 v[118:121], v[150:153], v[174:177], v[118:121]
	v_mfma_f32_16x16x32_bf16 v[114:117], v[158:161], v[174:177], v[114:117]
	v_mfma_f32_16x16x32_bf16 v[90:93], v[150:153], v[182:185], v[90:93]
	v_mfma_f32_16x16x32_bf16 v[86:89], v[158:161], v[182:185], v[86:89]
	v_mfma_f32_16x16x32_bf16 v[70:73], v[150:153], v[190:193], v[70:73]
	v_mfma_f32_16x16x32_bf16 v[66:69], v[158:161], v[190:193], v[66:69]
	s_setprio 0
	s_barrier
	s_add_i32 m0, s22, 0x10000
	s_add_u32 s100, s80, s46
	s_addc_u32 s101, s81, s47
	ds_read_b128 v[162:165], v249 offset:16384
	ds_read_b128 v[166:169], v249 offset:17408
	ds_read_b128 v[170:173], v249 offset:18432
	global_load_lds_dwordx4 v0, s[80:81]
	s_add_i32 m0, s22, 0x12000
	ds_read_b128 v[174:177], v249 offset:19456
	global_load_lds_dwordx4 v218, s[80:81]
	s_add_i32 m0, s22, 0x14000
	ds_read_b128 v[178:181], v249 offset:20480
	global_load_lds_dwordx4 v0, s[100:101]
	s_add_i32 m0, s22, 0x16000
	ds_read_b128 v[182:185], v249 offset:21504
	global_load_lds_dwordx4 v218, s[100:101]
	s_mov_b32 m0, s64
	ds_read_b128 v[186:189], v249 offset:22528
	global_load_lds_dwordx4 v0, s[20:21]
	s_mov_b32 m0, s30
	ds_read_b128 v[190:193], v249 offset:23552
	global_load_lds_dwordx4 v218, s[20:21]
	s_waitcnt vmcnt(8) lgkmcnt(0)
	s_barrier
	s_setprio 1
	v_mfma_f32_16x16x32_bf16 v[62:65], v[82:85], v[162:165], 0
	v_mfma_f32_16x16x32_bf16 v[58:61], v[102:105], v[162:165], 0
	v_mfma_f32_16x16x32_bf16 v[46:49], v[82:85], v[170:173], 0
	v_mfma_f32_16x16x32_bf16 v[42:45], v[102:105], v[170:173], 0
	v_mfma_f32_16x16x32_bf16 v[30:33], v[82:85], v[178:181], 0
	v_mfma_f32_16x16x32_bf16 v[26:29], v[102:105], v[178:181], 0
	v_mfma_f32_16x16x32_bf16 v[14:17], v[82:85], v[186:189], 0
	v_mfma_f32_16x16x32_bf16 v[10:13], v[102:105], v[186:189], 0
	v_mfma_f32_16x16x32_bf16 v[62:65], v[98:101], v[166:169], v[62:65]
	v_mfma_f32_16x16x32_bf16 v[58:61], v[106:109], v[166:169], v[58:61]
	v_mfma_f32_16x16x32_bf16 v[46:49], v[98:101], v[174:177], v[46:49]
	v_mfma_f32_16x16x32_bf16 v[42:45], v[106:109], v[174:177], v[42:45]
	v_mfma_f32_16x16x32_bf16 v[30:33], v[98:101], v[182:185], v[30:33]
	v_mfma_f32_16x16x32_bf16 v[26:29], v[106:109], v[182:185], v[26:29]
	v_mfma_f32_16x16x32_bf16 v[14:17], v[98:101], v[190:193], v[14:17]
	v_mfma_f32_16x16x32_bf16 v[10:13], v[106:109], v[190:193], v[10:13]
	v_mfma_f32_16x16x32_bf16 v[54:57], v[146:149], v[162:165], 0
	v_mfma_f32_16x16x32_bf16 v[50:53], v[154:157], v[162:165], 0
	v_mfma_f32_16x16x32_bf16 v[38:41], v[146:149], v[170:173], 0
	v_mfma_f32_16x16x32_bf16 v[34:37], v[154:157], v[170:173], 0
	v_mfma_f32_16x16x32_bf16 v[22:25], v[146:149], v[178:181], 0
	v_mfma_f32_16x16x32_bf16 v[18:21], v[154:157], v[178:181], 0
	v_mfma_f32_16x16x32_bf16 v[6:9], v[146:149], v[186:189], 0
	v_mfma_f32_16x16x32_bf16 v[2:5], v[154:157], v[186:189], 0
	v_mfma_f32_16x16x32_bf16 v[54:57], v[150:153], v[166:169], v[54:57]
	v_mfma_f32_16x16x32_bf16 v[50:53], v[158:161], v[166:169], v[50:53]
	v_mfma_f32_16x16x32_bf16 v[38:41], v[150:153], v[174:177], v[38:41]
	v_mfma_f32_16x16x32_bf16 v[34:37], v[158:161], v[174:177], v[34:37]
	v_mfma_f32_16x16x32_bf16 v[22:25], v[150:153], v[182:185], v[22:25]
	v_mfma_f32_16x16x32_bf16 v[18:21], v[158:161], v[182:185], v[18:21]
	v_mfma_f32_16x16x32_bf16 v[6:9], v[150:153], v[190:193], v[6:9]
	v_mfma_f32_16x16x32_bf16 v[2:5], v[158:161], v[190:193], v[2:5]
	s_setprio 0
	s_barrier
; #define PG8_STAGE(bufoff, gbase, voff) do { _Pragma("unroll") for (int _i = 0; _i < 2; ++_i) \
;         __builtin_amdgcn_global_load_lds((const unsigned*)((const char*)(gbase) + (voff)[_i]), (PG8_LAS unsigned*)(lds + (bufoff) + ldsw + _i * 8192), 16, 0, 0); } while (0)
; #define PG8_LDA(dst, b, h) do { _Pragma("unroll") for (int m = 0; m < 4; ++m) _Pragma("unroll") for (int k = 0; k < 2; ++k) dst[m][k] = *(const PG8_LAS bf16x8*)(lds + PG8_SA(b, h) + aoff + m * 2048 + k * 1024); } while (0)
; #define PG8_LDB(dst, b, h) do { _Pragma("unroll") for (int n = 0; n < 2; ++n) _Pragma("unroll") for (int k = 0; k < 2; ++k) dst[n][k] = *(const PG8_LAS bf16x8*)(lds + PG8_SB(b, h) + boff + n * 2048 + k * 1024); } while (0)
; #define PG8_MMA(ai, bj, At, Bt) do { __builtin_amdgcn_s_setprio(1); _Pragma("unroll") for (int m = 0; m < 4; ++m) _Pragma("unroll") for (int n = 0; n < 2; ++n) _Pragma("unroll") for (int k = 0; k < 2; ++k) \
;         acc[ai][bj][m][n] = __builtin_amdgcn_mfma_f32_16x16x32_bf16(Bt[n][k], At[m][k], acc[ai][bj][m][n], 0, 0, 0); __builtin_amdgcn_s_setprio(0); } while (0)
; #define PG8_WAIT_V(n) asm volatile("s_waitcnt vmcnt(" #n ")" ::: "memory")
; #define PG8_WAIT_L(n) asm volatile("s_waitcnt lgkmcnt(" #n ")" ::: "memory")
; #define PG8_BAR __builtin_amdgcn_s_barrier()
; #define PG8_SCHED __builtin_amdgcn_sched_barrier(0)
; template <class Epi, class Sched, bool ALIGN_EPI = false, bool SP2 = false>
; __device__ __forceinline__ void gemm_phase(PG8_LAS unsigned char* lds, const Gemm g, const Sched& S, const Epi& E) {
;     ...
;             PG8_LDB(B0, 1, 0); PG8_LDB(B1, 1, 1); PG8_SCHED; PG8_LDA(At, 1, 0); PG8_STAGE(PG8_SA(0, 1), a2 + hstep, voffA);
;             PG8_WAIT_V(8); PG8_WAIT_L(0); PG8_BAR; PG8_MMA(0, 0, At, B0); PG8_MMA(0, 1, At, B1); PG8_BAR; PG8_SCHED;
;             PG8_LDA(At, 1, 1); PG8_STAGE(PG8_SB(1, 0), b3, voffB); PG8_STAGE(PG8_SB(1, 1), b3 + hstep, voffB); PG8_STAGE(PG8_SA(1, 0), a3, voffA);
;             PG8_WAIT_V(8); PG8_WAIT_L(0); PG8_BAR; PG8_MMA(1, 0, At, B0); PG8_MMA(1, 1, At, B1); PG8_BAR; PG8_SCHED;
	ds_read_b128 v[82:85], v246 offset:32768
	ds_read_b128 v[98:101], v246 offset:33792
	ds_read_b128 v[102:105], v246 offset:34816
	ds_read_b128 v[106:109], v246 offset:35840
	ds_read_b128 v[146:149], v246 offset:49152
	ds_read_b128 v[150:153], v246 offset:50176
	ds_read_b128 v[154:157], v246 offset:51200
	ds_read_b128 v[158:161], v246 offset:52224
	s_mov_b32 m0, s31
	ds_read_b128 v[162:165], v249 offset:32768
	ds_read_b128 v[166:169], v249 offset:33792
	ds_read_b128 v[170:173], v249 offset:34816
	ds_read_b128 v[174:177], v249 offset:35840
	ds_read_b128 v[178:181], v249 offset:36864
	ds_read_b128 v[182:185], v249 offset:37888
	ds_read_b128 v[186:189], v249 offset:38912
	global_load_lds_dwordx4 v224, s[20:21]
	s_mov_b32 m0, s33
	ds_read_b128 v[190:193], v249 offset:39936
	global_load_lds_dwordx4 v226, s[20:21]
	s_waitcnt vmcnt(8) lgkmcnt(0)
	s_barrier
	s_setprio 1
	v_mfma_f32_16x16x32_bf16 v[142:145], v[82:85], v[162:165], v[142:145]
	v_mfma_f32_16x16x32_bf16 v[138:141], v[102:105], v[162:165], v[138:141]
	v_mfma_f32_16x16x32_bf16 v[126:129], v[82:85], v[170:173], v[126:129]
	v_mfma_f32_16x16x32_bf16 v[122:125], v[102:105], v[170:173], v[122:125]
	v_mfma_f32_16x16x32_bf16 v[110:113], v[82:85], v[178:181], v[110:113]
	v_mfma_f32_16x16x32_bf16 v[94:97], v[102:105], v[178:181], v[94:97]
	v_mfma_f32_16x16x32_bf16 v[78:81], v[82:85], v[186:189], v[78:81]
	v_mfma_f32_16x16x32_bf16 v[74:77], v[102:105], v[186:189], v[74:77]
	v_mfma_f32_16x16x32_bf16 v[142:145], v[98:101], v[166:169], v[142:145]
	v_mfma_f32_16x16x32_bf16 v[138:141], v[106:109], v[166:169], v[138:141]
	v_mfma_f32_16x16x32_bf16 v[126:129], v[98:101], v[174:177], v[126:129]
	v_mfma_f32_16x16x32_bf16 v[122:125], v[106:109], v[174:177], v[122:125]
	v_mfma_f32_16x16x32_bf16 v[110:113], v[98:101], v[182:185], v[110:113]
	v_mfma_f32_16x16x32_bf16 v[94:97], v[106:109], v[182:185], v[94:97]
	v_mfma_f32_16x16x32_bf16 v[78:81], v[98:101], v[190:193], v[78:81]
	v_mfma_f32_16x16x32_bf16 v[74:77], v[106:109], v[190:193], v[74:77]
	v_mfma_f32_16x16x32_bf16 v[134:137], v[146:149], v[162:165], v[134:137]
	v_mfma_f32_16x16x32_bf16 v[130:133], v[154:157], v[162:165], v[130:133]
	v_mfma_f32_16x16x32_bf16 v[118:121], v[146:149], v[170:173], v[118:121]
	v_mfma_f32_16x16x32_bf16 v[114:117], v[154:157], v[170:173], v[114:117]
	v_mfma_f32_16x16x32_bf16 v[90:93], v[146:149], v[178:181], v[90:93]
	v_mfma_f32_16x16x32_bf16 v[86:89], v[154:157], v[178:181], v[86:89]
	v_mfma_f32_16x16x32_bf16 v[70:73], v[146:149], v[186:189], v[70:73]
	v_mfma_f32_16x16x32_bf16 v[66:69], v[154:157], v[186:189], v[66:69]
	v_mfma_f32_16x16x32_bf16 v[134:137], v[150:153], v[166:169], v[134:137]
	v_mfma_f32_16x16x32_bf16 v[130:133], v[158:161], v[166:169], v[130:133]
	v_mfma_f32_16x16x32_bf16 v[118:121], v[150:153], v[174:177], v[118:121]
	v_mfma_f32_16x16x32_bf16 v[114:117], v[158:161], v[174:177], v[114:117]
	v_mfma_f32_16x16x32_bf16 v[90:93], v[150:153], v[182:185], v[90:93]
	v_mfma_f32_16x16x32_bf16 v[86:89], v[158:161], v[182:185], v[86:89]
	v_mfma_f32_16x16x32_bf16 v[70:73], v[150:153], v[190:193], v[70:73]
	v_mfma_f32_16x16x32_bf16 v[66:69], v[158:161], v[190:193], v[66:69]
	s_setprio 0
	s_barrier
	s_add_i32 m0, s22, 0x17f80
	ds_read_b128 v[162:165], v249 offset:49152
	ds_read_b128 v[166:169], v249 offset:50176
	ds_read_b128 v[170:173], v249 offset:51200
	global_load_lds_dwordx4 v0, s[80:81] offset:128
	s_add_i32 m0, s22, 0x19f80
	ds_read_b128 v[174:177], v249 offset:52224
	global_load_lds_dwordx4 v218, s[80:81] offset:128
	s_add_i32 m0, s22, 0x1bf80
	ds_read_b128 v[178:181], v249 offset:53248
	global_load_lds_dwordx4 v0, s[100:101] offset:128
	s_add_i32 m0, s22, 0x1df80
	ds_read_b128 v[182:185], v249 offset:54272
	global_load_lds_dwordx4 v218, s[100:101] offset:128
	s_sub_i32 m0, s39, 0x80
	ds_read_b128 v[186:189], v249 offset:55296
	global_load_lds_dwordx4 v0, s[20:21] offset:128
	s_sub_i32 m0, s65, 0x80
	ds_read_b128 v[190:193], v249 offset:56320
	global_load_lds_dwordx4 v218, s[20:21] offset:128
	s_waitcnt vmcnt(8) lgkmcnt(0)
	s_barrier
	s_setprio 1
	v_mfma_f32_16x16x32_bf16 v[62:65], v[82:85], v[162:165], v[62:65]
	v_mfma_f32_16x16x32_bf16 v[58:61], v[102:105], v[162:165], v[58:61]
	v_mfma_f32_16x16x32_bf16 v[46:49], v[82:85], v[170:173], v[46:49]
	v_mfma_f32_16x16x32_bf16 v[42:45], v[102:105], v[170:173], v[42:45]
	s_add_u32 s10, s10, 0x100
	v_mfma_f32_16x16x32_bf16 v[30:33], v[82:85], v[178:181], v[30:33]
	s_addc_u32 s11, s11, 0
	v_mfma_f32_16x16x32_bf16 v[26:29], v[102:105], v[178:181], v[26:29]
	s_add_u32 s62, s62, 0x100
	v_mfma_f32_16x16x32_bf16 v[14:17], v[82:85], v[186:189], v[14:17]
	s_addc_u32 s63, s63, 0
	v_mfma_f32_16x16x32_bf16 v[10:13], v[102:105], v[186:189], v[10:13]
	s_mov_b32 s20, s78
	v_mfma_f32_16x16x32_bf16 v[62:65], v[98:101], v[166:169], v[62:65]
	v_mfma_f32_16x16x32_bf16 v[58:61], v[106:109], v[166:169], v[58:61]
	v_mfma_f32_16x16x32_bf16 v[46:49], v[98:101], v[174:177], v[46:49]
	v_mfma_f32_16x16x32_bf16 v[42:45], v[106:109], v[174:177], v[42:45]
	v_mfma_f32_16x16x32_bf16 v[30:33], v[98:101], v[182:185], v[30:33]
	v_mfma_f32_16x16x32_bf16 v[26:29], v[106:109], v[182:185], v[26:29]
	v_mfma_f32_16x16x32_bf16 v[14:17], v[98:101], v[190:193], v[14:17]
	v_mfma_f32_16x16x32_bf16 v[10:13], v[106:109], v[190:193], v[10:13]
	v_mfma_f32_16x16x32_bf16 v[54:57], v[146:149], v[162:165], v[54:57]
	v_mfma_f32_16x16x32_bf16 v[50:53], v[154:157], v[162:165], v[50:53]
	v_mfma_f32_16x16x32_bf16 v[38:41], v[146:149], v[170:173], v[38:41]
	v_mfma_f32_16x16x32_bf16 v[34:37], v[154:157], v[170:173], v[34:37]
	v_mfma_f32_16x16x32_bf16 v[22:25], v[146:149], v[178:181], v[22:25]
	v_mfma_f32_16x16x32_bf16 v[18:21], v[154:157], v[178:181], v[18:21]
	v_mfma_f32_16x16x32_bf16 v[6:9], v[146:149], v[186:189], v[6:9]
	v_mfma_f32_16x16x32_bf16 v[2:5], v[154:157], v[186:189], v[2:5]
	v_mfma_f32_16x16x32_bf16 v[54:57], v[150:153], v[166:169], v[54:57]
	v_mfma_f32_16x16x32_bf16 v[50:53], v[158:161], v[166:169], v[50:53]
	v_mfma_f32_16x16x32_bf16 v[38:41], v[150:153], v[174:177], v[38:41]
	v_mfma_f32_16x16x32_bf16 v[34:37], v[158:161], v[174:177], v[34:37]
	v_mfma_f32_16x16x32_bf16 v[22:25], v[150:153], v[182:185], v[22:25]
	v_mfma_f32_16x16x32_bf16 v[18:21], v[158:161], v[182:185], v[18:21]
	v_mfma_f32_16x16x32_bf16 v[6:9], v[150:153], v[190:193], v[6:9]
	v_mfma_f32_16x16x32_bf16 v[2:5], v[158:161], v[190:193], v[2:5]
	s_setprio 0
	s_barrier
	s_cmp_ge_i32 s78, s67
	s_cbranch_scc1 .Lpz_exit_570
; #define PG8_STAGE(bufoff, gbase, voff) do { _Pragma("unroll") for (int _i = 0; _i < 2; ++_i) \
;         __builtin_amdgcn_global_load_lds((const unsigned*)((const char*)(gbase) + (voff)[_i]), (PG8_LAS unsigned*)(lds + (bufoff) + ldsw + _i * 8192), 16, 0, 0); } while (0)
; #define PG8_LDA(dst, b, h) do { _Pragma("unroll") for (int m = 0; m < 4; ++m) _Pragma("unroll") for (int k = 0; k < 2; ++k) dst[m][k] = *(const PG8_LAS bf16x8*)(lds + PG8_SA(b, h) + aoff + m * 2048 + k * 1024); } while (0)
; #define PG8_LDB(dst, b, h) do { _Pragma("unroll") for (int n = 0; n < 2; ++n) _Pragma("unroll") for (int k = 0; k < 2; ++k) dst[n][k] = *(const PG8_LAS bf16x8*)(lds + PG8_SB(b, h) + boff + n * 2048 + k * 1024); } while (0)
; #define PG8_MMA(ai, bj, At, Bt) do { __builtin_amdgcn_s_setprio(1); _Pragma("unroll") for (int m = 0; m < 4; ++m) _Pragma("unroll") for (int n = 0; n < 2; ++n) _Pragma("unroll") for (int k = 0; k < 2; ++k) \
;         acc[ai][bj][m][n] = __builtin_amdgcn_mfma_f32_16x16x32_bf16(Bt[n][k], At[m][k], acc[ai][bj][m][n], 0, 0, 0); __builtin_amdgcn_s_setprio(0); } while (0)
; #define PG8_WAIT_V(n) asm volatile("s_waitcnt vmcnt(" #n ")" ::: "memory")
; #define PG8_BAR __builtin_amdgcn_s_barrier()
; template <class Epi, class Sched, bool ALIGN_EPI = false, bool SP2 = false>
; __device__ __forceinline__ void gemm_phase(PG8_LAS unsigned char* lds, const Gemm g, const Sched& S, const Epi& E) {
;     ...
;         for (int t = 0; t < nt; t += 2) {
;             const bool last = (t == nt - 2);
;             const char* a1 = cA + (size_t)(t + 1) * kstep;
;             const char* a2 = last ? nA : cA + (size_t)(t + 2) * kstep; const char* b2 = last ? nB : cB + (size_t)(t + 2) * kstep;
;             const char* a3 = a2 + kstep; const char* b3 = b2 + kstep;
;             if (last && has_next) S.a_ready(nxt);
;             if constexpr (SP2) {
;             PG8_LDB(B0, 0, 0); PG8_LDB(B1, 0, 1); PG8_SCHED; PG8_LDA(At, 0, 0); PG8_STAGE(PG8_SA(1, 1), a1 + hstep, voffA);
;             PG8_WAIT_V(8); PG8_WAIT_L(0); PG8_BAR; PG8_MMA(0, 0, At, B0); PG8_MMA(0, 1, At, B1); PG8_BAR; PG8_SCHED;
;             PG8_LDA(At, 0, 1); PG8_STAGE(PG8_SB(0, 0), b2, voffB); PG8_STAGE(PG8_SB(0, 1), b2 + hstep, voffB); PG8_STAGE(PG8_SA(0, 0), a2, voffA);
;             PG8_WAIT_V(8); PG8_WAIT_L(0); PG8_BAR; PG8_MMA(1, 0, At, B0); PG8_MMA(1, 1, At, B1); PG8_BAR; PG8_SCHED;
.LBB0_570:
	ds_read_b128 v[82:85], v246
	ds_read_b128 v[98:101], v246 offset:1024
	ds_read_b128 v[102:105], v246 offset:2048
	ds_read_b128 v[106:109], v246 offset:3072
	ds_read_b128 v[146:149], v246 offset:16384
	ds_read_b128 v[150:153], v246 offset:17408
	ds_read_b128 v[154:157], v246 offset:18432
	ds_read_b128 v[158:161], v246 offset:19456
	s_add_i32 m0, s64, 0xc000
	ds_read_b128 v[162:165], v249
	ds_read_b128 v[166:169], v249 offset:1024
	ds_read_b128 v[170:173], v249 offset:2048
	ds_read_b128 v[174:177], v249 offset:3072
	ds_read_b128 v[178:181], v249 offset:4096
	ds_read_b128 v[182:185], v249 offset:5120
	ds_read_b128 v[186:189], v249 offset:6144
	global_load_lds_dwordx4 v224, s[10:11]
	s_add_i32 m0, s64, 0xe000
	ds_read_b128 v[190:193], v249 offset:7168
	global_load_lds_dwordx4 v226, s[10:11]
	s_waitcnt vmcnt(8) lgkmcnt(0)
	s_barrier
	s_setprio 1
	v_mfma_f32_16x16x32_bf16 v[142:145], v[82:85], v[162:165], v[142:145]
	v_mfma_f32_16x16x32_bf16 v[138:141], v[102:105], v[162:165], v[138:141]
	v_mfma_f32_16x16x32_bf16 v[126:129], v[82:85], v[170:173], v[126:129]
	v_mfma_f32_16x16x32_bf16 v[122:125], v[102:105], v[170:173], v[122:125]
	s_add_i32 s78, s20, 2
	v_mfma_f32_16x16x32_bf16 v[110:113], v[82:85], v[178:181], v[110:113]
	s_add_u32 s79, s10, 0x80
	v_mfma_f32_16x16x32_bf16 v[94:97], v[102:105], v[178:181], v[94:97]
	s_addc_u32 s21, s11, 0
	v_mfma_f32_16x16x32_bf16 v[78:81], v[82:85], v[186:189], v[78:81]
	s_cmp_eq_u32 s68, s20
	v_mfma_f32_16x16x32_bf16 v[74:77], v[102:105], v[186:189], v[74:77]
	s_cselect_b32 s21, s59, s21
	v_mfma_f32_16x16x32_bf16 v[142:145], v[98:101], v[166:169], v[142:145]
	s_cselect_b32 s20, s58, s79
	v_mfma_f32_16x16x32_bf16 v[138:141], v[106:109], v[166:169], v[138:141]
	s_cselect_b32 s81, s61, s63
	v_mfma_f32_16x16x32_bf16 v[126:129], v[98:101], v[174:177], v[126:129]
	s_cselect_b32 s80, s60, s62
	v_mfma_f32_16x16x32_bf16 v[122:125], v[106:109], v[174:177], v[122:125]
	v_mfma_f32_16x16x32_bf16 v[110:113], v[98:101], v[182:185], v[110:113]
	v_mfma_f32_16x16x32_bf16 v[94:97], v[106:109], v[182:185], v[94:97]
	v_mfma_f32_16x16x32_bf16 v[78:81], v[98:101], v[190:193], v[78:81]
	v_mfma_f32_16x16x32_bf16 v[74:77], v[106:109], v[190:193], v[74:77]
	v_mfma_f32_16x16x32_bf16 v[134:137], v[146:149], v[162:165], v[134:137]
	v_mfma_f32_16x16x32_bf16 v[130:133], v[154:157], v[162:165], v[130:133]
	v_mfma_f32_16x16x32_bf16 v[118:121], v[146:149], v[170:173], v[118:121]
	v_mfma_f32_16x16x32_bf16 v[114:117], v[154:157], v[170:173], v[114:117]
	v_mfma_f32_16x16x32_bf16 v[90:93], v[146:149], v[178:181], v[90:93]
	v_mfma_f32_16x16x32_bf16 v[86:89], v[154:157], v[178:181], v[86:89]
	v_mfma_f32_16x16x32_bf16 v[70:73], v[146:149], v[186:189], v[70:73]
	v_mfma_f32_16x16x32_bf16 v[66:69], v[154:157], v[186:189], v[66:69]
	v_mfma_f32_16x16x32_bf16 v[134:137], v[150:153], v[166:169], v[134:137]
	v_mfma_f32_16x16x32_bf16 v[130:133], v[158:161], v[166:169], v[130:133]
	v_mfma_f32_16x16x32_bf16 v[118:121], v[150:153], v[174:177], v[118:121]
	v_mfma_f32_16x16x32_bf16 v[114:117], v[158:161], v[174:177], v[114:117]
	v_mfma_f32_16x16x32_bf16 v[90:93], v[150:153], v[182:185], v[90:93]
	v_mfma_f32_16x16x32_bf16 v[86:89], v[158:161], v[182:185], v[86:89]
	v_mfma_f32_16x16x32_bf16 v[70:73], v[150:153], v[190:193], v[70:73]
	v_mfma_f32_16x16x32_bf16 v[66:69], v[158:161], v[190:193], v[66:69]
	s_setprio 0
	s_barrier
	s_add_i32 m0, s22, 0x10000
	s_add_u32 s100, s80, s46
	s_addc_u32 s101, s81, s47
	ds_read_b128 v[162:165], v249 offset:16384
	ds_read_b128 v[166:169], v249 offset:17408
	ds_read_b128 v[170:173], v249 offset:18432
	global_load_lds_dwordx4 v0, s[80:81]
	s_add_i32 m0, s22, 0x12000
	ds_read_b128 v[174:177], v249 offset:19456
	global_load_lds_dwordx4 v218, s[80:81]
	s_add_i32 m0, s22, 0x14000
	ds_read_b128 v[178:181], v249 offset:20480
	global_load_lds_dwordx4 v0, s[100:101]
	s_add_i32 m0, s22, 0x16000
	ds_read_b128 v[182:185], v249 offset:21504
	global_load_lds_dwordx4 v218, s[100:101]
	s_mov_b32 m0, s64
	ds_read_b128 v[186:189], v249 offset:22528
	global_load_lds_dwordx4 v0, s[20:21]
	s_mov_b32 m0, s30
	ds_read_b128 v[190:193], v249 offset:23552
	global_load_lds_dwordx4 v218, s[20:21]
	s_waitcnt vmcnt(8) lgkmcnt(0)
	s_barrier
	s_setprio 1
	v_mfma_f32_16x16x32_bf16 v[62:65], v[82:85], v[162:165], v[62:65]
	v_mfma_f32_16x16x32_bf16 v[58:61], v[102:105], v[162:165], v[58:61]
	v_mfma_f32_16x16x32_bf16 v[46:49], v[82:85], v[170:173], v[46:49]
	v_mfma_f32_16x16x32_bf16 v[42:45], v[102:105], v[170:173], v[42:45]
	v_mfma_f32_16x16x32_bf16 v[30:33], v[82:85], v[178:181], v[30:33]
	v_mfma_f32_16x16x32_bf16 v[26:29], v[102:105], v[178:181], v[26:29]
	v_mfma_f32_16x16x32_bf16 v[14:17], v[82:85], v[186:189], v[14:17]
	v_mfma_f32_16x16x32_bf16 v[10:13], v[102:105], v[186:189], v[10:13]
	v_mfma_f32_16x16x32_bf16 v[62:65], v[98:101], v[166:169], v[62:65]
	v_mfma_f32_16x16x32_bf16 v[58:61], v[106:109], v[166:169], v[58:61]
	v_mfma_f32_16x16x32_bf16 v[46:49], v[98:101], v[174:177], v[46:49]
	v_mfma_f32_16x16x32_bf16 v[42:45], v[106:109], v[174:177], v[42:45]
	v_mfma_f32_16x16x32_bf16 v[30:33], v[98:101], v[182:185], v[30:33]
	v_mfma_f32_16x16x32_bf16 v[26:29], v[106:109], v[182:185], v[26:29]
	v_mfma_f32_16x16x32_bf16 v[14:17], v[98:101], v[190:193], v[14:17]
	v_mfma_f32_16x16x32_bf16 v[10:13], v[106:109], v[190:193], v[10:13]
	v_mfma_f32_16x16x32_bf16 v[54:57], v[146:149], v[162:165], v[54:57]
	v_mfma_f32_16x16x32_bf16 v[50:53], v[154:157], v[162:165], v[50:53]
	v_mfma_f32_16x16x32_bf16 v[38:41], v[146:149], v[170:173], v[38:41]
	v_mfma_f32_16x16x32_bf16 v[34:37], v[154:157], v[170:173], v[34:37]
	v_mfma_f32_16x16x32_bf16 v[22:25], v[146:149], v[178:181], v[22:25]
	v_mfma_f32_16x16x32_bf16 v[18:21], v[154:157], v[178:181], v[18:21]
	v_mfma_f32_16x16x32_bf16 v[6:9], v[146:149], v[186:189], v[6:9]
	v_mfma_f32_16x16x32_bf16 v[2:5], v[154:157], v[186:189], v[2:5]
	v_mfma_f32_16x16x32_bf16 v[54:57], v[150:153], v[166:169], v[54:57]
	v_mfma_f32_16x16x32_bf16 v[50:53], v[158:161], v[166:169], v[50:53]
	v_mfma_f32_16x16x32_bf16 v[38:41], v[150:153], v[174:177], v[38:41]
	v_mfma_f32_16x16x32_bf16 v[34:37], v[158:161], v[174:177], v[34:37]
	v_mfma_f32_16x16x32_bf16 v[22:25], v[150:153], v[182:185], v[22:25]
	v_mfma_f32_16x16x32_bf16 v[18:21], v[158:161], v[182:185], v[18:21]
	v_mfma_f32_16x16x32_bf16 v[6:9], v[150:153], v[190:193], v[6:9]
	v_mfma_f32_16x16x32_bf16 v[2:5], v[158:161], v[190:193], v[2:5]
	s_setprio 0
	s_barrier
; #define PG8_STAGE(bufoff, gbase, voff) do { _Pragma("unroll") for (int _i = 0; _i < 2; ++_i) \
;         __builtin_amdgcn_global_load_lds((const unsigned*)((const char*)(gbase) + (voff)[_i]), (PG8_LAS unsigned*)(lds + (bufoff) + ldsw + _i * 8192), 16, 0, 0); } while (0)
; #define PG8_LDA(dst, b, h) do { _Pragma("unroll") for (int m = 0; m < 4; ++m) _Pragma("unroll") for (int k = 0; k < 2; ++k) dst[m][k] = *(const PG8_LAS bf16x8*)(lds + PG8_SA(b, h) + aoff + m * 2048 + k * 1024); } while (0)
; #define PG8_LDB(dst, b, h) do { _Pragma("unroll") for (int n = 0; n < 2; ++n) _Pragma("unroll") for (int k = 0; k < 2; ++k) dst[n][k] = *(const PG8_LAS bf16x8*)(lds + PG8_SB(b, h) + boff + n * 2048 + k * 1024); } while (0)
; #define PG8_MMA(ai, bj, At, Bt) do { __builtin_amdgcn_s_setprio(1); _Pragma("unroll") for (int m = 0; m < 4; ++m) _Pragma("unroll") for (int n = 0; n < 2; ++n) _Pragma("unroll") for (int k = 0; k < 2; ++k) \
;         acc[ai][bj][m][n] = __builtin_amdgcn_mfma_f32_16x16x32_bf16(Bt[n][k], At[m][k], acc[ai][bj][m][n], 0, 0, 0); __builtin_amdgcn_s_setprio(0); } while (0)
; #define PG8_WAIT_V(n) asm volatile("s_waitcnt vmcnt(" #n ")" ::: "memory")
; #define PG8_WAIT_L(n) asm volatile("s_waitcnt lgkmcnt(" #n ")" ::: "memory")
; #define PG8_BAR __builtin_amdgcn_s_barrier()
; #define PG8_SCHED __builtin_amdgcn_sched_barrier(0)
; template <class Epi, class Sched, bool ALIGN_EPI = false, bool SP2 = false>
; __device__ __forceinline__ void gemm_phase(PG8_LAS unsigned char* lds, const Gemm g, const Sched& S, const Epi& E) {
;     ...
;             PG8_LDB(B0, 1, 0); PG8_LDB(B1, 1, 1); PG8_SCHED; PG8_LDA(At, 1, 0); PG8_STAGE(PG8_SA(0, 1), a2 + hstep, voffA);
;             PG8_WAIT_V(8); PG8_WAIT_L(0); PG8_BAR; PG8_MMA(0, 0, At, B0); PG8_MMA(0, 1, At, B1); PG8_BAR; PG8_SCHED;
;             PG8_LDA(At, 1, 1); PG8_STAGE(PG8_SB(1, 0), b3, voffB); PG8_STAGE(PG8_SB(1, 1), b3 + hstep, voffB); PG8_STAGE(PG8_SA(1, 0), a3, voffA);
;             PG8_WAIT_V(8); PG8_WAIT_L(0); PG8_BAR; PG8_MMA(1, 0, At, B0); PG8_MMA(1, 1, At, B1); PG8_BAR; PG8_SCHED;
	ds_read_b128 v[82:85], v246 offset:32768
	ds_read_b128 v[98:101], v246 offset:33792
	ds_read_b128 v[102:105], v246 offset:34816
	ds_read_b128 v[106:109], v246 offset:35840
	ds_read_b128 v[146:149], v246 offset:49152
	ds_read_b128 v[150:153], v246 offset:50176
	ds_read_b128 v[154:157], v246 offset:51200
	ds_read_b128 v[158:161], v246 offset:52224
	s_mov_b32 m0, s31
	ds_read_b128 v[162:165], v249 offset:32768
	ds_read_b128 v[166:169], v249 offset:33792
	ds_read_b128 v[170:173], v249 offset:34816
	ds_read_b128 v[174:177], v249 offset:35840
	ds_read_b128 v[178:181], v249 offset:36864
	ds_read_b128 v[182:185], v249 offset:37888
	ds_read_b128 v[186:189], v249 offset:38912
	global_load_lds_dwordx4 v224, s[20:21]
	s_mov_b32 m0, s33
	ds_read_b128 v[190:193], v249 offset:39936
	global_load_lds_dwordx4 v226, s[20:21]
	s_waitcnt vmcnt(8) lgkmcnt(0)
	s_barrier
	s_setprio 1
	v_mfma_f32_16x16x32_bf16 v[142:145], v[82:85], v[162:165], v[142:145]
	v_mfma_f32_16x16x32_bf16 v[138:141], v[102:105], v[162:165], v[138:141]
	v_mfma_f32_16x16x32_bf16 v[126:129], v[82:85], v[170:173], v[126:129]
	v_mfma_f32_16x16x32_bf16 v[122:125], v[102:105], v[170:173], v[122:125]
	v_mfma_f32_16x16x32_bf16 v[110:113], v[82:85], v[178:181], v[110:113]
	v_mfma_f32_16x16x32_bf16 v[94:97], v[102:105], v[178:181], v[94:97]
	v_mfma_f32_16x16x32_bf16 v[78:81], v[82:85], v[186:189], v[78:81]
	v_mfma_f32_16x16x32_bf16 v[74:77], v[102:105], v[186:189], v[74:77]
	v_mfma_f32_16x16x32_bf16 v[142:145], v[98:101], v[166:169], v[142:145]
	v_mfma_f32_16x16x32_bf16 v[138:141], v[106:109], v[166:169], v[138:141]
	v_mfma_f32_16x16x32_bf16 v[126:129], v[98:101], v[174:177], v[126:129]
	v_mfma_f32_16x16x32_bf16 v[122:125], v[106:109], v[174:177], v[122:125]
	v_mfma_f32_16x16x32_bf16 v[110:113], v[98:101], v[182:185], v[110:113]
	v_mfma_f32_16x16x32_bf16 v[94:97], v[106:109], v[182:185], v[94:97]
	v_mfma_f32_16x16x32_bf16 v[78:81], v[98:101], v[190:193], v[78:81]
	v_mfma_f32_16x16x32_bf16 v[74:77], v[106:109], v[190:193], v[74:77]
	v_mfma_f32_16x16x32_bf16 v[134:137], v[146:149], v[162:165], v[134:137]
	v_mfma_f32_16x16x32_bf16 v[130:133], v[154:157], v[162:165], v[130:133]
	v_mfma_f32_16x16x32_bf16 v[118:121], v[146:149], v[170:173], v[118:121]
	v_mfma_f32_16x16x32_bf16 v[114:117], v[154:157], v[170:173], v[114:117]
	v_mfma_f32_16x16x32_bf16 v[90:93], v[146:149], v[178:181], v[90:93]
	v_mfma_f32_16x16x32_bf16 v[86:89], v[154:157], v[178:181], v[86:89]
	v_mfma_f32_16x16x32_bf16 v[70:73], v[146:149], v[186:189], v[70:73]
	v_mfma_f32_16x16x32_bf16 v[66:69], v[154:157], v[186:189], v[66:69]
	v_mfma_f32_16x16x32_bf16 v[134:137], v[150:153], v[166:169], v[134:137]
	v_mfma_f32_16x16x32_bf16 v[130:133], v[158:161], v[166:169], v[130:133]
	v_mfma_f32_16x16x32_bf16 v[118:121], v[150:153], v[174:177], v[118:121]
	v_mfma_f32_16x16x32_bf16 v[114:117], v[158:161], v[174:177], v[114:117]
	v_mfma_f32_16x16x32_bf16 v[90:93], v[150:153], v[182:185], v[90:93]
	v_mfma_f32_16x16x32_bf16 v[86:89], v[158:161], v[182:185], v[86:89]
	v_mfma_f32_16x16x32_bf16 v[70:73], v[150:153], v[190:193], v[70:73]
	v_mfma_f32_16x16x32_bf16 v[66:69], v[158:161], v[190:193], v[66:69]
	s_setprio 0
	s_barrier
	s_add_i32 m0, s22, 0x17f80
	ds_read_b128 v[162:165], v249 offset:49152
	ds_read_b128 v[166:169], v249 offset:50176
	ds_read_b128 v[170:173], v249 offset:51200
	global_load_lds_dwordx4 v0, s[80:81] offset:128
	s_add_i32 m0, s22, 0x19f80
	ds_read_b128 v[174:177], v249 offset:52224
	global_load_lds_dwordx4 v218, s[80:81] offset:128
	s_add_i32 m0, s22, 0x1bf80
	ds_read_b128 v[178:181], v249 offset:53248
	global_load_lds_dwordx4 v0, s[100:101] offset:128
	s_add_i32 m0, s22, 0x1df80
	ds_read_b128 v[182:185], v249 offset:54272
	global_load_lds_dwordx4 v218, s[100:101] offset:128
	s_sub_i32 m0, s39, 0x80
	ds_read_b128 v[186:189], v249 offset:55296
	global_load_lds_dwordx4 v0, s[20:21] offset:128
	s_sub_i32 m0, s65, 0x80
	ds_read_b128 v[190:193], v249 offset:56320
	global_load_lds_dwordx4 v218, s[20:21] offset:128
	s_waitcnt vmcnt(8) lgkmcnt(0)
	s_barrier
	s_setprio 1
	v_mfma_f32_16x16x32_bf16 v[62:65], v[82:85], v[162:165], v[62:65]
	v_mfma_f32_16x16x32_bf16 v[58:61], v[102:105], v[162:165], v[58:61]
	v_mfma_f32_16x16x32_bf16 v[46:49], v[82:85], v[170:173], v[46:49]
	v_mfma_f32_16x16x32_bf16 v[42:45], v[102:105], v[170:173], v[42:45]
	s_add_u32 s10, s10, 0x100
	v_mfma_f32_16x16x32_bf16 v[30:33], v[82:85], v[178:181], v[30:33]
	s_addc_u32 s11, s11, 0
	v_mfma_f32_16x16x32_bf16 v[26:29], v[102:105], v[178:181], v[26:29]
	s_add_u32 s62, s62, 0x100
	v_mfma_f32_16x16x32_bf16 v[14:17], v[82:85], v[186:189], v[14:17]
	s_addc_u32 s63, s63, 0
	v_mfma_f32_16x16x32_bf16 v[10:13], v[102:105], v[186:189], v[10:13]
	s_mov_b32 s20, s78
	v_mfma_f32_16x16x32_bf16 v[62:65], v[98:101], v[166:169], v[62:65]
	v_mfma_f32_16x16x32_bf16 v[58:61], v[106:109], v[166:169], v[58:61]
	v_mfma_f32_16x16x32_bf16 v[46:49], v[98:101], v[174:177], v[46:49]
	v_mfma_f32_16x16x32_bf16 v[42:45], v[106:109], v[174:177], v[42:45]
	v_mfma_f32_16x16x32_bf16 v[30:33], v[98:101], v[182:185], v[30:33]
	v_mfma_f32_16x16x32_bf16 v[26:29], v[106:109], v[182:185], v[26:29]
	v_mfma_f32_16x16x32_bf16 v[14:17], v[98:101], v[190:193], v[14:17]
	v_mfma_f32_16x16x32_bf16 v[10:13], v[106:109], v[190:193], v[10:13]
	v_mfma_f32_16x16x32_bf16 v[54:57], v[146:149], v[162:165], v[54:57]
	v_mfma_f32_16x16x32_bf16 v[50:53], v[154:157], v[162:165], v[50:53]
	v_mfma_f32_16x16x32_bf16 v[38:41], v[146:149], v[170:173], v[38:41]
	v_mfma_f32_16x16x32_bf16 v[34:37], v[154:157], v[170:173], v[34:37]
	v_mfma_f32_16x16x32_bf16 v[22:25], v[146:149], v[178:181], v[22:25]
	v_mfma_f32_16x16x32_bf16 v[18:21], v[154:157], v[178:181], v[18:21]
	v_mfma_f32_16x16x32_bf16 v[6:9], v[146:149], v[186:189], v[6:9]
	v_mfma_f32_16x16x32_bf16 v[2:5], v[154:157], v[186:189], v[2:5]
	v_mfma_f32_16x16x32_bf16 v[54:57], v[150:153], v[166:169], v[54:57]
	v_mfma_f32_16x16x32_bf16 v[50:53], v[158:161], v[166:169], v[50:53]
	v_mfma_f32_16x16x32_bf16 v[38:41], v[150:153], v[174:177], v[38:41]
	v_mfma_f32_16x16x32_bf16 v[34:37], v[158:161], v[174:177], v[34:37]
	v_mfma_f32_16x16x32_bf16 v[22:25], v[150:153], v[182:185], v[22:25]
	v_mfma_f32_16x16x32_bf16 v[18:21], v[158:161], v[182:185], v[18:21]
	v_mfma_f32_16x16x32_bf16 v[6:9], v[150:153], v[190:193], v[6:9]
	v_mfma_f32_16x16x32_bf16 v[2:5], v[158:161], v[190:193], v[2:5]
	s_setprio 0
	s_barrier
	s_cmp_ge_i32 s78, s67
	s_cbranch_scc0 .LBB0_570

; #define PG8_STAGE(bufoff, gbase, voff) do { _Pragma("unroll") for (int _i = 0; _i < 2; ++_i) \
;         __builtin_amdgcn_global_load_lds((const unsigned*)((const char*)(gbase) + (voff)[_i]), (PG8_LAS unsigned*)(lds + (bufoff) + ldsw + _i * 8192), 16, 0, 0); } while (0)
; #define PG8_LDA(dst, b, h) do { _Pragma("unroll") for (int m = 0; m < 4; ++m) _Pragma("unroll") for (int k = 0; k < 2; ++k) dst[m][k] = *(const PG8_LAS bf16x8*)(lds + PG8_SA(b, h) + aoff + m * 2048 + k * 1024); } while (0)
; #define PG8_LDB(dst, b, h) do { _Pragma("unroll") for (int n = 0; n < 2; ++n) _Pragma("unroll") for (int k = 0; k < 2; ++k) dst[n][k] = *(const PG8_LAS bf16x8*)(lds + PG8_SB(b, h) + boff + n * 2048 + k * 1024); } while (0)
; #define PG8_MMA(ai, bj, At, Bt) do { __builtin_amdgcn_s_setprio(1); _Pragma("unroll") for (int m = 0; m < 4; ++m) _Pragma("unroll") for (int n = 0; n < 2; ++n) _Pragma("unroll") for (int k = 0; k < 2; ++k) \
;         acc[ai][bj][m][n] = __builtin_amdgcn_mfma_f32_16x16x32_bf16(Bt[n][k], At[m][k], acc[ai][bj][m][n], 0, 0, 0); __builtin_amdgcn_s_setprio(0); } while (0)
; #define PG8_WAIT_V(n) asm volatile("s_waitcnt vmcnt(" #n ")" ::: "memory")
; #define PG8_BAR __builtin_amdgcn_s_barrier()
; template <class Epi, class Sched, bool ALIGN_EPI = false, bool SP2 = false>
; __device__ __forceinline__ void gemm_phase(PG8_LAS unsigned char* lds, const Gemm g, const Sched& S, const Epi& E) {
;     ...
;         for (int t = 0; t < nt; t += 2) {
;             const bool last = (t == nt - 2);
;             const char* a1 = cA + (size_t)(t + 1) * kstep;
;             const char* a2 = last ? nA : cA + (size_t)(t + 2) * kstep; const char* b2 = last ? nB : cB + (size_t)(t + 2) * kstep;
;             const char* a3 = a2 + kstep; const char* b3 = b2 + kstep;
;             if (last && has_next) S.a_ready(nxt);
;             if constexpr (SP2) {
;             PG8_LDB(B0, 0, 0); PG8_LDB(B1, 0, 1); PG8_SCHED; PG8_LDA(At, 0, 0); PG8_STAGE(PG8_SA(1, 1), a1 + hstep, voffA);
;             PG8_WAIT_V(8); PG8_WAIT_L(0); PG8_BAR; PG8_MMA(0, 0, At, B0); PG8_MMA(0, 1, At, B1); PG8_BAR; PG8_SCHED;
;             PG8_LDA(At, 0, 1); PG8_STAGE(PG8_SB(0, 0), b2, voffB); PG8_STAGE(PG8_SB(0, 1), b2 + hstep, voffB); PG8_STAGE(PG8_SA(0, 0), a2, voffA);
;             PG8_WAIT_V(8); PG8_WAIT_L(0); PG8_BAR; PG8_MMA(1, 0, At, B0); PG8_MMA(1, 1, At, B1); PG8_BAR; PG8_SCHED;
.Lz_enter_639:
	s_add_u32 s8, s52, 0x80
	s_addc_u32 s9, s53, 0
	s_add_u32 s52, s20, 0x100
	s_addc_u32 s53, s21, 0
	s_mov_b32 s20, 0
	ds_read_b128 v[130:133], v181
	ds_read_b128 v[134:137], v181 offset:1024
	ds_read_b128 v[138:141], v181 offset:2048
	ds_read_b128 v[142:145], v181 offset:3072
	ds_read_b128 v[146:149], v181 offset:16384
	ds_read_b128 v[150:153], v181 offset:17408
	ds_read_b128 v[166:169], v181 offset:18432
	ds_read_b128 v[170:173], v181 offset:19456
	s_add_i32 m0, s55, 0xc000
	ds_read_b128 v[174:177], v183
	ds_read_b128 v[184:187], v183 offset:1024
	ds_read_b128 v[188:191], v183 offset:2048
	ds_read_b128 v[192:195], v183 offset:3072
	ds_read_b128 v[196:199], v183 offset:4096
	ds_read_b128 v[200:203], v183 offset:5120
	ds_read_b128 v[204:207], v183 offset:6144
	global_load_lds_dwordx4 v162, s[8:9]
	s_add_i32 m0, s55, 0xe000
	ds_read_b128 v[208:211], v183 offset:7168
	global_load_lds_dwordx4 v164, s[8:9]
	s_waitcnt vmcnt(8) lgkmcnt(0)
	s_barrier
	s_setprio 1
	v_mfma_f32_16x16x32_bf16 v[122:125], v[130:133], v[174:177], 0
	v_mfma_f32_16x16x32_bf16 v[118:121], v[138:141], v[174:177], 0
	v_mfma_f32_16x16x32_bf16 v[106:109], v[130:133], v[188:191], 0
	v_mfma_f32_16x16x32_bf16 v[102:105], v[138:141], v[188:191], 0
	s_add_i32 s68, s20, 2
	v_mfma_f32_16x16x32_bf16 v[90:93], v[130:133], v[196:199], 0
	s_add_u32 s69, s8, 0x80
	v_mfma_f32_16x16x32_bf16 v[86:89], v[138:141], v[196:199], 0
	s_addc_u32 s21, s9, 0
	v_mfma_f32_16x16x32_bf16 v[74:77], v[130:133], v[204:207], 0
	s_cmp_eq_u32 s63, s20
	v_mfma_f32_16x16x32_bf16 v[70:73], v[138:141], v[204:207], 0
	s_cselect_b32 s21, s49, s21
	v_mfma_f32_16x16x32_bf16 v[122:125], v[134:137], v[184:187], v[122:125]
	s_cselect_b32 s20, s48, s69
	v_mfma_f32_16x16x32_bf16 v[118:121], v[142:145], v[184:187], v[118:121]
	s_cselect_b32 s71, s51, s53
	v_mfma_f32_16x16x32_bf16 v[106:109], v[134:137], v[192:195], v[106:109]
	s_cselect_b32 s70, s50, s52
	v_mfma_f32_16x16x32_bf16 v[102:105], v[142:145], v[192:195], v[102:105]
	v_mfma_f32_16x16x32_bf16 v[90:93], v[134:137], v[200:203], v[90:93]
	v_mfma_f32_16x16x32_bf16 v[86:89], v[142:145], v[200:203], v[86:89]
	v_mfma_f32_16x16x32_bf16 v[74:77], v[134:137], v[208:211], v[74:77]
	v_mfma_f32_16x16x32_bf16 v[70:73], v[142:145], v[208:211], v[70:73]
	v_mfma_f32_16x16x32_bf16 v[126:129], v[146:149], v[174:177], 0
	v_mfma_f32_16x16x32_bf16 v[114:117], v[166:169], v[174:177], 0
	v_mfma_f32_16x16x32_bf16 v[110:113], v[146:149], v[188:191], 0
	v_mfma_f32_16x16x32_bf16 v[98:101], v[166:169], v[188:191], 0
	v_mfma_f32_16x16x32_bf16 v[94:97], v[146:149], v[196:199], 0
	v_mfma_f32_16x16x32_bf16 v[82:85], v[166:169], v[196:199], 0
	v_mfma_f32_16x16x32_bf16 v[78:81], v[146:149], v[204:207], 0
	v_mfma_f32_16x16x32_bf16 v[66:69], v[166:169], v[204:207], 0
	v_mfma_f32_16x16x32_bf16 v[126:129], v[150:153], v[184:187], v[126:129]
	v_mfma_f32_16x16x32_bf16 v[114:117], v[170:173], v[184:187], v[114:117]
	v_mfma_f32_16x16x32_bf16 v[110:113], v[150:153], v[192:195], v[110:113]
	v_mfma_f32_16x16x32_bf16 v[98:101], v[170:173], v[192:195], v[98:101]
	v_mfma_f32_16x16x32_bf16 v[94:97], v[150:153], v[200:203], v[94:97]
	v_mfma_f32_16x16x32_bf16 v[82:85], v[170:173], v[200:203], v[82:85]
	v_mfma_f32_16x16x32_bf16 v[78:81], v[150:153], v[208:211], v[78:81]
	v_mfma_f32_16x16x32_bf16 v[66:69], v[170:173], v[208:211], v[66:69]
	s_setprio 0
	s_barrier
	s_add_i32 m0, s23, 0x10000
	s_add_u32 s100, s70, s10
	s_addc_u32 s101, s71, s11
	ds_read_b128 v[174:177], v183 offset:16384
	ds_read_b128 v[184:187], v183 offset:17408
	ds_read_b128 v[188:191], v183 offset:18432
	global_load_lds_dwordx4 v0, s[70:71]
	s_add_i32 m0, s23, 0x12000
	ds_read_b128 v[192:195], v183 offset:19456
	global_load_lds_dwordx4 v154, s[70:71]
	s_add_i32 m0, s23, 0x14000
	ds_read_b128 v[196:199], v183 offset:20480
	global_load_lds_dwordx4 v0, s[100:101]
	s_add_i32 m0, s23, 0x16000
	ds_read_b128 v[200:203], v183 offset:21504
	global_load_lds_dwordx4 v154, s[100:101]
	s_mov_b32 m0, s55
	ds_read_b128 v[204:207], v183 offset:22528
	global_load_lds_dwordx4 v158, s[20:21]
	s_mov_b32 m0, s56
	ds_read_b128 v[208:211], v183 offset:23552
	global_load_lds_dwordx4 v156, s[20:21]
	s_waitcnt vmcnt(8) lgkmcnt(0)
	s_barrier
	s_setprio 1
	v_mfma_f32_16x16x32_bf16 v[58:61], v[130:133], v[174:177], 0
	v_mfma_f32_16x16x32_bf16 v[54:57], v[138:141], v[174:177], 0
	v_mfma_f32_16x16x32_bf16 v[42:45], v[130:133], v[188:191], 0
	v_mfma_f32_16x16x32_bf16 v[38:41], v[138:141], v[188:191], 0
	v_mfma_f32_16x16x32_bf16 v[26:29], v[130:133], v[196:199], 0
	v_mfma_f32_16x16x32_bf16 v[22:25], v[138:141], v[196:199], 0
	v_mfma_f32_16x16x32_bf16 v[10:13], v[130:133], v[204:207], 0
	v_mfma_f32_16x16x32_bf16 v[6:9], v[138:141], v[204:207], 0
	v_mfma_f32_16x16x32_bf16 v[58:61], v[134:137], v[184:187], v[58:61]
	v_mfma_f32_16x16x32_bf16 v[54:57], v[142:145], v[184:187], v[54:57]
	v_mfma_f32_16x16x32_bf16 v[42:45], v[134:137], v[192:195], v[42:45]
	v_mfma_f32_16x16x32_bf16 v[38:41], v[142:145], v[192:195], v[38:41]
	v_mfma_f32_16x16x32_bf16 v[26:29], v[134:137], v[200:203], v[26:29]
	v_mfma_f32_16x16x32_bf16 v[22:25], v[142:145], v[200:203], v[22:25]
	v_mfma_f32_16x16x32_bf16 v[10:13], v[134:137], v[208:211], v[10:13]
	v_mfma_f32_16x16x32_bf16 v[6:9], v[142:145], v[208:211], v[6:9]
	v_mfma_f32_16x16x32_bf16 v[62:65], v[146:149], v[174:177], 0
	v_mfma_f32_16x16x32_bf16 v[50:53], v[166:169], v[174:177], 0
	v_mfma_f32_16x16x32_bf16 v[46:49], v[146:149], v[188:191], 0
	v_mfma_f32_16x16x32_bf16 v[34:37], v[166:169], v[188:191], 0
	v_mfma_f32_16x16x32_bf16 v[30:33], v[146:149], v[196:199], 0
	v_mfma_f32_16x16x32_bf16 v[18:21], v[166:169], v[196:199], 0
	v_mfma_f32_16x16x32_bf16 v[14:17], v[146:149], v[204:207], 0
	v_mfma_f32_16x16x32_bf16 v[2:5], v[166:169], v[204:207], 0
	v_mfma_f32_16x16x32_bf16 v[62:65], v[150:153], v[184:187], v[62:65]
	v_mfma_f32_16x16x32_bf16 v[50:53], v[170:173], v[184:187], v[50:53]
	v_mfma_f32_16x16x32_bf16 v[46:49], v[150:153], v[192:195], v[46:49]
	v_mfma_f32_16x16x32_bf16 v[34:37], v[170:173], v[192:195], v[34:37]
	v_mfma_f32_16x16x32_bf16 v[30:33], v[150:153], v[200:203], v[30:33]
	v_mfma_f32_16x16x32_bf16 v[18:21], v[170:173], v[200:203], v[18:21]
	v_mfma_f32_16x16x32_bf16 v[14:17], v[150:153], v[208:211], v[14:17]
	v_mfma_f32_16x16x32_bf16 v[2:5], v[170:173], v[208:211], v[2:5]
	s_setprio 0
	s_barrier
; #define PG8_STAGE(bufoff, gbase, voff) do { _Pragma("unroll") for (int _i = 0; _i < 2; ++_i) \
;         __builtin_amdgcn_global_load_lds((const unsigned*)((const char*)(gbase) + (voff)[_i]), (PG8_LAS unsigned*)(lds + (bufoff) + ldsw + _i * 8192), 16, 0, 0); } while (0)
; #define PG8_LDA(dst, b, h) do { _Pragma("unroll") for (int m = 0; m < 4; ++m) _Pragma("unroll") for (int k = 0; k < 2; ++k) dst[m][k] = *(const PG8_LAS bf16x8*)(lds + PG8_SA(b, h) + aoff + m * 2048 + k * 1024); } while (0)
; #define PG8_LDB(dst, b, h) do { _Pragma("unroll") for (int n = 0; n < 2; ++n) _Pragma("unroll") for (int k = 0; k < 2; ++k) dst[n][k] = *(const PG8_LAS bf16x8*)(lds + PG8_SB(b, h) + boff + n * 2048 + k * 1024); } while (0)
; #define PG8_MMA(ai, bj, At, Bt) do { __builtin_amdgcn_s_setprio(1); _Pragma("unroll") for (int m = 0; m < 4; ++m) _Pragma("unroll") for (int n = 0; n < 2; ++n) _Pragma("unroll") for (int k = 0; k < 2; ++k) \
;         acc[ai][bj][m][n] = __builtin_amdgcn_mfma_f32_16x16x32_bf16(Bt[n][k], At[m][k], acc[ai][bj][m][n], 0, 0, 0); __builtin_amdgcn_s_setprio(0); } while (0)
; #define PG8_WAIT_V(n) asm volatile("s_waitcnt vmcnt(" #n ")" ::: "memory")
; #define PG8_WAIT_L(n) asm volatile("s_waitcnt lgkmcnt(" #n ")" ::: "memory")
; #define PG8_BAR __builtin_amdgcn_s_barrier()
; #define PG8_SCHED __builtin_amdgcn_sched_barrier(0)
; template <class Epi, class Sched, bool ALIGN_EPI = false, bool SP2 = false>
; __device__ __forceinline__ void gemm_phase(PG8_LAS unsigned char* lds, const Gemm g, const Sched& S, const Epi& E) {
;     ...
;             PG8_LDB(B0, 1, 0); PG8_LDB(B1, 1, 1); PG8_SCHED; PG8_LDA(At, 1, 0); PG8_STAGE(PG8_SA(0, 1), a2 + hstep, voffA);
;             PG8_WAIT_V(8); PG8_WAIT_L(0); PG8_BAR; PG8_MMA(0, 0, At, B0); PG8_MMA(0, 1, At, B1); PG8_BAR; PG8_SCHED;
;             PG8_LDA(At, 1, 1); PG8_STAGE(PG8_SB(1, 0), b3, voffB); PG8_STAGE(PG8_SB(1, 1), b3 + hstep, voffB); PG8_STAGE(PG8_SA(1, 0), a3, voffA);
;             PG8_WAIT_V(8); PG8_WAIT_L(0); PG8_BAR; PG8_MMA(1, 0, At, B0); PG8_MMA(1, 1, At, B1); PG8_BAR; PG8_SCHED;
	ds_read_b128 v[130:133], v181 offset:32768
	ds_read_b128 v[134:137], v181 offset:33792
	ds_read_b128 v[138:141], v181 offset:34816
	ds_read_b128 v[142:145], v181 offset:35840
	ds_read_b128 v[146:149], v181 offset:49152
	ds_read_b128 v[150:153], v181 offset:50176
	ds_read_b128 v[166:169], v181 offset:51200
	ds_read_b128 v[170:173], v181 offset:52224
	s_mov_b32 m0, s57
	ds_read_b128 v[174:177], v183 offset:32768
	ds_read_b128 v[184:187], v183 offset:33792
	ds_read_b128 v[188:191], v183 offset:34816
	ds_read_b128 v[192:195], v183 offset:35840
	ds_read_b128 v[196:199], v183 offset:36864
	ds_read_b128 v[200:203], v183 offset:37888
	ds_read_b128 v[204:207], v183 offset:38912
	global_load_lds_dwordx4 v162, s[20:21]
	s_mov_b32 m0, s58
	ds_read_b128 v[208:211], v183 offset:39936
	global_load_lds_dwordx4 v164, s[20:21]
	s_waitcnt vmcnt(8) lgkmcnt(0)
	s_barrier
	s_setprio 1
	v_mfma_f32_16x16x32_bf16 v[122:125], v[130:133], v[174:177], v[122:125]
	v_mfma_f32_16x16x32_bf16 v[118:121], v[138:141], v[174:177], v[118:121]
	v_mfma_f32_16x16x32_bf16 v[106:109], v[130:133], v[188:191], v[106:109]
	v_mfma_f32_16x16x32_bf16 v[102:105], v[138:141], v[188:191], v[102:105]
	v_mfma_f32_16x16x32_bf16 v[90:93], v[130:133], v[196:199], v[90:93]
	v_mfma_f32_16x16x32_bf16 v[86:89], v[138:141], v[196:199], v[86:89]
	v_mfma_f32_16x16x32_bf16 v[74:77], v[130:133], v[204:207], v[74:77]
	v_mfma_f32_16x16x32_bf16 v[70:73], v[138:141], v[204:207], v[70:73]
	v_mfma_f32_16x16x32_bf16 v[122:125], v[134:137], v[184:187], v[122:125]
	v_mfma_f32_16x16x32_bf16 v[118:121], v[142:145], v[184:187], v[118:121]
	v_mfma_f32_16x16x32_bf16 v[106:109], v[134:137], v[192:195], v[106:109]
	v_mfma_f32_16x16x32_bf16 v[102:105], v[142:145], v[192:195], v[102:105]
	v_mfma_f32_16x16x32_bf16 v[90:93], v[134:137], v[200:203], v[90:93]
	v_mfma_f32_16x16x32_bf16 v[86:89], v[142:145], v[200:203], v[86:89]
	v_mfma_f32_16x16x32_bf16 v[74:77], v[134:137], v[208:211], v[74:77]
	v_mfma_f32_16x16x32_bf16 v[70:73], v[142:145], v[208:211], v[70:73]
	v_mfma_f32_16x16x32_bf16 v[126:129], v[146:149], v[174:177], v[126:129]
	v_mfma_f32_16x16x32_bf16 v[114:117], v[166:169], v[174:177], v[114:117]
	v_mfma_f32_16x16x32_bf16 v[110:113], v[146:149], v[188:191], v[110:113]
	v_mfma_f32_16x16x32_bf16 v[98:101], v[166:169], v[188:191], v[98:101]
	v_mfma_f32_16x16x32_bf16 v[94:97], v[146:149], v[196:199], v[94:97]
	v_mfma_f32_16x16x32_bf16 v[82:85], v[166:169], v[196:199], v[82:85]
	v_mfma_f32_16x16x32_bf16 v[78:81], v[146:149], v[204:207], v[78:81]
	v_mfma_f32_16x16x32_bf16 v[66:69], v[166:169], v[204:207], v[66:69]
	v_mfma_f32_16x16x32_bf16 v[126:129], v[150:153], v[184:187], v[126:129]
	v_mfma_f32_16x16x32_bf16 v[114:117], v[170:173], v[184:187], v[114:117]
	v_mfma_f32_16x16x32_bf16 v[110:113], v[150:153], v[192:195], v[110:113]
	v_mfma_f32_16x16x32_bf16 v[98:101], v[170:173], v[192:195], v[98:101]
	v_mfma_f32_16x16x32_bf16 v[94:97], v[150:153], v[200:203], v[94:97]
	v_mfma_f32_16x16x32_bf16 v[82:85], v[170:173], v[200:203], v[82:85]
	v_mfma_f32_16x16x32_bf16 v[78:81], v[150:153], v[208:211], v[78:81]
	v_mfma_f32_16x16x32_bf16 v[66:69], v[170:173], v[208:211], v[66:69]
	s_setprio 0
	s_barrier
	s_add_i32 m0, s23, 0x17f80
	ds_read_b128 v[174:177], v183 offset:49152
	ds_read_b128 v[184:187], v183 offset:50176
	ds_read_b128 v[188:191], v183 offset:51200
	global_load_lds_dwordx4 v0, s[70:71] offset:128
	s_add_i32 m0, s23, 0x19f80
	ds_read_b128 v[192:195], v183 offset:52224
	global_load_lds_dwordx4 v154, s[70:71] offset:128
	s_add_i32 m0, s23, 0x1bf80
	ds_read_b128 v[196:199], v183 offset:53248
	global_load_lds_dwordx4 v0, s[100:101] offset:128
	s_add_i32 m0, s23, 0x1df80
	ds_read_b128 v[200:203], v183 offset:54272
	global_load_lds_dwordx4 v154, s[100:101] offset:128
	s_sub_i32 m0, s59, 0x80
	ds_read_b128 v[204:207], v183 offset:55296
	global_load_lds_dwordx4 v158, s[20:21] offset:128
	s_sub_i32 m0, s60, 0x80
	ds_read_b128 v[208:211], v183 offset:56320
	global_load_lds_dwordx4 v156, s[20:21] offset:128
	s_waitcnt vmcnt(8) lgkmcnt(0)
	s_barrier
	s_setprio 1
	v_mfma_f32_16x16x32_bf16 v[58:61], v[130:133], v[174:177], v[58:61]
	v_mfma_f32_16x16x32_bf16 v[54:57], v[138:141], v[174:177], v[54:57]
	v_mfma_f32_16x16x32_bf16 v[42:45], v[130:133], v[188:191], v[42:45]
	v_mfma_f32_16x16x32_bf16 v[38:41], v[138:141], v[188:191], v[38:41]
	s_add_u32 s8, s8, 0x100
	v_mfma_f32_16x16x32_bf16 v[26:29], v[130:133], v[196:199], v[26:29]
	s_addc_u32 s9, s9, 0
	v_mfma_f32_16x16x32_bf16 v[22:25], v[138:141], v[196:199], v[22:25]
	s_add_u32 s52, s52, 0x100
	v_mfma_f32_16x16x32_bf16 v[10:13], v[130:133], v[204:207], v[10:13]
	s_addc_u32 s53, s53, 0
	v_mfma_f32_16x16x32_bf16 v[6:9], v[138:141], v[204:207], v[6:9]
	s_mov_b32 s20, s68
	v_mfma_f32_16x16x32_bf16 v[58:61], v[134:137], v[184:187], v[58:61]
	v_mfma_f32_16x16x32_bf16 v[54:57], v[142:145], v[184:187], v[54:57]
	v_mfma_f32_16x16x32_bf16 v[42:45], v[134:137], v[192:195], v[42:45]
	v_mfma_f32_16x16x32_bf16 v[38:41], v[142:145], v[192:195], v[38:41]
	v_mfma_f32_16x16x32_bf16 v[26:29], v[134:137], v[200:203], v[26:29]
	v_mfma_f32_16x16x32_bf16 v[22:25], v[142:145], v[200:203], v[22:25]
	v_mfma_f32_16x16x32_bf16 v[10:13], v[134:137], v[208:211], v[10:13]
	v_mfma_f32_16x16x32_bf16 v[6:9], v[142:145], v[208:211], v[6:9]
	v_mfma_f32_16x16x32_bf16 v[62:65], v[146:149], v[174:177], v[62:65]
	v_mfma_f32_16x16x32_bf16 v[50:53], v[166:169], v[174:177], v[50:53]
	v_mfma_f32_16x16x32_bf16 v[46:49], v[146:149], v[188:191], v[46:49]
	v_mfma_f32_16x16x32_bf16 v[34:37], v[166:169], v[188:191], v[34:37]
	v_mfma_f32_16x16x32_bf16 v[30:33], v[146:149], v[196:199], v[30:33]
	v_mfma_f32_16x16x32_bf16 v[18:21], v[166:169], v[196:199], v[18:21]
	v_mfma_f32_16x16x32_bf16 v[14:17], v[146:149], v[204:207], v[14:17]
	v_mfma_f32_16x16x32_bf16 v[2:5], v[166:169], v[204:207], v[2:5]
	v_mfma_f32_16x16x32_bf16 v[62:65], v[150:153], v[184:187], v[62:65]
	v_mfma_f32_16x16x32_bf16 v[50:53], v[170:173], v[184:187], v[50:53]
	v_mfma_f32_16x16x32_bf16 v[46:49], v[150:153], v[192:195], v[46:49]
	v_mfma_f32_16x16x32_bf16 v[34:37], v[170:173], v[192:195], v[34:37]
	v_mfma_f32_16x16x32_bf16 v[30:33], v[150:153], v[200:203], v[30:33]
	v_mfma_f32_16x16x32_bf16 v[18:21], v[170:173], v[200:203], v[18:21]
	v_mfma_f32_16x16x32_bf16 v[14:17], v[150:153], v[208:211], v[14:17]
	v_mfma_f32_16x16x32_bf16 v[2:5], v[170:173], v[208:211], v[2:5]
	s_setprio 0
	s_barrier
	s_cmp_ge_i32 s68, s62
	s_cbranch_scc1 .Lpz_exit_641
; #define PG8_STAGE(bufoff, gbase, voff) do { _Pragma("unroll") for (int _i = 0; _i < 2; ++_i) \
;         __builtin_amdgcn_global_load_lds((const unsigned*)((const char*)(gbase) + (voff)[_i]), (PG8_LAS unsigned*)(lds + (bufoff) + ldsw + _i * 8192), 16, 0, 0); } while (0)
; #define PG8_LDA(dst, b, h) do { _Pragma("unroll") for (int m = 0; m < 4; ++m) _Pragma("unroll") for (int k = 0; k < 2; ++k) dst[m][k] = *(const PG8_LAS bf16x8*)(lds + PG8_SA(b, h) + aoff + m * 2048 + k * 1024); } while (0)
; #define PG8_LDB(dst, b, h) do { _Pragma("unroll") for (int n = 0; n < 2; ++n) _Pragma("unroll") for (int k = 0; k < 2; ++k) dst[n][k] = *(const PG8_LAS bf16x8*)(lds + PG8_SB(b, h) + boff + n * 2048 + k * 1024); } while (0)
; #define PG8_MMA(ai, bj, At, Bt) do { __builtin_amdgcn_s_setprio(1); _Pragma("unroll") for (int m = 0; m < 4; ++m) _Pragma("unroll") for (int n = 0; n < 2; ++n) _Pragma("unroll") for (int k = 0; k < 2; ++k) \
;         acc[ai][bj][m][n] = __builtin_amdgcn_mfma_f32_16x16x32_bf16(Bt[n][k], At[m][k], acc[ai][bj][m][n], 0, 0, 0); __builtin_amdgcn_s_setprio(0); } while (0)
; #define PG8_WAIT_V(n) asm volatile("s_waitcnt vmcnt(" #n ")" ::: "memory")
; #define PG8_BAR __builtin_amdgcn_s_barrier()
; template <class Epi, class Sched, bool ALIGN_EPI = false, bool SP2 = false>
; __device__ __forceinline__ void gemm_phase(PG8_LAS unsigned char* lds, const Gemm g, const Sched& S, const Epi& E) {
;     ...
;         for (int t = 0; t < nt; t += 2) {
;             const bool last = (t == nt - 2);
;             const char* a1 = cA + (size_t)(t + 1) * kstep;
;             const char* a2 = last ? nA : cA + (size_t)(t + 2) * kstep; const char* b2 = last ? nB : cB + (size_t)(t + 2) * kstep;
;             const char* a3 = a2 + kstep; const char* b3 = b2 + kstep;
;             if (last && has_next) S.a_ready(nxt);
;             if constexpr (SP2) {
;             PG8_LDB(B0, 0, 0); PG8_LDB(B1, 0, 1); PG8_SCHED; PG8_LDA(At, 0, 0); PG8_STAGE(PG8_SA(1, 1), a1 + hstep, voffA);
;             PG8_WAIT_V(8); PG8_WAIT_L(0); PG8_BAR; PG8_MMA(0, 0, At, B0); PG8_MMA(0, 1, At, B1); PG8_BAR; PG8_SCHED;
;             PG8_LDA(At, 0, 1); PG8_STAGE(PG8_SB(0, 0), b2, voffB); PG8_STAGE(PG8_SB(0, 1), b2 + hstep, voffB); PG8_STAGE(PG8_SA(0, 0), a2, voffA);
;             PG8_WAIT_V(8); PG8_WAIT_L(0); PG8_BAR; PG8_MMA(1, 0, At, B0); PG8_MMA(1, 1, At, B1); PG8_BAR; PG8_SCHED;
.LBB0_641:
	ds_read_b128 v[130:133], v181
	ds_read_b128 v[134:137], v181 offset:1024
	ds_read_b128 v[138:141], v181 offset:2048
	ds_read_b128 v[142:145], v181 offset:3072
	ds_read_b128 v[146:149], v181 offset:16384
	ds_read_b128 v[150:153], v181 offset:17408
	ds_read_b128 v[166:169], v181 offset:18432
	ds_read_b128 v[170:173], v181 offset:19456
	s_add_i32 m0, s55, 0xc000
	ds_read_b128 v[174:177], v183
	ds_read_b128 v[184:187], v183 offset:1024
	ds_read_b128 v[188:191], v183 offset:2048
	ds_read_b128 v[192:195], v183 offset:3072
	ds_read_b128 v[196:199], v183 offset:4096
	ds_read_b128 v[200:203], v183 offset:5120
	ds_read_b128 v[204:207], v183 offset:6144
	global_load_lds_dwordx4 v162, s[8:9]
	s_add_i32 m0, s55, 0xe000
	ds_read_b128 v[208:211], v183 offset:7168
	global_load_lds_dwordx4 v164, s[8:9]
	s_waitcnt vmcnt(8) lgkmcnt(0)
	s_barrier
	s_setprio 1
	v_mfma_f32_16x16x32_bf16 v[122:125], v[130:133], v[174:177], v[122:125]
	v_mfma_f32_16x16x32_bf16 v[118:121], v[138:141], v[174:177], v[118:121]
	v_mfma_f32_16x16x32_bf16 v[106:109], v[130:133], v[188:191], v[106:109]
	v_mfma_f32_16x16x32_bf16 v[102:105], v[138:141], v[188:191], v[102:105]
	s_add_i32 s68, s20, 2
	v_mfma_f32_16x16x32_bf16 v[90:93], v[130:133], v[196:199], v[90:93]
	s_add_u32 s69, s8, 0x80
	v_mfma_f32_16x16x32_bf16 v[86:89], v[138:141], v[196:199], v[86:89]
	s_addc_u32 s21, s9, 0
	v_mfma_f32_16x16x32_bf16 v[74:77], v[130:133], v[204:207], v[74:77]
	s_cmp_eq_u32 s63, s20
	v_mfma_f32_16x16x32_bf16 v[70:73], v[138:141], v[204:207], v[70:73]
	s_cselect_b32 s21, s49, s21
	v_mfma_f32_16x16x32_bf16 v[122:125], v[134:137], v[184:187], v[122:125]
	s_cselect_b32 s20, s48, s69
	v_mfma_f32_16x16x32_bf16 v[118:121], v[142:145], v[184:187], v[118:121]
	s_cselect_b32 s71, s51, s53
	v_mfma_f32_16x16x32_bf16 v[106:109], v[134:137], v[192:195], v[106:109]
	s_cselect_b32 s70, s50, s52
	v_mfma_f32_16x16x32_bf16 v[102:105], v[142:145], v[192:195], v[102:105]
	v_mfma_f32_16x16x32_bf16 v[90:93], v[134:137], v[200:203], v[90:93]
	v_mfma_f32_16x16x32_bf16 v[86:89], v[142:145], v[200:203], v[86:89]
	v_mfma_f32_16x16x32_bf16 v[74:77], v[134:137], v[208:211], v[74:77]
	v_mfma_f32_16x16x32_bf16 v[70:73], v[142:145], v[208:211], v[70:73]
	v_mfma_f32_16x16x32_bf16 v[126:129], v[146:149], v[174:177], v[126:129]
	v_mfma_f32_16x16x32_bf16 v[114:117], v[166:169], v[174:177], v[114:117]
	v_mfma_f32_16x16x32_bf16 v[110:113], v[146:149], v[188:191], v[110:113]
	v_mfma_f32_16x16x32_bf16 v[98:101], v[166:169], v[188:191], v[98:101]
	v_mfma_f32_16x16x32_bf16 v[94:97], v[146:149], v[196:199], v[94:97]
	v_mfma_f32_16x16x32_bf16 v[82:85], v[166:169], v[196:199], v[82:85]
	v_mfma_f32_16x16x32_bf16 v[78:81], v[146:149], v[204:207], v[78:81]
	v_mfma_f32_16x16x32_bf16 v[66:69], v[166:169], v[204:207], v[66:69]
	v_mfma_f32_16x16x32_bf16 v[126:129], v[150:153], v[184:187], v[126:129]
	v_mfma_f32_16x16x32_bf16 v[114:117], v[170:173], v[184:187], v[114:117]
	v_mfma_f32_16x16x32_bf16 v[110:113], v[150:153], v[192:195], v[110:113]
	v_mfma_f32_16x16x32_bf16 v[98:101], v[170:173], v[192:195], v[98:101]
	v_mfma_f32_16x16x32_bf16 v[94:97], v[150:153], v[200:203], v[94:97]
	v_mfma_f32_16x16x32_bf16 v[82:85], v[170:173], v[200:203], v[82:85]
	v_mfma_f32_16x16x32_bf16 v[78:81], v[150:153], v[208:211], v[78:81]
	v_mfma_f32_16x16x32_bf16 v[66:69], v[170:173], v[208:211], v[66:69]
	s_setprio 0
	s_barrier
	s_add_i32 m0, s23, 0x10000
	s_add_u32 s100, s70, s10
	s_addc_u32 s101, s71, s11
	ds_read_b128 v[174:177], v183 offset:16384
	ds_read_b128 v[184:187], v183 offset:17408
	ds_read_b128 v[188:191], v183 offset:18432
	global_load_lds_dwordx4 v0, s[70:71]
	s_add_i32 m0, s23, 0x12000
	ds_read_b128 v[192:195], v183 offset:19456
	global_load_lds_dwordx4 v154, s[70:71]
	s_add_i32 m0, s23, 0x14000
	ds_read_b128 v[196:199], v183 offset:20480
	global_load_lds_dwordx4 v0, s[100:101]
	s_add_i32 m0, s23, 0x16000
	ds_read_b128 v[200:203], v183 offset:21504
	global_load_lds_dwordx4 v154, s[100:101]
	s_mov_b32 m0, s55
	ds_read_b128 v[204:207], v183 offset:22528
	global_load_lds_dwordx4 v158, s[20:21]
	s_mov_b32 m0, s56
	ds_read_b128 v[208:211], v183 offset:23552
	global_load_lds_dwordx4 v156, s[20:21]
	s_waitcnt vmcnt(8) lgkmcnt(0)
	s_barrier
	s_setprio 1
	v_mfma_f32_16x16x32_bf16 v[58:61], v[130:133], v[174:177], v[58:61]
	v_mfma_f32_16x16x32_bf16 v[54:57], v[138:141], v[174:177], v[54:57]
	v_mfma_f32_16x16x32_bf16 v[42:45], v[130:133], v[188:191], v[42:45]
	v_mfma_f32_16x16x32_bf16 v[38:41], v[138:141], v[188:191], v[38:41]
	v_mfma_f32_16x16x32_bf16 v[26:29], v[130:133], v[196:199], v[26:29]
	v_mfma_f32_16x16x32_bf16 v[22:25], v[138:141], v[196:199], v[22:25]
	v_mfma_f32_16x16x32_bf16 v[10:13], v[130:133], v[204:207], v[10:13]
	v_mfma_f32_16x16x32_bf16 v[6:9], v[138:141], v[204:207], v[6:9]
	v_mfma_f32_16x16x32_bf16 v[58:61], v[134:137], v[184:187], v[58:61]
	v_mfma_f32_16x16x32_bf16 v[54:57], v[142:145], v[184:187], v[54:57]
	v_mfma_f32_16x16x32_bf16 v[42:45], v[134:137], v[192:195], v[42:45]
	v_mfma_f32_16x16x32_bf16 v[38:41], v[142:145], v[192:195], v[38:41]
	v_mfma_f32_16x16x32_bf16 v[26:29], v[134:137], v[200:203], v[26:29]
	v_mfma_f32_16x16x32_bf16 v[22:25], v[142:145], v[200:203], v[22:25]
	v_mfma_f32_16x16x32_bf16 v[10:13], v[134:137], v[208:211], v[10:13]
	v_mfma_f32_16x16x32_bf16 v[6:9], v[142:145], v[208:211], v[6:9]
	v_mfma_f32_16x16x32_bf16 v[62:65], v[146:149], v[174:177], v[62:65]
	v_mfma_f32_16x16x32_bf16 v[50:53], v[166:169], v[174:177], v[50:53]
	v_mfma_f32_16x16x32_bf16 v[46:49], v[146:149], v[188:191], v[46:49]
	v_mfma_f32_16x16x32_bf16 v[34:37], v[166:169], v[188:191], v[34:37]
	v_mfma_f32_16x16x32_bf16 v[30:33], v[146:149], v[196:199], v[30:33]
	v_mfma_f32_16x16x32_bf16 v[18:21], v[166:169], v[196:199], v[18:21]
	v_mfma_f32_16x16x32_bf16 v[14:17], v[146:149], v[204:207], v[14:17]
	v_mfma_f32_16x16x32_bf16 v[2:5], v[166:169], v[204:207], v[2:5]
	v_mfma_f32_16x16x32_bf16 v[62:65], v[150:153], v[184:187], v[62:65]
	v_mfma_f32_16x16x32_bf16 v[50:53], v[170:173], v[184:187], v[50:53]
	v_mfma_f32_16x16x32_bf16 v[46:49], v[150:153], v[192:195], v[46:49]
	v_mfma_f32_16x16x32_bf16 v[34:37], v[170:173], v[192:195], v[34:37]
	v_mfma_f32_16x16x32_bf16 v[30:33], v[150:153], v[200:203], v[30:33]
	v_mfma_f32_16x16x32_bf16 v[18:21], v[170:173], v[200:203], v[18:21]
	v_mfma_f32_16x16x32_bf16 v[14:17], v[150:153], v[208:211], v[14:17]
	v_mfma_f32_16x16x32_bf16 v[2:5], v[170:173], v[208:211], v[2:5]
	s_setprio 0
	s_barrier
; #define PG8_STAGE(bufoff, gbase, voff) do { _Pragma("unroll") for (int _i = 0; _i < 2; ++_i) \
;         __builtin_amdgcn_global_load_lds((const unsigned*)((const char*)(gbase) + (voff)[_i]), (PG8_LAS unsigned*)(lds + (bufoff) + ldsw + _i * 8192), 16, 0, 0); } while (0)
; #define PG8_LDA(dst, b, h) do { _Pragma("unroll") for (int m = 0; m < 4; ++m) _Pragma("unroll") for (int k = 0; k < 2; ++k) dst[m][k] = *(const PG8_LAS bf16x8*)(lds + PG8_SA(b, h) + aoff + m * 2048 + k * 1024); } while (0)
; #define PG8_LDB(dst, b, h) do { _Pragma("unroll") for (int n = 0; n < 2; ++n) _Pragma("unroll") for (int k = 0; k < 2; ++k) dst[n][k] = *(const PG8_LAS bf16x8*)(lds + PG8_SB(b, h) + boff + n * 2048 + k * 1024); } while (0)
; #define PG8_MMA(ai, bj, At, Bt) do { __builtin_amdgcn_s_setprio(1); _Pragma("unroll") for (int m = 0; m < 4; ++m) _Pragma("unroll") for (int n = 0; n < 2; ++n) _Pragma("unroll") for (int k = 0; k < 2; ++k) \
;         acc[ai][bj][m][n] = __builtin_amdgcn_mfma_f32_16x16x32_bf16(Bt[n][k], At[m][k], acc[ai][bj][m][n], 0, 0, 0); __builtin_amdgcn_s_setprio(0); } while (0)
; #define PG8_WAIT_V(n) asm volatile("s_waitcnt vmcnt(" #n ")" ::: "memory")
; #define PG8_WAIT_L(n) asm volatile("s_waitcnt lgkmcnt(" #n ")" ::: "memory")
; #define PG8_BAR __builtin_amdgcn_s_barrier()
; #define PG8_SCHED __builtin_amdgcn_sched_barrier(0)
; template <class Epi, class Sched, bool ALIGN_EPI = false, bool SP2 = false>
; __device__ __forceinline__ void gemm_phase(PG8_LAS unsigned char* lds, const Gemm g, const Sched& S, const Epi& E) {
;     ...
;             PG8_LDB(B0, 1, 0); PG8_LDB(B1, 1, 1); PG8_SCHED; PG8_LDA(At, 1, 0); PG8_STAGE(PG8_SA(0, 1), a2 + hstep, voffA);
;             PG8_WAIT_V(8); PG8_WAIT_L(0); PG8_BAR; PG8_MMA(0, 0, At, B0); PG8_MMA(0, 1, At, B1); PG8_BAR; PG8_SCHED;
;             PG8_LDA(At, 1, 1); PG8_STAGE(PG8_SB(1, 0), b3, voffB); PG8_STAGE(PG8_SB(1, 1), b3 + hstep, voffB); PG8_STAGE(PG8_SA(1, 0), a3, voffA);
;             PG8_WAIT_V(8); PG8_WAIT_L(0); PG8_BAR; PG8_MMA(1, 0, At, B0); PG8_MMA(1, 1, At, B1); PG8_BAR; PG8_SCHED;
	ds_read_b128 v[130:133], v181 offset:32768
	ds_read_b128 v[134:137], v181 offset:33792
	ds_read_b128 v[138:141], v181 offset:34816
	ds_read_b128 v[142:145], v181 offset:35840
	ds_read_b128 v[146:149], v181 offset:49152
	ds_read_b128 v[150:153], v181 offset:50176
	ds_read_b128 v[166:169], v181 offset:51200
	ds_read_b128 v[170:173], v181 offset:52224
	s_mov_b32 m0, s57
	ds_read_b128 v[174:177], v183 offset:32768
	ds_read_b128 v[184:187], v183 offset:33792
	ds_read_b128 v[188:191], v183 offset:34816
	ds_read_b128 v[192:195], v183 offset:35840
	ds_read_b128 v[196:199], v183 offset:36864
	ds_read_b128 v[200:203], v183 offset:37888
	ds_read_b128 v[204:207], v183 offset:38912
	global_load_lds_dwordx4 v162, s[20:21]
	s_mov_b32 m0, s58
	ds_read_b128 v[208:211], v183 offset:39936
	global_load_lds_dwordx4 v164, s[20:21]
	s_waitcnt vmcnt(8) lgkmcnt(0)
	s_barrier
	s_setprio 1
	v_mfma_f32_16x16x32_bf16 v[122:125], v[130:133], v[174:177], v[122:125]
	v_mfma_f32_16x16x32_bf16 v[118:121], v[138:141], v[174:177], v[118:121]
	v_mfma_f32_16x16x32_bf16 v[106:109], v[130:133], v[188:191], v[106:109]
	v_mfma_f32_16x16x32_bf16 v[102:105], v[138:141], v[188:191], v[102:105]
	v_mfma_f32_16x16x32_bf16 v[90:93], v[130:133], v[196:199], v[90:93]
	v_mfma_f32_16x16x32_bf16 v[86:89], v[138:141], v[196:199], v[86:89]
	v_mfma_f32_16x16x32_bf16 v[74:77], v[130:133], v[204:207], v[74:77]
	v_mfma_f32_16x16x32_bf16 v[70:73], v[138:141], v[204:207], v[70:73]
	v_mfma_f32_16x16x32_bf16 v[122:125], v[134:137], v[184:187], v[122:125]
	v_mfma_f32_16x16x32_bf16 v[118:121], v[142:145], v[184:187], v[118:121]
	v_mfma_f32_16x16x32_bf16 v[106:109], v[134:137], v[192:195], v[106:109]
	v_mfma_f32_16x16x32_bf16 v[102:105], v[142:145], v[192:195], v[102:105]
	v_mfma_f32_16x16x32_bf16 v[90:93], v[134:137], v[200:203], v[90:93]
	v_mfma_f32_16x16x32_bf16 v[86:89], v[142:145], v[200:203], v[86:89]
	v_mfma_f32_16x16x32_bf16 v[74:77], v[134:137], v[208:211], v[74:77]
	v_mfma_f32_16x16x32_bf16 v[70:73], v[142:145], v[208:211], v[70:73]
	v_mfma_f32_16x16x32_bf16 v[126:129], v[146:149], v[174:177], v[126:129]
	v_mfma_f32_16x16x32_bf16 v[114:117], v[166:169], v[174:177], v[114:117]
	v_mfma_f32_16x16x32_bf16 v[110:113], v[146:149], v[188:191], v[110:113]
	v_mfma_f32_16x16x32_bf16 v[98:101], v[166:169], v[188:191], v[98:101]
	v_mfma_f32_16x16x32_bf16 v[94:97], v[146:149], v[196:199], v[94:97]
	v_mfma_f32_16x16x32_bf16 v[82:85], v[166:169], v[196:199], v[82:85]
	v_mfma_f32_16x16x32_bf16 v[78:81], v[146:149], v[204:207], v[78:81]
	v_mfma_f32_16x16x32_bf16 v[66:69], v[166:169], v[204:207], v[66:69]
	v_mfma_f32_16x16x32_bf16 v[126:129], v[150:153], v[184:187], v[126:129]
	v_mfma_f32_16x16x32_bf16 v[114:117], v[170:173], v[184:187], v[114:117]
	v_mfma_f32_16x16x32_bf16 v[110:113], v[150:153], v[192:195], v[110:113]
	v_mfma_f32_16x16x32_bf16 v[98:101], v[170:173], v[192:195], v[98:101]
	v_mfma_f32_16x16x32_bf16 v[94:97], v[150:153], v[200:203], v[94:97]
	v_mfma_f32_16x16x32_bf16 v[82:85], v[170:173], v[200:203], v[82:85]
	v_mfma_f32_16x16x32_bf16 v[78:81], v[150:153], v[208:211], v[78:81]
	v_mfma_f32_16x16x32_bf16 v[66:69], v[170:173], v[208:211], v[66:69]
	s_setprio 0
	s_barrier
	s_add_i32 m0, s23, 0x17f80
	ds_read_b128 v[174:177], v183 offset:49152
	ds_read_b128 v[184:187], v183 offset:50176
	ds_read_b128 v[188:191], v183 offset:51200
	global_load_lds_dwordx4 v0, s[70:71] offset:128
	s_add_i32 m0, s23, 0x19f80
	ds_read_b128 v[192:195], v183 offset:52224
	global_load_lds_dwordx4 v154, s[70:71] offset:128
	s_add_i32 m0, s23, 0x1bf80
	ds_read_b128 v[196:199], v183 offset:53248
	global_load_lds_dwordx4 v0, s[100:101] offset:128
	s_add_i32 m0, s23, 0x1df80
	ds_read_b128 v[200:203], v183 offset:54272
	global_load_lds_dwordx4 v154, s[100:101] offset:128
	s_sub_i32 m0, s59, 0x80
	ds_read_b128 v[204:207], v183 offset:55296
	global_load_lds_dwordx4 v158, s[20:21] offset:128
	s_sub_i32 m0, s60, 0x80
	ds_read_b128 v[208:211], v183 offset:56320
	global_load_lds_dwordx4 v156, s[20:21] offset:128
	s_waitcnt vmcnt(8) lgkmcnt(0)
	s_barrier
	s_setprio 1
	v_mfma_f32_16x16x32_bf16 v[58:61], v[130:133], v[174:177], v[58:61]
	v_mfma_f32_16x16x32_bf16 v[54:57], v[138:141], v[174:177], v[54:57]
	v_mfma_f32_16x16x32_bf16 v[42:45], v[130:133], v[188:191], v[42:45]
	v_mfma_f32_16x16x32_bf16 v[38:41], v[138:141], v[188:191], v[38:41]
	s_add_u32 s8, s8, 0x100
	v_mfma_f32_16x16x32_bf16 v[26:29], v[130:133], v[196:199], v[26:29]
	s_addc_u32 s9, s9, 0
	v_mfma_f32_16x16x32_bf16 v[22:25], v[138:141], v[196:199], v[22:25]
	s_add_u32 s52, s52, 0x100
	v_mfma_f32_16x16x32_bf16 v[10:13], v[130:133], v[204:207], v[10:13]
	s_addc_u32 s53, s53, 0
	v_mfma_f32_16x16x32_bf16 v[6:9], v[138:141], v[204:207], v[6:9]
	s_mov_b32 s20, s68
	v_mfma_f32_16x16x32_bf16 v[58:61], v[134:137], v[184:187], v[58:61]
	v_mfma_f32_16x16x32_bf16 v[54:57], v[142:145], v[184:187], v[54:57]
	v_mfma_f32_16x16x32_bf16 v[42:45], v[134:137], v[192:195], v[42:45]
	v_mfma_f32_16x16x32_bf16 v[38:41], v[142:145], v[192:195], v[38:41]
	v_mfma_f32_16x16x32_bf16 v[26:29], v[134:137], v[200:203], v[26:29]
	v_mfma_f32_16x16x32_bf16 v[22:25], v[142:145], v[200:203], v[22:25]
	v_mfma_f32_16x16x32_bf16 v[10:13], v[134:137], v[208:211], v[10:13]
	v_mfma_f32_16x16x32_bf16 v[6:9], v[142:145], v[208:211], v[6:9]
	v_mfma_f32_16x16x32_bf16 v[62:65], v[146:149], v[174:177], v[62:65]
	v_mfma_f32_16x16x32_bf16 v[50:53], v[166:169], v[174:177], v[50:53]
	v_mfma_f32_16x16x32_bf16 v[46:49], v[146:149], v[188:191], v[46:49]
	v_mfma_f32_16x16x32_bf16 v[34:37], v[166:169], v[188:191], v[34:37]
	v_mfma_f32_16x16x32_bf16 v[30:33], v[146:149], v[196:199], v[30:33]
	v_mfma_f32_16x16x32_bf16 v[18:21], v[166:169], v[196:199], v[18:21]
	v_mfma_f32_16x16x32_bf16 v[14:17], v[146:149], v[204:207], v[14:17]
	v_mfma_f32_16x16x32_bf16 v[2:5], v[166:169], v[204:207], v[2:5]
	v_mfma_f32_16x16x32_bf16 v[62:65], v[150:153], v[184:187], v[62:65]
	v_mfma_f32_16x16x32_bf16 v[50:53], v[170:173], v[184:187], v[50:53]
	v_mfma_f32_16x16x32_bf16 v[46:49], v[150:153], v[192:195], v[46:49]
	v_mfma_f32_16x16x32_bf16 v[34:37], v[170:173], v[192:195], v[34:37]
	v_mfma_f32_16x16x32_bf16 v[30:33], v[150:153], v[200:203], v[30:33]
	v_mfma_f32_16x16x32_bf16 v[18:21], v[170:173], v[200:203], v[18:21]
	v_mfma_f32_16x16x32_bf16 v[14:17], v[150:153], v[208:211], v[14:17]
	v_mfma_f32_16x16x32_bf16 v[2:5], v[170:173], v[208:211], v[2:5]
	s_setprio 0
	s_barrier
	s_cmp_ge_i32 s68, s62
	s_cbranch_scc0 .LBB0_641

; __global__ void __launch_bounds__(NTHR, 2) mega_fwd(Args a) {
	.amdhsa_kernel _Z8mega_fwd4Args
		.amdhsa_group_segment_fixed_size 0
		.amdhsa_private_segment_fixed_size 0
		.amdhsa_kernarg_size 544
		.amdhsa_user_sgpr_count 2
		.amdhsa_user_sgpr_dispatch_ptr 0
		.amdhsa_user_sgpr_queue_ptr 0
		.amdhsa_user_sgpr_kernarg_segment_ptr 1
		.amdhsa_user_sgpr_dispatch_id 0
		.amdhsa_user_sgpr_kernarg_preload_length 0
		.amdhsa_user_sgpr_kernarg_preload_offset 0
		.amdhsa_user_sgpr_private_segment_size 0
		.amdhsa_uses_dynamic_stack 0
		.amdhsa_enable_private_segment 0
		.amdhsa_system_sgpr_workgroup_id_x 1
		.amdhsa_system_sgpr_workgroup_id_y 0
		.amdhsa_system_sgpr_workgroup_id_z 0
		.amdhsa_system_sgpr_workgroup_info 0
		.amdhsa_system_vgpr_workitem_id 2
		.amdhsa_next_free_vgpr 256
		.amdhsa_next_free_sgpr 102
		.amdhsa_accum_offset 256
		.amdhsa_reserve_vcc 1
		.amdhsa_float_round_mode_32 0
		.amdhsa_float_round_mode_16_64 0
		.amdhsa_float_denorm_mode_32 3
		.amdhsa_float_denorm_mode_16_64 3
		.amdhsa_dx10_clamp 1
		.amdhsa_ieee_mode 1
		.amdhsa_fp16_overflow 0
		.amdhsa_tg_split 0
		.amdhsa_exception_fp_ieee_invalid_op 0
		.amdhsa_exception_fp_denorm_src 0
		.amdhsa_exception_fp_ieee_div_zero 0
		.amdhsa_exception_fp_ieee_overflow 0
		.amdhsa_exception_fp_ieee_underflow 0
		.amdhsa_exception_fp_ieee_inexact 0
		.amdhsa_exception_int_div_zero 0
	.end_amdhsa_kernel

; __global__ void __launch_bounds__(NTHR, 2) mega_fwd(Args a) {
amdhsa.kernels:
  - .agpr_count:     0
    .args:
      - .offset:         0
        .size:           288
        .value_kind:     by_value
      - .offset:         288
        .size:           4
        .value_kind:     hidden_block_count_x
      - .offset:         292
        .size:           4
        .value_kind:     hidden_block_count_y
      - .offset:         296
        .size:           4
        .value_kind:     hidden_block_count_z
      - .offset:         300
        .size:           2
        .value_kind:     hidden_group_size_x
      - .offset:         302
        .size:           2
        .value_kind:     hidden_group_size_y
      - .offset:         304
        .size:           2
        .value_kind:     hidden_group_size_z
      - .offset:         306
        .size:           2
        .value_kind:     hidden_remainder_x
      - .offset:         308
        .size:           2
        .value_kind:     hidden_remainder_y
      - .offset:         310
        .size:           2
        .value_kind:     hidden_remainder_z
      - .offset:         328
        .size:           8
        .value_kind:     hidden_global_offset_x
      - .offset:         336
        .size:           8
        .value_kind:     hidden_global_offset_y
      - .offset:         344
        .size:           8
        .value_kind:     hidden_global_offset_z
      - .offset:         352
        .size:           2
        .value_kind:     hidden_grid_dims
      - .offset:         376
        .size:           8
        .value_kind:     hidden_multigrid_sync_arg
      - .offset:         408
        .size:           4
        .value_kind:     hidden_dynamic_lds_size
    .group_segment_fixed_size: 0
    .kernarg_segment_align: 8
    .kernarg_segment_size: 544
    .language:       OpenCL C
    .language_version:
      - 2
      - 0
    .max_flat_workgroup_size: 512
    .name:           _Z8mega_fwd4Args
    .private_segment_fixed_size: 0
    .sgpr_count:     108
    .sgpr_spill_count: 235
    .symbol:         _Z8mega_fwd4Args.kd
    .uniform_work_group_size: 1
    .uses_dynamic_stack: false
    .vgpr_count:     256
    .vgpr_spill_count: 0
    .wavefront_size: 64
